# v53 plus deletion of the redundant post-barrier s_waitcnt lgkmcnt(0) in the GEMM compute phases (56 sites)
# baseline (speedup 1.0000x reference)
; #define PG8_STAGE(bufoff, gbase, voff) do { _Pragma("unroll") for (int _i = 0; _i < 2; ++_i) \
;         __builtin_amdgcn_global_load_lds((const unsigned*)((const char*)(gbase) + (voff)[_i]), (LAS unsigned*)(lds + (bufoff) + ldsw + _i * 8192), 16, 0, 0); } while (0)
; #define PG8_LDA(dst, b, h) do { _Pragma("unroll") for (int m = 0; m < 4; ++m) _Pragma("unroll") for (int k = 0; k < 2; ++k) dst[m][k] = *(const LAS bf16x8*)(lds + PG8_SA(b, h) + aoff + m * 2048 + k * 1024); } while (0)
; #define PG8_LDB(dst, b, h) do { _Pragma("unroll") for (int n = 0; n < 2; ++n) _Pragma("unroll") for (int k = 0; k < 2; ++k) dst[n][k] = *(const LAS bf16x8*)(lds + PG8_SB(b, h) + boff + n * 2048 + k * 1024); } while (0)
; #define PG8_MMA(ai, bj, At, Bt) do { __builtin_amdgcn_s_setprio(1); _Pragma("unroll") for (int m = 0; m < 4; ++m) _Pragma("unroll") for (int n = 0; n < 2; ++n) _Pragma("unroll") for (int k = 0; k < 2; ++k) \
;         acc[ai][bj][m][n] = __builtin_amdgcn_mfma_f32_16x16x32_bf16(Bt[n][k], At[m][k], acc[ai][bj][m][n], 0, 0, 0); __builtin_amdgcn_s_setprio(0); } while (0)
; #define PG8_WAIT_V(n) asm volatile("s_waitcnt vmcnt(" #n ")" ::: "memory")
; #define PG8_WAIT_L(n) asm volatile("s_waitcnt lgkmcnt(" #n ")" ::: "memory")
; #define PG8_BAR __builtin_amdgcn_s_barrier()
; #define PG8_SCHED __builtin_amdgcn_sched_barrier(0)
; template <class Epi>
; DI void gemm_phase(int wv, LAS unsigned char* lds, LAS unsigned char* scr, const Sched& S, const Epi& E) {
;     ...
;             PG8_LDB(B0, 0, 0); PG8_LDB(B1, 0, 1); PG8_SCHED; PG8_LDA(At, 0, 0); PG8_STAGE(PG8_SA(1, 1), a1 + hstepA, voffA);
;             PG8_WAIT_V(8); PG8_WAIT_L(0); PG8_BAR; PG8_MMA(0, 0, At, B0); PG8_MMA(0, 1, At, B1); PG8_BAR; PG8_SCHED;
;             PG8_LDA(At, 0, 1); PG8_STAGE(PG8_SB(0, 0), b2, voffB); PG8_STAGE(PG8_SB(0, 1), b2 + hstepB, voffB); PG8_STAGE(PG8_SA(0, 0), a2, voffA);
;             PG8_WAIT_V(8); PG8_WAIT_L(0); PG8_BAR; PG8_MMA(1, 0, At, B0); PG8_MMA(1, 1, At, B1); PG8_BAR; PG8_SCHED;
.LBB0_43:
	s_add_u32 s22, s20, 0xfffc0080
	s_addc_u32 s23, s21, -1
	s_add_i32 s56, 0, 0x10000
	s_cmp_eq_u32 s53, 12
	s_cselect_b32 s25, s7, s23
	s_cselect_b32 s24, s9, s22
	s_cselect_b32 s23, s13, s52
	s_cselect_b32 s22, s15, s49
	s_add_i32 s58, 0, 0x14000
	v_add_u32_e32 v156, s56, v142
	v_add_u32_e32 v172, s58, v142
	ds_read_b128 v[144:147], v156
	ds_read_b128 v[148:151], v156 offset:1024
	ds_read_b128 v[152:155], v156 offset:2048
	ds_read_b128 v[156:159], v156 offset:3072
	ds_read_b128 v[160:163], v172
	ds_read_b128 v[164:167], v172 offset:1024
	ds_read_b128 v[168:171], v172 offset:2048
	ds_read_b128 v[172:175], v172 offset:3072
	v_lshl_add_u64 v[210:211], s[20:21], 0, v[140:141]
	s_add_i32 m0, s38, 0xc000
	ds_read_b128 v[176:179], v143
	ds_read_b128 v[180:183], v143 offset:1024
	ds_read_b128 v[184:187], v143 offset:2048
	ds_read_b128 v[188:191], v143 offset:3072
	ds_read_b128 v[194:197], v143 offset:4096
	ds_read_b128 v[198:201], v143 offset:5120
	ds_read_b128 v[202:205], v143 offset:6144
	ds_read_b128 v[206:209], v143 offset:7168
	global_load_lds_dwordx4 v[210:211], off
	v_lshl_add_u64 v[210:211], s[20:21], 0, v[138:139]
	s_add_i32 m0, s38, 0xe000
	s_nop 0
	global_load_lds_dwordx4 v[210:211], off
	s_waitcnt vmcnt(8)
	s_waitcnt lgkmcnt(0)
	s_barrier
	v_mfma_f32_16x16x32_bf16 v[124:127], v[144:147], v[176:179], v[124:127]
	v_mfma_f32_16x16x32_bf16 v[120:123], v[152:155], v[176:179], v[120:123]
	v_mfma_f32_16x16x32_bf16 v[116:119], v[144:147], v[184:187], v[116:119]
	v_mfma_f32_16x16x32_bf16 v[112:115], v[152:155], v[184:187], v[112:115]
	v_mfma_f32_16x16x32_bf16 v[100:103], v[144:147], v[194:197], v[100:103]
	v_mfma_f32_16x16x32_bf16 v[96:99], v[152:155], v[194:197], v[96:99]
	v_mfma_f32_16x16x32_bf16 v[84:87], v[144:147], v[202:205], v[84:87]
	v_mfma_f32_16x16x32_bf16 v[80:83], v[152:155], v[202:205], v[80:83]
	v_mfma_f32_16x16x32_bf16 v[124:127], v[148:151], v[180:183], v[124:127]
	v_mfma_f32_16x16x32_bf16 v[120:123], v[156:159], v[180:183], v[120:123]
	v_mfma_f32_16x16x32_bf16 v[116:119], v[148:151], v[188:191], v[116:119]
	v_mfma_f32_16x16x32_bf16 v[112:115], v[156:159], v[188:191], v[112:115]
	v_mfma_f32_16x16x32_bf16 v[100:103], v[148:151], v[198:201], v[100:103]
	v_mfma_f32_16x16x32_bf16 v[96:99], v[156:159], v[198:201], v[96:99]
	v_mfma_f32_16x16x32_bf16 v[84:87], v[148:151], v[206:209], v[84:87]
	v_mfma_f32_16x16x32_bf16 v[80:83], v[156:159], v[206:209], v[80:83]
	v_mfma_f32_16x16x32_bf16 v[108:111], v[160:163], v[176:179], v[108:111]
	v_mfma_f32_16x16x32_bf16 v[104:107], v[168:171], v[176:179], v[104:107]
	v_mfma_f32_16x16x32_bf16 v[92:95], v[160:163], v[184:187], v[92:95]
	v_mfma_f32_16x16x32_bf16 v[88:91], v[168:171], v[184:187], v[88:91]
	v_mfma_f32_16x16x32_bf16 v[76:79], v[160:163], v[194:197], v[76:79]
	v_mfma_f32_16x16x32_bf16 v[72:75], v[168:171], v[194:197], v[72:75]
	v_mfma_f32_16x16x32_bf16 v[68:71], v[160:163], v[202:205], v[68:71]
	v_mfma_f32_16x16x32_bf16 v[64:67], v[168:171], v[202:205], v[64:67]
	v_mfma_f32_16x16x32_bf16 v[108:111], v[164:167], v[180:183], v[108:111]
	v_mfma_f32_16x16x32_bf16 v[104:107], v[172:175], v[180:183], v[104:107]
	v_mfma_f32_16x16x32_bf16 v[92:95], v[164:167], v[188:191], v[92:95]
	v_mfma_f32_16x16x32_bf16 v[88:91], v[172:175], v[188:191], v[88:91]
	v_mfma_f32_16x16x32_bf16 v[76:79], v[164:167], v[198:201], v[76:79]
	v_mfma_f32_16x16x32_bf16 v[72:75], v[172:175], v[198:201], v[72:75]
	v_mfma_f32_16x16x32_bf16 v[68:71], v[164:167], v[206:209], v[68:71]
	v_mfma_f32_16x16x32_bf16 v[64:67], v[172:175], v[206:209], v[64:67]
	s_barrier
	s_add_i32 s56, s56, s37
	v_lshl_add_u64 v[210:211], s[22:23], 0, v[130:131]
	s_mov_b32 m0, s56
	ds_read_b128 v[176:179], v143 offset:16384
	ds_read_b128 v[180:183], v143 offset:17408
	ds_read_b128 v[184:187], v143 offset:18432
	ds_read_b128 v[188:191], v143 offset:19456
	ds_read_b128 v[194:197], v143 offset:20480
	ds_read_b128 v[198:201], v143 offset:21504
	ds_read_b128 v[202:205], v143 offset:22528
	ds_read_b128 v[206:209], v143 offset:23552
	global_load_lds_dwordx4 v[210:211], off
	s_add_i32 m0, s56, 0x2000
	s_add_u32 s56, s22, 0x40000
	v_lshl_add_u64 v[212:213], s[22:23], 0, v[134:135]
	s_addc_u32 s57, s23, 0
	s_add_i32 s58, s58, s37
	global_load_lds_dwordx4 v[212:213], off
	v_lshl_add_u64 v[214:215], s[56:57], 0, v[130:131]
	s_mov_b32 m0, s58
	v_lshl_add_u64 v[216:217], s[24:25], 0, v[132:133]
	global_load_lds_dwordx4 v[214:215], off
	v_lshl_add_u64 v[214:215], s[56:57], 0, v[134:135]
	s_add_i32 m0, s58, 0x2000
	s_nop 0
	global_load_lds_dwordx4 v[214:215], off
	v_lshl_add_u64 v[214:215], s[24:25], 0, v[128:129]
	s_mov_b32 m0, s38
	s_nop 0
	global_load_lds_dwordx4 v[214:215], off
	s_mov_b32 m0, s39
	s_nop 0
	global_load_lds_dwordx4 v[216:217], off
	s_waitcnt vmcnt(8)
	s_waitcnt lgkmcnt(0)
	s_barrier
; #define PG8_STAGE(bufoff, gbase, voff) do { _Pragma("unroll") for (int _i = 0; _i < 2; ++_i) \
;         __builtin_amdgcn_global_load_lds((const unsigned*)((const char*)(gbase) + (voff)[_i]), (LAS unsigned*)(lds + (bufoff) + ldsw + _i * 8192), 16, 0, 0); } while (0)
; #define PG8_LDA(dst, b, h) do { _Pragma("unroll") for (int m = 0; m < 4; ++m) _Pragma("unroll") for (int k = 0; k < 2; ++k) dst[m][k] = *(const LAS bf16x8*)(lds + PG8_SA(b, h) + aoff + m * 2048 + k * 1024); } while (0)
; #define PG8_LDB(dst, b, h) do { _Pragma("unroll") for (int n = 0; n < 2; ++n) _Pragma("unroll") for (int k = 0; k < 2; ++k) dst[n][k] = *(const LAS bf16x8*)(lds + PG8_SB(b, h) + boff + n * 2048 + k * 1024); } while (0)
; #define PG8_MMA(ai, bj, At, Bt) do { __builtin_amdgcn_s_setprio(1); _Pragma("unroll") for (int m = 0; m < 4; ++m) _Pragma("unroll") for (int n = 0; n < 2; ++n) _Pragma("unroll") for (int k = 0; k < 2; ++k) \
;         acc[ai][bj][m][n] = __builtin_amdgcn_mfma_f32_16x16x32_bf16(Bt[n][k], At[m][k], acc[ai][bj][m][n], 0, 0, 0); __builtin_amdgcn_s_setprio(0); } while (0)
; #define PG8_WAIT_V(n) asm volatile("s_waitcnt vmcnt(" #n ")" ::: "memory")
; #define PG8_WAIT_L(n) asm volatile("s_waitcnt lgkmcnt(" #n ")" ::: "memory")
; #define PG8_BAR __builtin_amdgcn_s_barrier()
; #define PG8_SCHED __builtin_amdgcn_sched_barrier(0)
; template <class Epi>
; DI void gemm_phase(int wv, LAS unsigned char* lds, LAS unsigned char* scr, const Sched& S, const Epi& E) {
;     ...
;             PG8_WAIT_V(8); PG8_WAIT_L(0); PG8_BAR; PG8_MMA(1, 0, At, B0); PG8_MMA(1, 1, At, B1); PG8_BAR; PG8_SCHED;
;             PG8_LDB(B0, 1, 0); PG8_LDB(B1, 1, 1); PG8_SCHED; PG8_LDA(At, 1, 0); PG8_STAGE(PG8_SA(0, 1), a2 + hstepA, voffA);
;             PG8_WAIT_V(8); PG8_WAIT_L(0); PG8_BAR; PG8_MMA(0, 0, At, B0); PG8_MMA(0, 1, At, B1); PG8_BAR; PG8_SCHED;
	v_mfma_f32_16x16x32_bf16 v[60:63], v[144:147], v[176:179], v[60:63]
	v_mfma_f32_16x16x32_bf16 v[56:59], v[152:155], v[176:179], v[56:59]
	v_mfma_f32_16x16x32_bf16 v[52:55], v[144:147], v[184:187], v[52:55]
	v_mfma_f32_16x16x32_bf16 v[48:51], v[152:155], v[184:187], v[48:51]
	v_mfma_f32_16x16x32_bf16 v[36:39], v[144:147], v[194:197], v[36:39]
	v_mfma_f32_16x16x32_bf16 v[32:35], v[152:155], v[194:197], v[32:35]
	v_mfma_f32_16x16x32_bf16 v[20:23], v[144:147], v[202:205], v[20:23]
	v_mfma_f32_16x16x32_bf16 v[16:19], v[152:155], v[202:205], v[16:19]
	v_mfma_f32_16x16x32_bf16 v[60:63], v[148:151], v[180:183], v[60:63]
	v_mfma_f32_16x16x32_bf16 v[56:59], v[156:159], v[180:183], v[56:59]
	v_mfma_f32_16x16x32_bf16 v[52:55], v[148:151], v[188:191], v[52:55]
	v_mfma_f32_16x16x32_bf16 v[48:51], v[156:159], v[188:191], v[48:51]
	v_mfma_f32_16x16x32_bf16 v[36:39], v[148:151], v[198:201], v[36:39]
	v_mfma_f32_16x16x32_bf16 v[32:35], v[156:159], v[198:201], v[32:35]
	v_mfma_f32_16x16x32_bf16 v[20:23], v[148:151], v[206:209], v[20:23]
	v_mfma_f32_16x16x32_bf16 v[16:19], v[156:159], v[206:209], v[16:19]
	v_mfma_f32_16x16x32_bf16 v[44:47], v[160:163], v[176:179], v[44:47]
	v_mfma_f32_16x16x32_bf16 v[40:43], v[168:171], v[176:179], v[40:43]
	v_mfma_f32_16x16x32_bf16 v[28:31], v[160:163], v[184:187], v[28:31]
	v_mfma_f32_16x16x32_bf16 v[24:27], v[168:171], v[184:187], v[24:27]
	v_mfma_f32_16x16x32_bf16 v[12:15], v[160:163], v[194:197], v[12:15]
	v_mfma_f32_16x16x32_bf16 v[8:11], v[168:171], v[194:197], v[8:11]
	v_mfma_f32_16x16x32_bf16 v[4:7], v[160:163], v[202:205], v[4:7]
	v_mfma_f32_16x16x32_bf16 v[0:3], v[168:171], v[202:205], v[0:3]
	v_mfma_f32_16x16x32_bf16 v[44:47], v[164:167], v[180:183], v[44:47]
	v_mfma_f32_16x16x32_bf16 v[40:43], v[172:175], v[180:183], v[40:43]
	v_mfma_f32_16x16x32_bf16 v[28:31], v[164:167], v[188:191], v[28:31]
	v_mfma_f32_16x16x32_bf16 v[24:27], v[172:175], v[188:191], v[24:27]
	v_mfma_f32_16x16x32_bf16 v[12:15], v[164:167], v[198:201], v[12:15]
	v_mfma_f32_16x16x32_bf16 v[8:11], v[172:175], v[198:201], v[8:11]
	v_mfma_f32_16x16x32_bf16 v[4:7], v[164:167], v[206:209], v[4:7]
	v_mfma_f32_16x16x32_bf16 v[0:3], v[172:175], v[206:209], v[0:3]
	s_barrier
	s_add_i32 s56, 0, 0x18000
	s_add_i32 s57, 0, 0x1c000
	v_add_u32_e32 v156, s56, v142
	v_add_u32_e32 v172, s57, v142
	ds_read_b128 v[144:147], v156
	ds_read_b128 v[148:151], v156 offset:1024
	ds_read_b128 v[152:155], v156 offset:2048
	ds_read_b128 v[156:159], v156 offset:3072
	ds_read_b128 v[160:163], v172
	ds_read_b128 v[164:167], v172 offset:1024
	ds_read_b128 v[168:171], v172 offset:2048
	ds_read_b128 v[172:175], v172 offset:3072
	s_add_u32 s24, s24, 0x40000
	s_addc_u32 s25, s25, 0
	s_mov_b32 m0, s42
	v_lshl_add_u64 v[218:219], s[24:25], 0, v[128:129]
	ds_read_b128 v[176:179], v143 offset:32768
	ds_read_b128 v[180:183], v143 offset:33792
	ds_read_b128 v[184:187], v143 offset:34816
	ds_read_b128 v[188:191], v143 offset:35840
	ds_read_b128 v[194:197], v143 offset:36864
	ds_read_b128 v[198:201], v143 offset:37888
	ds_read_b128 v[202:205], v143 offset:38912
	ds_read_b128 v[206:209], v143 offset:39936
	global_load_lds_dwordx4 v[218:219], off
	v_lshl_add_u64 v[218:219], s[24:25], 0, v[132:133]
	s_mov_b32 m0, s43
	s_nop 0
	global_load_lds_dwordx4 v[218:219], off
	s_waitcnt vmcnt(8)
	s_waitcnt lgkmcnt(0)
	s_barrier
	v_mfma_f32_16x16x32_bf16 v[124:127], v[144:147], v[176:179], v[124:127]
	v_mfma_f32_16x16x32_bf16 v[120:123], v[152:155], v[176:179], v[120:123]
	v_mfma_f32_16x16x32_bf16 v[116:119], v[144:147], v[184:187], v[116:119]
	v_mfma_f32_16x16x32_bf16 v[112:115], v[152:155], v[184:187], v[112:115]
	v_mfma_f32_16x16x32_bf16 v[100:103], v[144:147], v[194:197], v[100:103]
	v_mfma_f32_16x16x32_bf16 v[96:99], v[152:155], v[194:197], v[96:99]
	v_mfma_f32_16x16x32_bf16 v[84:87], v[144:147], v[202:205], v[84:87]
	v_mfma_f32_16x16x32_bf16 v[80:83], v[152:155], v[202:205], v[80:83]
	v_mfma_f32_16x16x32_bf16 v[124:127], v[148:151], v[180:183], v[124:127]
	v_mfma_f32_16x16x32_bf16 v[120:123], v[156:159], v[180:183], v[120:123]
	v_mfma_f32_16x16x32_bf16 v[116:119], v[148:151], v[188:191], v[116:119]
	v_mfma_f32_16x16x32_bf16 v[112:115], v[156:159], v[188:191], v[112:115]
	v_mfma_f32_16x16x32_bf16 v[100:103], v[148:151], v[198:201], v[100:103]
	v_mfma_f32_16x16x32_bf16 v[96:99], v[156:159], v[198:201], v[96:99]
	v_mfma_f32_16x16x32_bf16 v[84:87], v[148:151], v[206:209], v[84:87]
	v_mfma_f32_16x16x32_bf16 v[80:83], v[156:159], v[206:209], v[80:83]
	v_mfma_f32_16x16x32_bf16 v[108:111], v[160:163], v[176:179], v[108:111]
	v_mfma_f32_16x16x32_bf16 v[104:107], v[168:171], v[176:179], v[104:107]
	v_mfma_f32_16x16x32_bf16 v[92:95], v[160:163], v[184:187], v[92:95]
	v_mfma_f32_16x16x32_bf16 v[88:91], v[168:171], v[184:187], v[88:91]
	v_mfma_f32_16x16x32_bf16 v[76:79], v[160:163], v[194:197], v[76:79]
	v_mfma_f32_16x16x32_bf16 v[72:75], v[168:171], v[194:197], v[72:75]
	v_mfma_f32_16x16x32_bf16 v[68:71], v[160:163], v[202:205], v[68:71]
	v_mfma_f32_16x16x32_bf16 v[64:67], v[168:171], v[202:205], v[64:67]
	v_mfma_f32_16x16x32_bf16 v[108:111], v[164:167], v[180:183], v[108:111]
	v_mfma_f32_16x16x32_bf16 v[104:107], v[172:175], v[180:183], v[104:107]
	v_mfma_f32_16x16x32_bf16 v[92:95], v[164:167], v[188:191], v[92:95]
	v_mfma_f32_16x16x32_bf16 v[88:91], v[172:175], v[188:191], v[88:91]
	v_mfma_f32_16x16x32_bf16 v[76:79], v[164:167], v[198:201], v[76:79]
	v_mfma_f32_16x16x32_bf16 v[72:75], v[172:175], v[198:201], v[72:75]
	v_mfma_f32_16x16x32_bf16 v[68:71], v[164:167], v[206:209], v[68:71]
	v_mfma_f32_16x16x32_bf16 v[64:67], v[172:175], v[206:209], v[64:67]
	s_barrier
; #define PG8_STAGE(bufoff, gbase, voff) do { _Pragma("unroll") for (int _i = 0; _i < 2; ++_i) \
;         __builtin_amdgcn_global_load_lds((const unsigned*)((const char*)(gbase) + (voff)[_i]), (LAS unsigned*)(lds + (bufoff) + ldsw + _i * 8192), 16, 0, 0); } while (0)
; #define PG8_LDA(dst, b, h) do { _Pragma("unroll") for (int m = 0; m < 4; ++m) _Pragma("unroll") for (int k = 0; k < 2; ++k) dst[m][k] = *(const LAS bf16x8*)(lds + PG8_SA(b, h) + aoff + m * 2048 + k * 1024); } while (0)
; #define PG8_MMA(ai, bj, At, Bt) do { __builtin_amdgcn_s_setprio(1); _Pragma("unroll") for (int m = 0; m < 4; ++m) _Pragma("unroll") for (int n = 0; n < 2; ++n) _Pragma("unroll") for (int k = 0; k < 2; ++k) \
;         acc[ai][bj][m][n] = __builtin_amdgcn_mfma_f32_16x16x32_bf16(Bt[n][k], At[m][k], acc[ai][bj][m][n], 0, 0, 0); __builtin_amdgcn_s_setprio(0); } while (0)
; #define PG8_WAIT_V(n) asm volatile("s_waitcnt vmcnt(" #n ")" ::: "memory")
; #define PG8_WAIT_L(n) asm volatile("s_waitcnt lgkmcnt(" #n ")" ::: "memory")
; #define PG8_BAR __builtin_amdgcn_s_barrier()
; #define PG8_SCHED __builtin_amdgcn_sched_barrier(0)
; template <class Epi>
; DI void gemm_phase(int wv, LAS unsigned char* lds, LAS unsigned char* scr, const Sched& S, const Epi& E) {
;     ...
;             PG8_LDA(At, 1, 1); PG8_STAGE(PG8_SB(1, 0), b3, voffB); PG8_STAGE(PG8_SB(1, 1), b3 + hstepB, voffB); PG8_STAGE(PG8_SA(1, 0), a3, voffA);
;             PG8_WAIT_V(8); PG8_WAIT_L(0); PG8_BAR; PG8_MMA(1, 0, At, B0); PG8_MMA(1, 1, At, B1); PG8_BAR; PG8_SCHED;
;         }
;         if (wr == 0) PG8_BAR;
	s_add_i32 s24, s56, s37
	v_lshl_add_u64 v[210:211], v[210:211], 0, s[2:3]
	s_mov_b32 m0, s24
	ds_read_b128 v[176:179], v143 offset:49152
	ds_read_b128 v[180:183], v143 offset:50176
	ds_read_b128 v[184:187], v143 offset:51200
	ds_read_b128 v[188:191], v143 offset:52224
	ds_read_b128 v[194:197], v143 offset:53248
	ds_read_b128 v[198:201], v143 offset:54272
	ds_read_b128 v[202:205], v143 offset:55296
	ds_read_b128 v[206:209], v143 offset:56320
	global_load_lds_dwordx4 v[210:211], off
	s_add_i32 m0, s24, 0x2000
	s_add_u32 s22, s22, 0x40080
	v_lshl_add_u64 v[210:211], v[212:213], 0, s[2:3]
	s_addc_u32 s23, s23, 0
	s_add_i32 s24, s57, s37
	global_load_lds_dwordx4 v[210:211], off
	v_lshl_add_u64 v[210:211], s[22:23], 0, v[130:131]
	s_mov_b32 m0, s24
	s_nop 0
	global_load_lds_dwordx4 v[210:211], off
	v_lshl_add_u64 v[210:211], s[22:23], 0, v[134:135]
	s_add_i32 m0, s24, 0x2000
	s_nop 0
	global_load_lds_dwordx4 v[210:211], off
	v_lshl_add_u64 v[210:211], v[214:215], 0, s[2:3]
	s_mov_b32 m0, s46
	s_nop 0
	global_load_lds_dwordx4 v[210:211], off
	v_lshl_add_u64 v[210:211], v[216:217], 0, s[2:3]
	s_mov_b32 m0, s47
	s_nop 0
	global_load_lds_dwordx4 v[210:211], off
	s_waitcnt vmcnt(8)
	s_waitcnt lgkmcnt(0)
	s_barrier
	v_mfma_f32_16x16x32_bf16 v[60:63], v[144:147], v[176:179], v[60:63]
	v_mfma_f32_16x16x32_bf16 v[56:59], v[152:155], v[176:179], v[56:59]
	v_mfma_f32_16x16x32_bf16 v[52:55], v[144:147], v[184:187], v[52:55]
	v_mfma_f32_16x16x32_bf16 v[48:51], v[152:155], v[184:187], v[48:51]
	v_mfma_f32_16x16x32_bf16 v[36:39], v[144:147], v[194:197], v[36:39]
	v_mfma_f32_16x16x32_bf16 v[32:35], v[152:155], v[194:197], v[32:35]
	v_mfma_f32_16x16x32_bf16 v[20:23], v[144:147], v[202:205], v[20:23]
	v_mfma_f32_16x16x32_bf16 v[16:19], v[152:155], v[202:205], v[16:19]
	v_mfma_f32_16x16x32_bf16 v[60:63], v[148:151], v[180:183], v[60:63]
	v_mfma_f32_16x16x32_bf16 v[56:59], v[156:159], v[180:183], v[56:59]
	v_mfma_f32_16x16x32_bf16 v[52:55], v[148:151], v[188:191], v[52:55]
	v_mfma_f32_16x16x32_bf16 v[48:51], v[156:159], v[188:191], v[48:51]
	v_mfma_f32_16x16x32_bf16 v[36:39], v[148:151], v[198:201], v[36:39]
	v_mfma_f32_16x16x32_bf16 v[32:35], v[156:159], v[198:201], v[32:35]
	v_mfma_f32_16x16x32_bf16 v[20:23], v[148:151], v[206:209], v[20:23]
	v_mfma_f32_16x16x32_bf16 v[16:19], v[156:159], v[206:209], v[16:19]
	v_mfma_f32_16x16x32_bf16 v[44:47], v[160:163], v[176:179], v[44:47]
	v_mfma_f32_16x16x32_bf16 v[40:43], v[168:171], v[176:179], v[40:43]
	v_mfma_f32_16x16x32_bf16 v[28:31], v[160:163], v[184:187], v[28:31]
	v_mfma_f32_16x16x32_bf16 v[24:27], v[168:171], v[184:187], v[24:27]
	v_mfma_f32_16x16x32_bf16 v[12:15], v[160:163], v[194:197], v[12:15]
	v_mfma_f32_16x16x32_bf16 v[8:11], v[168:171], v[194:197], v[8:11]
	v_mfma_f32_16x16x32_bf16 v[4:7], v[160:163], v[202:205], v[4:7]
	v_mfma_f32_16x16x32_bf16 v[0:3], v[168:171], v[202:205], v[0:3]
	v_mfma_f32_16x16x32_bf16 v[44:47], v[164:167], v[180:183], v[44:47]
	v_mfma_f32_16x16x32_bf16 v[40:43], v[172:175], v[180:183], v[40:43]
	v_mfma_f32_16x16x32_bf16 v[28:31], v[164:167], v[188:191], v[28:31]
	v_mfma_f32_16x16x32_bf16 v[24:27], v[172:175], v[188:191], v[24:27]
	v_mfma_f32_16x16x32_bf16 v[12:15], v[164:167], v[198:201], v[12:15]
	v_mfma_f32_16x16x32_bf16 v[8:11], v[172:175], v[198:201], v[8:11]
	v_mfma_f32_16x16x32_bf16 v[4:7], v[164:167], v[206:209], v[4:7]
	v_mfma_f32_16x16x32_bf16 v[0:3], v[172:175], v[206:209], v[0:3]
	s_barrier
	s_add_i32 s53, s53, 2
	s_add_u32 s49, s49, 0x100
	s_addc_u32 s52, s52, 0
	s_add_u32 s20, s20, 0x100
	s_addc_u32 s21, s21, 0
	s_cmp_gt_u32 s53, 13
	s_cbranch_scc0 .LBB0_43
	s_and_b64 vcc, exec, s[4:5]
	s_cbranch_vccz .LBB0_46
	s_barrier

; #define PG8_STAGE(bufoff, gbase, voff) do { _Pragma("unroll") for (int _i = 0; _i < 2; ++_i) \
;         __builtin_amdgcn_global_load_lds((const unsigned*)((const char*)(gbase) + (voff)[_i]), (LAS unsigned*)(lds + (bufoff) + ldsw + _i * 8192), 16, 0, 0); } while (0)
; #define PG8_LDA(dst, b, h) do { _Pragma("unroll") for (int m = 0; m < 4; ++m) _Pragma("unroll") for (int k = 0; k < 2; ++k) dst[m][k] = *(const LAS bf16x8*)(lds + PG8_SA(b, h) + aoff + m * 2048 + k * 1024); } while (0)
; #define PG8_LDB(dst, b, h) do { _Pragma("unroll") for (int n = 0; n < 2; ++n) _Pragma("unroll") for (int k = 0; k < 2; ++k) dst[n][k] = *(const LAS bf16x8*)(lds + PG8_SB(b, h) + boff + n * 2048 + k * 1024); } while (0)
; #define PG8_MMA(ai, bj, At, Bt) do { __builtin_amdgcn_s_setprio(1); _Pragma("unroll") for (int m = 0; m < 4; ++m) _Pragma("unroll") for (int n = 0; n < 2; ++n) _Pragma("unroll") for (int k = 0; k < 2; ++k) \
;         acc[ai][bj][m][n] = __builtin_amdgcn_mfma_f32_16x16x32_bf16(Bt[n][k], At[m][k], acc[ai][bj][m][n], 0, 0, 0); __builtin_amdgcn_s_setprio(0); } while (0)
; #define PG8_WAIT_V(n) asm volatile("s_waitcnt vmcnt(" #n ")" ::: "memory")
; #define PG8_WAIT_L(n) asm volatile("s_waitcnt lgkmcnt(" #n ")" ::: "memory")
; #define PG8_BAR __builtin_amdgcn_s_barrier()
; #define PG8_SCHED __builtin_amdgcn_sched_barrier(0)
; template <class Epi>
; DI void gemm_phase(int wv, LAS unsigned char* lds, LAS unsigned char* scr, const Sched& S, const Epi& E) {
;     ...
;             PG8_LDB(B0, 0, 0); PG8_LDB(B1, 0, 1); PG8_SCHED; PG8_LDA(At, 0, 0); PG8_STAGE(PG8_SA(1, 1), a1 + hstepA, voffA);
;             PG8_WAIT_V(8); PG8_WAIT_L(0); PG8_BAR; PG8_MMA(0, 0, At, B0); PG8_MMA(0, 1, At, B1); PG8_BAR; PG8_SCHED;
;             PG8_LDA(At, 0, 1); PG8_STAGE(PG8_SB(0, 0), b2, voffB); PG8_STAGE(PG8_SB(0, 1), b2 + hstepB, voffB); PG8_STAGE(PG8_SA(0, 0), a2, voffA);
;             PG8_WAIT_V(8); PG8_WAIT_L(0); PG8_BAR; PG8_MMA(1, 0, At, B0); PG8_MMA(1, 1, At, B1); PG8_BAR; PG8_SCHED;
.LBB0_89:
	s_add_u32 s24, s22, 0xfffc0080
	s_addc_u32 s25, s23, -1
	s_add_i32 s58, 0, 0x10000
	s_cmp_eq_u32 s57, 12
	s_cselect_b32 s27, s15, s25
	s_cselect_b32 s26, s33, s24
	v_add_u32_e32 v145, s58, v150
	s_cselect_b32 s25, s13, s49
	s_cselect_b32 s24, s47, s48
	s_add_i32 s62, 0, 0x14000
	ds_read_b128 v[152:155], v145
	ds_read_b128 v[156:159], v145 offset:1024
	ds_read_b128 v[160:163], v145 offset:2048
	ds_read_b128 v[164:167], v145 offset:3072
	v_add_u32_e32 v145, s62, v150
	ds_read_b128 v[168:171], v145
	ds_read_b128 v[172:175], v145 offset:1024
	ds_read_b128 v[176:179], v145 offset:2048
	ds_read_b128 v[180:183], v145 offset:3072
	v_lshl_add_u64 v[148:149], s[22:23], 0, v[142:143]
	s_add_i32 m0, s36, 0xc000
	ds_read_b128 v[184:187], v151
	ds_read_b128 v[188:191], v151 offset:1024
	ds_read_b128 v[194:197], v151 offset:2048
	ds_read_b128 v[198:201], v151 offset:3072
	ds_read_b128 v[202:205], v151 offset:4096
	ds_read_b128 v[206:209], v151 offset:5120
	ds_read_b128 v[210:213], v151 offset:6144
	ds_read_b128 v[214:217], v151 offset:7168
	global_load_lds_dwordx4 v[148:149], off
	v_lshl_add_u64 v[148:149], s[22:23], 0, v[140:141]
	s_add_i32 m0, s36, 0xe000
	s_nop 0
	global_load_lds_dwordx4 v[148:149], off
	s_waitcnt vmcnt(8)
	s_waitcnt lgkmcnt(0)
	s_barrier
	v_mfma_f32_16x16x32_bf16 v[124:127], v[152:155], v[184:187], v[124:127]
	v_mfma_f32_16x16x32_bf16 v[120:123], v[160:163], v[184:187], v[120:123]
	v_mfma_f32_16x16x32_bf16 v[108:111], v[152:155], v[194:197], v[108:111]
	v_mfma_f32_16x16x32_bf16 v[104:107], v[160:163], v[194:197], v[104:107]
	v_mfma_f32_16x16x32_bf16 v[92:95], v[152:155], v[202:205], v[92:95]
	v_mfma_f32_16x16x32_bf16 v[88:91], v[160:163], v[202:205], v[88:91]
	v_mfma_f32_16x16x32_bf16 v[76:79], v[152:155], v[210:213], v[76:79]
	v_mfma_f32_16x16x32_bf16 v[72:75], v[160:163], v[210:213], v[72:75]
	v_mfma_f32_16x16x32_bf16 v[124:127], v[156:159], v[188:191], v[124:127]
	v_mfma_f32_16x16x32_bf16 v[120:123], v[164:167], v[188:191], v[120:123]
	v_mfma_f32_16x16x32_bf16 v[108:111], v[156:159], v[198:201], v[108:111]
	v_mfma_f32_16x16x32_bf16 v[104:107], v[164:167], v[198:201], v[104:107]
	v_mfma_f32_16x16x32_bf16 v[92:95], v[156:159], v[206:209], v[92:95]
	v_mfma_f32_16x16x32_bf16 v[88:91], v[164:167], v[206:209], v[88:91]
	v_mfma_f32_16x16x32_bf16 v[76:79], v[156:159], v[214:217], v[76:79]
	v_mfma_f32_16x16x32_bf16 v[72:75], v[164:167], v[214:217], v[72:75]
	v_mfma_f32_16x16x32_bf16 v[116:119], v[168:171], v[184:187], v[116:119]
	v_mfma_f32_16x16x32_bf16 v[112:115], v[176:179], v[184:187], v[112:115]
	v_mfma_f32_16x16x32_bf16 v[100:103], v[168:171], v[194:197], v[100:103]
	v_mfma_f32_16x16x32_bf16 v[96:99], v[176:179], v[194:197], v[96:99]
	v_mfma_f32_16x16x32_bf16 v[84:87], v[168:171], v[202:205], v[84:87]
	v_mfma_f32_16x16x32_bf16 v[80:83], v[176:179], v[202:205], v[80:83]
	v_mfma_f32_16x16x32_bf16 v[68:71], v[168:171], v[210:213], v[68:71]
	v_mfma_f32_16x16x32_bf16 v[64:67], v[176:179], v[210:213], v[64:67]
	v_mfma_f32_16x16x32_bf16 v[116:119], v[172:175], v[188:191], v[116:119]
	v_mfma_f32_16x16x32_bf16 v[112:115], v[180:183], v[188:191], v[112:115]
	v_mfma_f32_16x16x32_bf16 v[100:103], v[172:175], v[198:201], v[100:103]
	v_mfma_f32_16x16x32_bf16 v[96:99], v[180:183], v[198:201], v[96:99]
	v_mfma_f32_16x16x32_bf16 v[84:87], v[172:175], v[206:209], v[84:87]
	v_mfma_f32_16x16x32_bf16 v[80:83], v[180:183], v[206:209], v[80:83]
	v_mfma_f32_16x16x32_bf16 v[68:71], v[172:175], v[214:217], v[68:71]
	v_mfma_f32_16x16x32_bf16 v[64:67], v[180:183], v[214:217], v[64:67]
	s_barrier
	s_add_i32 s58, s58, s35
	v_lshl_add_u64 v[148:149], s[24:25], 0, v[130:131]
	s_mov_b32 m0, s58
	ds_read_b128 v[184:187], v151 offset:16384
	ds_read_b128 v[188:191], v151 offset:17408
	ds_read_b128 v[194:197], v151 offset:18432
	ds_read_b128 v[198:201], v151 offset:19456
	ds_read_b128 v[202:205], v151 offset:20480
	ds_read_b128 v[206:209], v151 offset:21504
	ds_read_b128 v[210:213], v151 offset:22528
	ds_read_b128 v[214:217], v151 offset:23552
	global_load_lds_dwordx4 v[148:149], off
	s_add_i32 m0, s58, 0x2000
	s_add_u32 s60, s24, 0x40000
	v_lshl_add_u64 v[218:219], s[24:25], 0, v[134:135]
	s_addc_u32 s61, s25, 0
	s_add_i32 s58, s62, s35
	global_load_lds_dwordx4 v[218:219], off
	v_lshl_add_u64 v[220:221], s[60:61], 0, v[130:131]
	s_mov_b32 m0, s58
	v_lshl_add_u64 v[222:223], s[26:27], 0, v[132:133]
	global_load_lds_dwordx4 v[220:221], off
	v_lshl_add_u64 v[220:221], s[60:61], 0, v[134:135]
	s_add_i32 m0, s58, 0x2000
	s_nop 0
	global_load_lds_dwordx4 v[220:221], off
	v_lshl_add_u64 v[220:221], s[26:27], 0, v[128:129]
	s_mov_b32 m0, s36
	s_nop 0
	global_load_lds_dwordx4 v[220:221], off
	s_mov_b32 m0, s37
	s_nop 0
	global_load_lds_dwordx4 v[222:223], off
	s_waitcnt vmcnt(8)
	s_waitcnt lgkmcnt(0)
	s_barrier
; #define PG8_STAGE(bufoff, gbase, voff) do { _Pragma("unroll") for (int _i = 0; _i < 2; ++_i) \
;         __builtin_amdgcn_global_load_lds((const unsigned*)((const char*)(gbase) + (voff)[_i]), (LAS unsigned*)(lds + (bufoff) + ldsw + _i * 8192), 16, 0, 0); } while (0)
; #define PG8_LDA(dst, b, h) do { _Pragma("unroll") for (int m = 0; m < 4; ++m) _Pragma("unroll") for (int k = 0; k < 2; ++k) dst[m][k] = *(const LAS bf16x8*)(lds + PG8_SA(b, h) + aoff + m * 2048 + k * 1024); } while (0)
; #define PG8_LDB(dst, b, h) do { _Pragma("unroll") for (int n = 0; n < 2; ++n) _Pragma("unroll") for (int k = 0; k < 2; ++k) dst[n][k] = *(const LAS bf16x8*)(lds + PG8_SB(b, h) + boff + n * 2048 + k * 1024); } while (0)
; #define PG8_MMA(ai, bj, At, Bt) do { __builtin_amdgcn_s_setprio(1); _Pragma("unroll") for (int m = 0; m < 4; ++m) _Pragma("unroll") for (int n = 0; n < 2; ++n) _Pragma("unroll") for (int k = 0; k < 2; ++k) \
;         acc[ai][bj][m][n] = __builtin_amdgcn_mfma_f32_16x16x32_bf16(Bt[n][k], At[m][k], acc[ai][bj][m][n], 0, 0, 0); __builtin_amdgcn_s_setprio(0); } while (0)
; #define PG8_WAIT_V(n) asm volatile("s_waitcnt vmcnt(" #n ")" ::: "memory")
; #define PG8_WAIT_L(n) asm volatile("s_waitcnt lgkmcnt(" #n ")" ::: "memory")
; #define PG8_BAR __builtin_amdgcn_s_barrier()
; #define PG8_SCHED __builtin_amdgcn_sched_barrier(0)
; template <class Epi>
; DI void gemm_phase(int wv, LAS unsigned char* lds, LAS unsigned char* scr, const Sched& S, const Epi& E) {
;     ...
;             PG8_WAIT_V(8); PG8_WAIT_L(0); PG8_BAR; PG8_MMA(1, 0, At, B0); PG8_MMA(1, 1, At, B1); PG8_BAR; PG8_SCHED;
;             PG8_LDB(B0, 1, 0); PG8_LDB(B1, 1, 1); PG8_SCHED; PG8_LDA(At, 1, 0); PG8_STAGE(PG8_SA(0, 1), a2 + hstepA, voffA);
;             PG8_WAIT_V(8); PG8_WAIT_L(0); PG8_BAR; PG8_MMA(0, 0, At, B0); PG8_MMA(0, 1, At, B1); PG8_BAR; PG8_SCHED;
	v_mfma_f32_16x16x32_bf16 v[60:63], v[152:155], v[184:187], v[60:63]
	v_mfma_f32_16x16x32_bf16 v[56:59], v[160:163], v[184:187], v[56:59]
	v_mfma_f32_16x16x32_bf16 v[44:47], v[152:155], v[194:197], v[44:47]
	v_mfma_f32_16x16x32_bf16 v[40:43], v[160:163], v[194:197], v[40:43]
	v_mfma_f32_16x16x32_bf16 v[28:31], v[152:155], v[202:205], v[28:31]
	v_mfma_f32_16x16x32_bf16 v[24:27], v[160:163], v[202:205], v[24:27]
	v_mfma_f32_16x16x32_bf16 v[12:15], v[152:155], v[210:213], v[12:15]
	v_mfma_f32_16x16x32_bf16 v[8:11], v[160:163], v[210:213], v[8:11]
	v_mfma_f32_16x16x32_bf16 v[60:63], v[156:159], v[188:191], v[60:63]
	v_mfma_f32_16x16x32_bf16 v[56:59], v[164:167], v[188:191], v[56:59]
	v_mfma_f32_16x16x32_bf16 v[44:47], v[156:159], v[198:201], v[44:47]
	v_mfma_f32_16x16x32_bf16 v[40:43], v[164:167], v[198:201], v[40:43]
	v_mfma_f32_16x16x32_bf16 v[28:31], v[156:159], v[206:209], v[28:31]
	v_mfma_f32_16x16x32_bf16 v[24:27], v[164:167], v[206:209], v[24:27]
	v_mfma_f32_16x16x32_bf16 v[12:15], v[156:159], v[214:217], v[12:15]
	v_mfma_f32_16x16x32_bf16 v[8:11], v[164:167], v[214:217], v[8:11]
	v_mfma_f32_16x16x32_bf16 v[52:55], v[168:171], v[184:187], v[52:55]
	v_mfma_f32_16x16x32_bf16 v[48:51], v[176:179], v[184:187], v[48:51]
	v_mfma_f32_16x16x32_bf16 v[36:39], v[168:171], v[194:197], v[36:39]
	v_mfma_f32_16x16x32_bf16 v[32:35], v[176:179], v[194:197], v[32:35]
	v_mfma_f32_16x16x32_bf16 v[20:23], v[168:171], v[202:205], v[20:23]
	v_mfma_f32_16x16x32_bf16 v[16:19], v[176:179], v[202:205], v[16:19]
	v_mfma_f32_16x16x32_bf16 v[4:7], v[168:171], v[210:213], v[4:7]
	v_mfma_f32_16x16x32_bf16 v[0:3], v[176:179], v[210:213], v[0:3]
	v_mfma_f32_16x16x32_bf16 v[52:55], v[172:175], v[188:191], v[52:55]
	v_mfma_f32_16x16x32_bf16 v[48:51], v[180:183], v[188:191], v[48:51]
	v_mfma_f32_16x16x32_bf16 v[36:39], v[172:175], v[198:201], v[36:39]
	v_mfma_f32_16x16x32_bf16 v[32:35], v[180:183], v[198:201], v[32:35]
	v_mfma_f32_16x16x32_bf16 v[20:23], v[172:175], v[206:209], v[20:23]
	v_mfma_f32_16x16x32_bf16 v[16:19], v[180:183], v[206:209], v[16:19]
	v_mfma_f32_16x16x32_bf16 v[4:7], v[172:175], v[214:217], v[4:7]
	v_mfma_f32_16x16x32_bf16 v[0:3], v[180:183], v[214:217], v[0:3]
	s_barrier
	s_add_i32 s58, 0, 0x18000
	v_add_u32_e32 v145, s58, v150
	s_add_i32 s60, 0, 0x1c000
	ds_read_b128 v[152:155], v145
	ds_read_b128 v[156:159], v145 offset:1024
	ds_read_b128 v[160:163], v145 offset:2048
	ds_read_b128 v[164:167], v145 offset:3072
	v_add_u32_e32 v145, s60, v150
	ds_read_b128 v[168:171], v145
	ds_read_b128 v[172:175], v145 offset:1024
	ds_read_b128 v[176:179], v145 offset:2048
	ds_read_b128 v[180:183], v145 offset:3072
	s_add_u32 s26, s26, 0x40000
	s_addc_u32 s27, s27, 0
	s_mov_b32 m0, s38
	v_lshl_add_u64 v[224:225], s[26:27], 0, v[128:129]
	ds_read_b128 v[184:187], v151 offset:32768
	ds_read_b128 v[188:191], v151 offset:33792
	ds_read_b128 v[194:197], v151 offset:34816
	ds_read_b128 v[198:201], v151 offset:35840
	ds_read_b128 v[202:205], v151 offset:36864
	ds_read_b128 v[206:209], v151 offset:37888
	ds_read_b128 v[210:213], v151 offset:38912
	ds_read_b128 v[214:217], v151 offset:39936
	global_load_lds_dwordx4 v[224:225], off
	v_lshl_add_u64 v[224:225], s[26:27], 0, v[132:133]
	s_mov_b32 m0, s39
	s_nop 0
	global_load_lds_dwordx4 v[224:225], off
	s_waitcnt vmcnt(8)
	s_waitcnt lgkmcnt(0)
	s_barrier
	v_mfma_f32_16x16x32_bf16 v[124:127], v[152:155], v[184:187], v[124:127]
	v_mfma_f32_16x16x32_bf16 v[120:123], v[160:163], v[184:187], v[120:123]
	v_mfma_f32_16x16x32_bf16 v[108:111], v[152:155], v[194:197], v[108:111]
	v_mfma_f32_16x16x32_bf16 v[104:107], v[160:163], v[194:197], v[104:107]
	v_mfma_f32_16x16x32_bf16 v[92:95], v[152:155], v[202:205], v[92:95]
	v_mfma_f32_16x16x32_bf16 v[88:91], v[160:163], v[202:205], v[88:91]
	v_mfma_f32_16x16x32_bf16 v[76:79], v[152:155], v[210:213], v[76:79]
	v_mfma_f32_16x16x32_bf16 v[72:75], v[160:163], v[210:213], v[72:75]
	v_mfma_f32_16x16x32_bf16 v[124:127], v[156:159], v[188:191], v[124:127]
	v_mfma_f32_16x16x32_bf16 v[120:123], v[164:167], v[188:191], v[120:123]
	v_mfma_f32_16x16x32_bf16 v[108:111], v[156:159], v[198:201], v[108:111]
	v_mfma_f32_16x16x32_bf16 v[104:107], v[164:167], v[198:201], v[104:107]
	v_mfma_f32_16x16x32_bf16 v[92:95], v[156:159], v[206:209], v[92:95]
	v_mfma_f32_16x16x32_bf16 v[88:91], v[164:167], v[206:209], v[88:91]
	v_mfma_f32_16x16x32_bf16 v[76:79], v[156:159], v[214:217], v[76:79]
	v_mfma_f32_16x16x32_bf16 v[72:75], v[164:167], v[214:217], v[72:75]
	v_mfma_f32_16x16x32_bf16 v[116:119], v[168:171], v[184:187], v[116:119]
	v_mfma_f32_16x16x32_bf16 v[112:115], v[176:179], v[184:187], v[112:115]
	v_mfma_f32_16x16x32_bf16 v[100:103], v[168:171], v[194:197], v[100:103]
	v_mfma_f32_16x16x32_bf16 v[96:99], v[176:179], v[194:197], v[96:99]
	v_mfma_f32_16x16x32_bf16 v[84:87], v[168:171], v[202:205], v[84:87]
	v_mfma_f32_16x16x32_bf16 v[80:83], v[176:179], v[202:205], v[80:83]
	v_mfma_f32_16x16x32_bf16 v[68:71], v[168:171], v[210:213], v[68:71]
	v_mfma_f32_16x16x32_bf16 v[64:67], v[176:179], v[210:213], v[64:67]
	v_mfma_f32_16x16x32_bf16 v[116:119], v[172:175], v[188:191], v[116:119]
	v_mfma_f32_16x16x32_bf16 v[112:115], v[180:183], v[188:191], v[112:115]
	v_mfma_f32_16x16x32_bf16 v[100:103], v[172:175], v[198:201], v[100:103]
	v_mfma_f32_16x16x32_bf16 v[96:99], v[180:183], v[198:201], v[96:99]
	v_mfma_f32_16x16x32_bf16 v[84:87], v[172:175], v[206:209], v[84:87]
	v_mfma_f32_16x16x32_bf16 v[80:83], v[180:183], v[206:209], v[80:83]
	v_mfma_f32_16x16x32_bf16 v[68:71], v[172:175], v[214:217], v[68:71]
	v_mfma_f32_16x16x32_bf16 v[64:67], v[180:183], v[214:217], v[64:67]
	s_barrier
; #define PG8_STAGE(bufoff, gbase, voff) do { _Pragma("unroll") for (int _i = 0; _i < 2; ++_i) \
;         __builtin_amdgcn_global_load_lds((const unsigned*)((const char*)(gbase) + (voff)[_i]), (LAS unsigned*)(lds + (bufoff) + ldsw + _i * 8192), 16, 0, 0); } while (0)
; #define PG8_LDA(dst, b, h) do { _Pragma("unroll") for (int m = 0; m < 4; ++m) _Pragma("unroll") for (int k = 0; k < 2; ++k) dst[m][k] = *(const LAS bf16x8*)(lds + PG8_SA(b, h) + aoff + m * 2048 + k * 1024); } while (0)
; #define PG8_MMA(ai, bj, At, Bt) do { __builtin_amdgcn_s_setprio(1); _Pragma("unroll") for (int m = 0; m < 4; ++m) _Pragma("unroll") for (int n = 0; n < 2; ++n) _Pragma("unroll") for (int k = 0; k < 2; ++k) \
;         acc[ai][bj][m][n] = __builtin_amdgcn_mfma_f32_16x16x32_bf16(Bt[n][k], At[m][k], acc[ai][bj][m][n], 0, 0, 0); __builtin_amdgcn_s_setprio(0); } while (0)
; #define PG8_WAIT_V(n) asm volatile("s_waitcnt vmcnt(" #n ")" ::: "memory")
; #define PG8_WAIT_L(n) asm volatile("s_waitcnt lgkmcnt(" #n ")" ::: "memory")
; #define PG8_BAR __builtin_amdgcn_s_barrier()
; #define PG8_SCHED __builtin_amdgcn_sched_barrier(0)
; template <class Epi>
; DI void gemm_phase(int wv, LAS unsigned char* lds, LAS unsigned char* scr, const Sched& S, const Epi& E) {
;     ...
;             PG8_LDA(At, 1, 1); PG8_STAGE(PG8_SB(1, 0), b3, voffB); PG8_STAGE(PG8_SB(1, 1), b3 + hstepB, voffB); PG8_STAGE(PG8_SA(1, 0), a3, voffA);
;             PG8_WAIT_V(8); PG8_WAIT_L(0); PG8_BAR; PG8_MMA(1, 0, At, B0); PG8_MMA(1, 1, At, B1); PG8_BAR; PG8_SCHED;
;         }
;         if (wr == 0) PG8_BAR;
	s_add_i32 s26, s58, s35
	v_lshl_add_u64 v[148:149], v[148:149], 0, s[2:3]
	s_mov_b32 m0, s26
	ds_read_b128 v[184:187], v151 offset:49152
	ds_read_b128 v[188:191], v151 offset:50176
	ds_read_b128 v[194:197], v151 offset:51200
	ds_read_b128 v[198:201], v151 offset:52224
	ds_read_b128 v[202:205], v151 offset:53248
	ds_read_b128 v[206:209], v151 offset:54272
	ds_read_b128 v[210:213], v151 offset:55296
	ds_read_b128 v[214:217], v151 offset:56320
	global_load_lds_dwordx4 v[148:149], off
	s_add_i32 m0, s26, 0x2000
	s_add_u32 s24, s24, 0x40080
	v_lshl_add_u64 v[148:149], v[218:219], 0, s[2:3]
	s_addc_u32 s25, s25, 0
	s_add_i32 s26, s60, s35
	global_load_lds_dwordx4 v[148:149], off
	v_lshl_add_u64 v[148:149], s[24:25], 0, v[130:131]
	s_mov_b32 m0, s26
	s_nop 0
	global_load_lds_dwordx4 v[148:149], off
	v_lshl_add_u64 v[148:149], s[24:25], 0, v[134:135]
	s_add_i32 m0, s26, 0x2000
	s_nop 0
	global_load_lds_dwordx4 v[148:149], off
	v_lshl_add_u64 v[148:149], v[220:221], 0, s[2:3]
	s_mov_b32 m0, s42
	s_nop 0
	global_load_lds_dwordx4 v[148:149], off
	v_lshl_add_u64 v[148:149], v[222:223], 0, s[2:3]
	s_mov_b32 m0, s43
	s_nop 0
	global_load_lds_dwordx4 v[148:149], off
	s_waitcnt vmcnt(8)
	s_waitcnt lgkmcnt(0)
	s_barrier
	v_mfma_f32_16x16x32_bf16 v[60:63], v[152:155], v[184:187], v[60:63]
	v_mfma_f32_16x16x32_bf16 v[56:59], v[160:163], v[184:187], v[56:59]
	v_mfma_f32_16x16x32_bf16 v[44:47], v[152:155], v[194:197], v[44:47]
	v_mfma_f32_16x16x32_bf16 v[40:43], v[160:163], v[194:197], v[40:43]
	v_mfma_f32_16x16x32_bf16 v[28:31], v[152:155], v[202:205], v[28:31]
	v_mfma_f32_16x16x32_bf16 v[24:27], v[160:163], v[202:205], v[24:27]
	v_mfma_f32_16x16x32_bf16 v[12:15], v[152:155], v[210:213], v[12:15]
	v_mfma_f32_16x16x32_bf16 v[8:11], v[160:163], v[210:213], v[8:11]
	v_mfma_f32_16x16x32_bf16 v[60:63], v[156:159], v[188:191], v[60:63]
	v_mfma_f32_16x16x32_bf16 v[56:59], v[164:167], v[188:191], v[56:59]
	v_mfma_f32_16x16x32_bf16 v[44:47], v[156:159], v[198:201], v[44:47]
	v_mfma_f32_16x16x32_bf16 v[40:43], v[164:167], v[198:201], v[40:43]
	v_mfma_f32_16x16x32_bf16 v[28:31], v[156:159], v[206:209], v[28:31]
	v_mfma_f32_16x16x32_bf16 v[24:27], v[164:167], v[206:209], v[24:27]
	v_mfma_f32_16x16x32_bf16 v[12:15], v[156:159], v[214:217], v[12:15]
	v_mfma_f32_16x16x32_bf16 v[8:11], v[164:167], v[214:217], v[8:11]
	v_mfma_f32_16x16x32_bf16 v[52:55], v[168:171], v[184:187], v[52:55]
	v_mfma_f32_16x16x32_bf16 v[48:51], v[176:179], v[184:187], v[48:51]
	v_mfma_f32_16x16x32_bf16 v[36:39], v[168:171], v[194:197], v[36:39]
	v_mfma_f32_16x16x32_bf16 v[32:35], v[176:179], v[194:197], v[32:35]
	v_mfma_f32_16x16x32_bf16 v[20:23], v[168:171], v[202:205], v[20:23]
	v_mfma_f32_16x16x32_bf16 v[16:19], v[176:179], v[202:205], v[16:19]
	v_mfma_f32_16x16x32_bf16 v[4:7], v[168:171], v[210:213], v[4:7]
	v_mfma_f32_16x16x32_bf16 v[0:3], v[176:179], v[210:213], v[0:3]
	v_mfma_f32_16x16x32_bf16 v[52:55], v[172:175], v[188:191], v[52:55]
	v_mfma_f32_16x16x32_bf16 v[48:51], v[180:183], v[188:191], v[48:51]
	v_mfma_f32_16x16x32_bf16 v[36:39], v[172:175], v[198:201], v[36:39]
	v_mfma_f32_16x16x32_bf16 v[32:35], v[180:183], v[198:201], v[32:35]
	v_mfma_f32_16x16x32_bf16 v[20:23], v[172:175], v[206:209], v[20:23]
	v_mfma_f32_16x16x32_bf16 v[16:19], v[180:183], v[206:209], v[16:19]
	v_mfma_f32_16x16x32_bf16 v[4:7], v[172:175], v[214:217], v[4:7]
	v_mfma_f32_16x16x32_bf16 v[0:3], v[180:183], v[214:217], v[0:3]
	s_barrier
	s_add_i32 s57, s57, 2
	s_add_u32 s48, s48, 0x100
	s_addc_u32 s49, s49, 0
	s_add_u32 s22, s22, 0x100
	s_addc_u32 s23, s23, 0
	s_cmp_gt_u32 s57, 13
	s_cbranch_scc0 .LBB0_89
	s_and_b64 vcc, exec, s[10:11]
	s_cbranch_vccz .LBB0_92
	s_barrier

; #define PG8_STAGE(bufoff, gbase, voff) do { _Pragma("unroll") for (int _i = 0; _i < 2; ++_i) \
;         __builtin_amdgcn_global_load_lds((const unsigned*)((const char*)(gbase) + (voff)[_i]), (LAS unsigned*)(lds + (bufoff) + ldsw + _i * 8192), 16, 0, 0); } while (0)
; #define PG8_LDA(dst, b, h) do { _Pragma("unroll") for (int m = 0; m < 4; ++m) _Pragma("unroll") for (int k = 0; k < 2; ++k) dst[m][k] = *(const LAS bf16x8*)(lds + PG8_SA(b, h) + aoff + m * 2048 + k * 1024); } while (0)
; #define PG8_LDB(dst, b, h) do { _Pragma("unroll") for (int n = 0; n < 2; ++n) _Pragma("unroll") for (int k = 0; k < 2; ++k) dst[n][k] = *(const LAS bf16x8*)(lds + PG8_SB(b, h) + boff + n * 2048 + k * 1024); } while (0)
; #define PG8_MMA(ai, bj, At, Bt) do { __builtin_amdgcn_s_setprio(1); _Pragma("unroll") for (int m = 0; m < 4; ++m) _Pragma("unroll") for (int n = 0; n < 2; ++n) _Pragma("unroll") for (int k = 0; k < 2; ++k) \
;         acc[ai][bj][m][n] = __builtin_amdgcn_mfma_f32_16x16x32_bf16(Bt[n][k], At[m][k], acc[ai][bj][m][n], 0, 0, 0); __builtin_amdgcn_s_setprio(0); } while (0)
; #define PG8_WAIT_V(n) asm volatile("s_waitcnt vmcnt(" #n ")" ::: "memory")
; #define PG8_WAIT_L(n) asm volatile("s_waitcnt lgkmcnt(" #n ")" ::: "memory")
; #define PG8_BAR __builtin_amdgcn_s_barrier()
; #define PG8_SCHED __builtin_amdgcn_sched_barrier(0)
; template <class Epi>
; DI void gemm_phase(int wv, LAS unsigned char* lds, LAS unsigned char* scr, const Sched& S, const Epi& E) {
;     ...
;             PG8_LDB(B0, 0, 0); PG8_LDB(B1, 0, 1); PG8_SCHED; PG8_LDA(At, 0, 0); PG8_STAGE(PG8_SA(1, 1), a1 + hstepA, voffA);
;             PG8_WAIT_V(8); PG8_WAIT_L(0); PG8_BAR; PG8_MMA(0, 0, At, B0); PG8_MMA(0, 1, At, B1); PG8_BAR; PG8_SCHED;
;             PG8_LDA(At, 0, 1); PG8_STAGE(PG8_SB(0, 0), b2, voffB); PG8_STAGE(PG8_SB(0, 1), b2 + hstepB, voffB); PG8_STAGE(PG8_SA(0, 0), a2, voffA);
;             PG8_WAIT_V(8); PG8_WAIT_L(0); PG8_BAR; PG8_MMA(1, 0, At, B0); PG8_MMA(1, 1, At, B1); PG8_BAR; PG8_SCHED;
.LBB0_113:
	s_add_u32 s46, s44, 0xfffc0080
	s_addc_u32 s47, s45, -1
	s_add_i32 s75, 0, 0x10000
	s_cmp_eq_u32 s74, 12
	s_cselect_b32 s49, s29, s47
	s_cselect_b32 s48, s31, s46
	s_cselect_b32 s47, s35, s73
	s_cselect_b32 s46, s37, s72
	s_add_i32 s78, 0, 0x14000
	v_add_u32_e32 v156, s75, v142
	v_add_u32_e32 v172, s78, v142
	ds_read_b128 v[144:147], v156
	ds_read_b128 v[148:151], v156 offset:1024
	ds_read_b128 v[152:155], v156 offset:2048
	ds_read_b128 v[156:159], v156 offset:3072
	ds_read_b128 v[160:163], v172
	ds_read_b128 v[164:167], v172 offset:1024
	ds_read_b128 v[168:171], v172 offset:2048
	ds_read_b128 v[172:175], v172 offset:3072
	v_lshl_add_u64 v[210:211], s[44:45], 0, v[140:141]
	s_add_i32 m0, s62, 0xc000
	ds_read_b128 v[176:179], v143
	ds_read_b128 v[180:183], v143 offset:1024
	ds_read_b128 v[184:187], v143 offset:2048
	ds_read_b128 v[188:191], v143 offset:3072
	ds_read_b128 v[194:197], v143 offset:4096
	ds_read_b128 v[198:201], v143 offset:5120
	ds_read_b128 v[202:205], v143 offset:6144
	ds_read_b128 v[206:209], v143 offset:7168
	global_load_lds_dwordx4 v[210:211], off
	v_lshl_add_u64 v[210:211], s[44:45], 0, v[138:139]
	s_add_i32 m0, s62, 0xe000
	s_nop 0
	global_load_lds_dwordx4 v[210:211], off
	s_waitcnt vmcnt(8)
	s_waitcnt lgkmcnt(0)
	s_barrier
	v_mfma_f32_16x16x32_bf16 v[124:127], v[144:147], v[176:179], v[124:127]
	v_mfma_f32_16x16x32_bf16 v[120:123], v[152:155], v[176:179], v[120:123]
	v_mfma_f32_16x16x32_bf16 v[116:119], v[144:147], v[184:187], v[116:119]
	v_mfma_f32_16x16x32_bf16 v[112:115], v[152:155], v[184:187], v[112:115]
	v_mfma_f32_16x16x32_bf16 v[100:103], v[144:147], v[194:197], v[100:103]
	v_mfma_f32_16x16x32_bf16 v[96:99], v[152:155], v[194:197], v[96:99]
	v_mfma_f32_16x16x32_bf16 v[84:87], v[144:147], v[202:205], v[84:87]
	v_mfma_f32_16x16x32_bf16 v[80:83], v[152:155], v[202:205], v[80:83]
	v_mfma_f32_16x16x32_bf16 v[124:127], v[148:151], v[180:183], v[124:127]
	v_mfma_f32_16x16x32_bf16 v[120:123], v[156:159], v[180:183], v[120:123]
	v_mfma_f32_16x16x32_bf16 v[116:119], v[148:151], v[188:191], v[116:119]
	v_mfma_f32_16x16x32_bf16 v[112:115], v[156:159], v[188:191], v[112:115]
	v_mfma_f32_16x16x32_bf16 v[100:103], v[148:151], v[198:201], v[100:103]
	v_mfma_f32_16x16x32_bf16 v[96:99], v[156:159], v[198:201], v[96:99]
	v_mfma_f32_16x16x32_bf16 v[84:87], v[148:151], v[206:209], v[84:87]
	v_mfma_f32_16x16x32_bf16 v[80:83], v[156:159], v[206:209], v[80:83]
	v_mfma_f32_16x16x32_bf16 v[108:111], v[160:163], v[176:179], v[108:111]
	v_mfma_f32_16x16x32_bf16 v[104:107], v[168:171], v[176:179], v[104:107]
	v_mfma_f32_16x16x32_bf16 v[92:95], v[160:163], v[184:187], v[92:95]
	v_mfma_f32_16x16x32_bf16 v[88:91], v[168:171], v[184:187], v[88:91]
	v_mfma_f32_16x16x32_bf16 v[76:79], v[160:163], v[194:197], v[76:79]
	v_mfma_f32_16x16x32_bf16 v[72:75], v[168:171], v[194:197], v[72:75]
	v_mfma_f32_16x16x32_bf16 v[68:71], v[160:163], v[202:205], v[68:71]
	v_mfma_f32_16x16x32_bf16 v[64:67], v[168:171], v[202:205], v[64:67]
	v_mfma_f32_16x16x32_bf16 v[108:111], v[164:167], v[180:183], v[108:111]
	v_mfma_f32_16x16x32_bf16 v[104:107], v[172:175], v[180:183], v[104:107]
	v_mfma_f32_16x16x32_bf16 v[92:95], v[164:167], v[188:191], v[92:95]
	v_mfma_f32_16x16x32_bf16 v[88:91], v[172:175], v[188:191], v[88:91]
	v_mfma_f32_16x16x32_bf16 v[76:79], v[164:167], v[198:201], v[76:79]
	v_mfma_f32_16x16x32_bf16 v[72:75], v[172:175], v[198:201], v[72:75]
	v_mfma_f32_16x16x32_bf16 v[68:71], v[164:167], v[206:209], v[68:71]
	v_mfma_f32_16x16x32_bf16 v[64:67], v[172:175], v[206:209], v[64:67]
	s_barrier
	s_add_i32 s75, s75, s60
	v_lshl_add_u64 v[210:211], s[46:47], 0, v[130:131]
	s_mov_b32 m0, s75
	ds_read_b128 v[176:179], v143 offset:16384
	ds_read_b128 v[180:183], v143 offset:17408
	ds_read_b128 v[184:187], v143 offset:18432
	ds_read_b128 v[188:191], v143 offset:19456
	ds_read_b128 v[194:197], v143 offset:20480
	ds_read_b128 v[198:201], v143 offset:21504
	ds_read_b128 v[202:205], v143 offset:22528
	ds_read_b128 v[206:209], v143 offset:23552
	global_load_lds_dwordx4 v[210:211], off
	s_add_i32 m0, s75, 0x2000
	s_add_u32 s76, s46, 0x40000
	v_lshl_add_u64 v[212:213], s[46:47], 0, v[134:135]
	s_addc_u32 s77, s47, 0
	s_add_i32 s75, s78, s60
	global_load_lds_dwordx4 v[212:213], off
	v_lshl_add_u64 v[214:215], s[76:77], 0, v[130:131]
	s_mov_b32 m0, s75
	v_lshl_add_u64 v[216:217], s[48:49], 0, v[132:133]
	global_load_lds_dwordx4 v[214:215], off
	v_lshl_add_u64 v[214:215], s[76:77], 0, v[134:135]
	s_add_i32 m0, s75, 0x2000
	s_nop 0
	global_load_lds_dwordx4 v[214:215], off
	v_lshl_add_u64 v[214:215], s[48:49], 0, v[128:129]
	s_mov_b32 m0, s62
	s_nop 0
	global_load_lds_dwordx4 v[214:215], off
	s_mov_b32 m0, s63
	s_nop 0
	global_load_lds_dwordx4 v[216:217], off
	s_waitcnt vmcnt(8)
	s_waitcnt lgkmcnt(0)
	s_barrier
; #define PG8_STAGE(bufoff, gbase, voff) do { _Pragma("unroll") for (int _i = 0; _i < 2; ++_i) \
;         __builtin_amdgcn_global_load_lds((const unsigned*)((const char*)(gbase) + (voff)[_i]), (LAS unsigned*)(lds + (bufoff) + ldsw + _i * 8192), 16, 0, 0); } while (0)
; #define PG8_LDA(dst, b, h) do { _Pragma("unroll") for (int m = 0; m < 4; ++m) _Pragma("unroll") for (int k = 0; k < 2; ++k) dst[m][k] = *(const LAS bf16x8*)(lds + PG8_SA(b, h) + aoff + m * 2048 + k * 1024); } while (0)
; #define PG8_LDB(dst, b, h) do { _Pragma("unroll") for (int n = 0; n < 2; ++n) _Pragma("unroll") for (int k = 0; k < 2; ++k) dst[n][k] = *(const LAS bf16x8*)(lds + PG8_SB(b, h) + boff + n * 2048 + k * 1024); } while (0)
; #define PG8_MMA(ai, bj, At, Bt) do { __builtin_amdgcn_s_setprio(1); _Pragma("unroll") for (int m = 0; m < 4; ++m) _Pragma("unroll") for (int n = 0; n < 2; ++n) _Pragma("unroll") for (int k = 0; k < 2; ++k) \
;         acc[ai][bj][m][n] = __builtin_amdgcn_mfma_f32_16x16x32_bf16(Bt[n][k], At[m][k], acc[ai][bj][m][n], 0, 0, 0); __builtin_amdgcn_s_setprio(0); } while (0)
; #define PG8_WAIT_V(n) asm volatile("s_waitcnt vmcnt(" #n ")" ::: "memory")
; #define PG8_WAIT_L(n) asm volatile("s_waitcnt lgkmcnt(" #n ")" ::: "memory")
; #define PG8_BAR __builtin_amdgcn_s_barrier()
; #define PG8_SCHED __builtin_amdgcn_sched_barrier(0)
; template <class Epi>
; DI void gemm_phase(int wv, LAS unsigned char* lds, LAS unsigned char* scr, const Sched& S, const Epi& E) {
;     ...
;             PG8_WAIT_V(8); PG8_WAIT_L(0); PG8_BAR; PG8_MMA(1, 0, At, B0); PG8_MMA(1, 1, At, B1); PG8_BAR; PG8_SCHED;
;             PG8_LDB(B0, 1, 0); PG8_LDB(B1, 1, 1); PG8_SCHED; PG8_LDA(At, 1, 0); PG8_STAGE(PG8_SA(0, 1), a2 + hstepA, voffA);
;             PG8_WAIT_V(8); PG8_WAIT_L(0); PG8_BAR; PG8_MMA(0, 0, At, B0); PG8_MMA(0, 1, At, B1); PG8_BAR; PG8_SCHED;
	v_mfma_f32_16x16x32_bf16 v[60:63], v[144:147], v[176:179], v[60:63]
	v_mfma_f32_16x16x32_bf16 v[56:59], v[152:155], v[176:179], v[56:59]
	v_mfma_f32_16x16x32_bf16 v[52:55], v[144:147], v[184:187], v[52:55]
	v_mfma_f32_16x16x32_bf16 v[48:51], v[152:155], v[184:187], v[48:51]
	v_mfma_f32_16x16x32_bf16 v[36:39], v[144:147], v[194:197], v[36:39]
	v_mfma_f32_16x16x32_bf16 v[32:35], v[152:155], v[194:197], v[32:35]
	v_mfma_f32_16x16x32_bf16 v[20:23], v[144:147], v[202:205], v[20:23]
	v_mfma_f32_16x16x32_bf16 v[16:19], v[152:155], v[202:205], v[16:19]
	v_mfma_f32_16x16x32_bf16 v[60:63], v[148:151], v[180:183], v[60:63]
	v_mfma_f32_16x16x32_bf16 v[56:59], v[156:159], v[180:183], v[56:59]
	v_mfma_f32_16x16x32_bf16 v[52:55], v[148:151], v[188:191], v[52:55]
	v_mfma_f32_16x16x32_bf16 v[48:51], v[156:159], v[188:191], v[48:51]
	v_mfma_f32_16x16x32_bf16 v[36:39], v[148:151], v[198:201], v[36:39]
	v_mfma_f32_16x16x32_bf16 v[32:35], v[156:159], v[198:201], v[32:35]
	v_mfma_f32_16x16x32_bf16 v[20:23], v[148:151], v[206:209], v[20:23]
	v_mfma_f32_16x16x32_bf16 v[16:19], v[156:159], v[206:209], v[16:19]
	v_mfma_f32_16x16x32_bf16 v[44:47], v[160:163], v[176:179], v[44:47]
	v_mfma_f32_16x16x32_bf16 v[40:43], v[168:171], v[176:179], v[40:43]
	v_mfma_f32_16x16x32_bf16 v[28:31], v[160:163], v[184:187], v[28:31]
	v_mfma_f32_16x16x32_bf16 v[24:27], v[168:171], v[184:187], v[24:27]
	v_mfma_f32_16x16x32_bf16 v[12:15], v[160:163], v[194:197], v[12:15]
	v_mfma_f32_16x16x32_bf16 v[8:11], v[168:171], v[194:197], v[8:11]
	v_mfma_f32_16x16x32_bf16 v[4:7], v[160:163], v[202:205], v[4:7]
	v_mfma_f32_16x16x32_bf16 v[0:3], v[168:171], v[202:205], v[0:3]
	v_mfma_f32_16x16x32_bf16 v[44:47], v[164:167], v[180:183], v[44:47]
	v_mfma_f32_16x16x32_bf16 v[40:43], v[172:175], v[180:183], v[40:43]
	v_mfma_f32_16x16x32_bf16 v[28:31], v[164:167], v[188:191], v[28:31]
	v_mfma_f32_16x16x32_bf16 v[24:27], v[172:175], v[188:191], v[24:27]
	v_mfma_f32_16x16x32_bf16 v[12:15], v[164:167], v[198:201], v[12:15]
	v_mfma_f32_16x16x32_bf16 v[8:11], v[172:175], v[198:201], v[8:11]
	v_mfma_f32_16x16x32_bf16 v[4:7], v[164:167], v[206:209], v[4:7]
	v_mfma_f32_16x16x32_bf16 v[0:3], v[172:175], v[206:209], v[0:3]
	s_barrier
	s_add_i32 s75, 0, 0x18000
	s_add_i32 s76, 0, 0x1c000
	v_add_u32_e32 v156, s75, v142
	v_add_u32_e32 v172, s76, v142
	ds_read_b128 v[144:147], v156
	ds_read_b128 v[148:151], v156 offset:1024
	ds_read_b128 v[152:155], v156 offset:2048
	ds_read_b128 v[156:159], v156 offset:3072
	ds_read_b128 v[160:163], v172
	ds_read_b128 v[164:167], v172 offset:1024
	ds_read_b128 v[168:171], v172 offset:2048
	ds_read_b128 v[172:175], v172 offset:3072
	s_add_u32 s48, s48, 0x40000
	s_addc_u32 s49, s49, 0
	s_mov_b32 m0, s64
	v_lshl_add_u64 v[218:219], s[48:49], 0, v[128:129]
	ds_read_b128 v[176:179], v143 offset:32768
	ds_read_b128 v[180:183], v143 offset:33792
	ds_read_b128 v[184:187], v143 offset:34816
	ds_read_b128 v[188:191], v143 offset:35840
	ds_read_b128 v[194:197], v143 offset:36864
	ds_read_b128 v[198:201], v143 offset:37888
	ds_read_b128 v[202:205], v143 offset:38912
	ds_read_b128 v[206:209], v143 offset:39936
	global_load_lds_dwordx4 v[218:219], off
	v_lshl_add_u64 v[218:219], s[48:49], 0, v[132:133]
	s_mov_b32 m0, s65
	s_nop 0
	global_load_lds_dwordx4 v[218:219], off
	s_waitcnt vmcnt(8)
	s_waitcnt lgkmcnt(0)
	s_barrier
	v_mfma_f32_16x16x32_bf16 v[124:127], v[144:147], v[176:179], v[124:127]
	v_mfma_f32_16x16x32_bf16 v[120:123], v[152:155], v[176:179], v[120:123]
	v_mfma_f32_16x16x32_bf16 v[116:119], v[144:147], v[184:187], v[116:119]
	v_mfma_f32_16x16x32_bf16 v[112:115], v[152:155], v[184:187], v[112:115]
	v_mfma_f32_16x16x32_bf16 v[100:103], v[144:147], v[194:197], v[100:103]
	v_mfma_f32_16x16x32_bf16 v[96:99], v[152:155], v[194:197], v[96:99]
	v_mfma_f32_16x16x32_bf16 v[84:87], v[144:147], v[202:205], v[84:87]
	v_mfma_f32_16x16x32_bf16 v[80:83], v[152:155], v[202:205], v[80:83]
	v_mfma_f32_16x16x32_bf16 v[124:127], v[148:151], v[180:183], v[124:127]
	v_mfma_f32_16x16x32_bf16 v[120:123], v[156:159], v[180:183], v[120:123]
	v_mfma_f32_16x16x32_bf16 v[116:119], v[148:151], v[188:191], v[116:119]
	v_mfma_f32_16x16x32_bf16 v[112:115], v[156:159], v[188:191], v[112:115]
	v_mfma_f32_16x16x32_bf16 v[100:103], v[148:151], v[198:201], v[100:103]
	v_mfma_f32_16x16x32_bf16 v[96:99], v[156:159], v[198:201], v[96:99]
	v_mfma_f32_16x16x32_bf16 v[84:87], v[148:151], v[206:209], v[84:87]
	v_mfma_f32_16x16x32_bf16 v[80:83], v[156:159], v[206:209], v[80:83]
	v_mfma_f32_16x16x32_bf16 v[108:111], v[160:163], v[176:179], v[108:111]
	v_mfma_f32_16x16x32_bf16 v[104:107], v[168:171], v[176:179], v[104:107]
	v_mfma_f32_16x16x32_bf16 v[92:95], v[160:163], v[184:187], v[92:95]
	v_mfma_f32_16x16x32_bf16 v[88:91], v[168:171], v[184:187], v[88:91]
	v_mfma_f32_16x16x32_bf16 v[76:79], v[160:163], v[194:197], v[76:79]
	v_mfma_f32_16x16x32_bf16 v[72:75], v[168:171], v[194:197], v[72:75]
	v_mfma_f32_16x16x32_bf16 v[68:71], v[160:163], v[202:205], v[68:71]
	v_mfma_f32_16x16x32_bf16 v[64:67], v[168:171], v[202:205], v[64:67]
	v_mfma_f32_16x16x32_bf16 v[108:111], v[164:167], v[180:183], v[108:111]
	v_mfma_f32_16x16x32_bf16 v[104:107], v[172:175], v[180:183], v[104:107]
	v_mfma_f32_16x16x32_bf16 v[92:95], v[164:167], v[188:191], v[92:95]
	v_mfma_f32_16x16x32_bf16 v[88:91], v[172:175], v[188:191], v[88:91]
	v_mfma_f32_16x16x32_bf16 v[76:79], v[164:167], v[198:201], v[76:79]
	v_mfma_f32_16x16x32_bf16 v[72:75], v[172:175], v[198:201], v[72:75]
	v_mfma_f32_16x16x32_bf16 v[68:71], v[164:167], v[206:209], v[68:71]
	v_mfma_f32_16x16x32_bf16 v[64:67], v[172:175], v[206:209], v[64:67]
	s_barrier
; #define PG8_STAGE(bufoff, gbase, voff) do { _Pragma("unroll") for (int _i = 0; _i < 2; ++_i) \
;         __builtin_amdgcn_global_load_lds((const unsigned*)((const char*)(gbase) + (voff)[_i]), (LAS unsigned*)(lds + (bufoff) + ldsw + _i * 8192), 16, 0, 0); } while (0)
; #define PG8_LDA(dst, b, h) do { _Pragma("unroll") for (int m = 0; m < 4; ++m) _Pragma("unroll") for (int k = 0; k < 2; ++k) dst[m][k] = *(const LAS bf16x8*)(lds + PG8_SA(b, h) + aoff + m * 2048 + k * 1024); } while (0)
; #define PG8_MMA(ai, bj, At, Bt) do { __builtin_amdgcn_s_setprio(1); _Pragma("unroll") for (int m = 0; m < 4; ++m) _Pragma("unroll") for (int n = 0; n < 2; ++n) _Pragma("unroll") for (int k = 0; k < 2; ++k) \
;         acc[ai][bj][m][n] = __builtin_amdgcn_mfma_f32_16x16x32_bf16(Bt[n][k], At[m][k], acc[ai][bj][m][n], 0, 0, 0); __builtin_amdgcn_s_setprio(0); } while (0)
; #define PG8_WAIT_V(n) asm volatile("s_waitcnt vmcnt(" #n ")" ::: "memory")
; #define PG8_WAIT_L(n) asm volatile("s_waitcnt lgkmcnt(" #n ")" ::: "memory")
; #define PG8_BAR __builtin_amdgcn_s_barrier()
; #define PG8_SCHED __builtin_amdgcn_sched_barrier(0)
; template <class Epi>
; DI void gemm_phase(int wv, LAS unsigned char* lds, LAS unsigned char* scr, const Sched& S, const Epi& E) {
;     ...
;             PG8_LDA(At, 1, 1); PG8_STAGE(PG8_SB(1, 0), b3, voffB); PG8_STAGE(PG8_SB(1, 1), b3 + hstepB, voffB); PG8_STAGE(PG8_SA(1, 0), a3, voffA);
;             PG8_WAIT_V(8); PG8_WAIT_L(0); PG8_BAR; PG8_MMA(1, 0, At, B0); PG8_MMA(1, 1, At, B1); PG8_BAR; PG8_SCHED;
;         }
;         if (wr == 0) PG8_BAR;
	s_add_i32 s48, s75, s60
	v_lshl_add_u64 v[210:211], v[210:211], 0, s[2:3]
	s_mov_b32 m0, s48
	ds_read_b128 v[176:179], v143 offset:49152
	ds_read_b128 v[180:183], v143 offset:50176
	ds_read_b128 v[184:187], v143 offset:51200
	ds_read_b128 v[188:191], v143 offset:52224
	ds_read_b128 v[194:197], v143 offset:53248
	ds_read_b128 v[198:201], v143 offset:54272
	ds_read_b128 v[202:205], v143 offset:55296
	ds_read_b128 v[206:209], v143 offset:56320
	global_load_lds_dwordx4 v[210:211], off
	s_add_i32 m0, s48, 0x2000
	s_add_u32 s46, s46, 0x40080
	v_lshl_add_u64 v[210:211], v[212:213], 0, s[2:3]
	s_addc_u32 s47, s47, 0
	s_add_i32 s48, s76, s60
	global_load_lds_dwordx4 v[210:211], off
	v_lshl_add_u64 v[210:211], s[46:47], 0, v[130:131]
	s_mov_b32 m0, s48
	s_nop 0
	global_load_lds_dwordx4 v[210:211], off
	v_lshl_add_u64 v[210:211], s[46:47], 0, v[134:135]
	s_add_i32 m0, s48, 0x2000
	s_nop 0
	global_load_lds_dwordx4 v[210:211], off
	v_lshl_add_u64 v[210:211], v[214:215], 0, s[2:3]
	s_mov_b32 m0, s66
	s_nop 0
	global_load_lds_dwordx4 v[210:211], off
	v_lshl_add_u64 v[210:211], v[216:217], 0, s[2:3]
	s_mov_b32 m0, s67
	s_nop 0
	global_load_lds_dwordx4 v[210:211], off
	s_waitcnt vmcnt(8)
	s_waitcnt lgkmcnt(0)
	s_barrier
	v_mfma_f32_16x16x32_bf16 v[60:63], v[144:147], v[176:179], v[60:63]
	v_mfma_f32_16x16x32_bf16 v[56:59], v[152:155], v[176:179], v[56:59]
	v_mfma_f32_16x16x32_bf16 v[52:55], v[144:147], v[184:187], v[52:55]
	v_mfma_f32_16x16x32_bf16 v[48:51], v[152:155], v[184:187], v[48:51]
	v_mfma_f32_16x16x32_bf16 v[36:39], v[144:147], v[194:197], v[36:39]
	v_mfma_f32_16x16x32_bf16 v[32:35], v[152:155], v[194:197], v[32:35]
	v_mfma_f32_16x16x32_bf16 v[20:23], v[144:147], v[202:205], v[20:23]
	v_mfma_f32_16x16x32_bf16 v[16:19], v[152:155], v[202:205], v[16:19]
	v_mfma_f32_16x16x32_bf16 v[60:63], v[148:151], v[180:183], v[60:63]
	v_mfma_f32_16x16x32_bf16 v[56:59], v[156:159], v[180:183], v[56:59]
	v_mfma_f32_16x16x32_bf16 v[52:55], v[148:151], v[188:191], v[52:55]
	v_mfma_f32_16x16x32_bf16 v[48:51], v[156:159], v[188:191], v[48:51]
	v_mfma_f32_16x16x32_bf16 v[36:39], v[148:151], v[198:201], v[36:39]
	v_mfma_f32_16x16x32_bf16 v[32:35], v[156:159], v[198:201], v[32:35]
	v_mfma_f32_16x16x32_bf16 v[20:23], v[148:151], v[206:209], v[20:23]
	v_mfma_f32_16x16x32_bf16 v[16:19], v[156:159], v[206:209], v[16:19]
	v_mfma_f32_16x16x32_bf16 v[44:47], v[160:163], v[176:179], v[44:47]
	v_mfma_f32_16x16x32_bf16 v[40:43], v[168:171], v[176:179], v[40:43]
	v_mfma_f32_16x16x32_bf16 v[28:31], v[160:163], v[184:187], v[28:31]
	v_mfma_f32_16x16x32_bf16 v[24:27], v[168:171], v[184:187], v[24:27]
	v_mfma_f32_16x16x32_bf16 v[12:15], v[160:163], v[194:197], v[12:15]
	v_mfma_f32_16x16x32_bf16 v[8:11], v[168:171], v[194:197], v[8:11]
	v_mfma_f32_16x16x32_bf16 v[4:7], v[160:163], v[202:205], v[4:7]
	v_mfma_f32_16x16x32_bf16 v[0:3], v[168:171], v[202:205], v[0:3]
	v_mfma_f32_16x16x32_bf16 v[44:47], v[164:167], v[180:183], v[44:47]
	v_mfma_f32_16x16x32_bf16 v[40:43], v[172:175], v[180:183], v[40:43]
	v_mfma_f32_16x16x32_bf16 v[28:31], v[164:167], v[188:191], v[28:31]
	v_mfma_f32_16x16x32_bf16 v[24:27], v[172:175], v[188:191], v[24:27]
	v_mfma_f32_16x16x32_bf16 v[12:15], v[164:167], v[198:201], v[12:15]
	v_mfma_f32_16x16x32_bf16 v[8:11], v[172:175], v[198:201], v[8:11]
	v_mfma_f32_16x16x32_bf16 v[4:7], v[164:167], v[206:209], v[4:7]
	v_mfma_f32_16x16x32_bf16 v[0:3], v[172:175], v[206:209], v[0:3]
	s_barrier
	s_add_i32 s74, s74, 2
	s_add_u32 s72, s72, 0x100
	s_addc_u32 s73, s73, 0
	s_add_u32 s44, s44, 0x100
	s_addc_u32 s45, s45, 0
	s_cmp_gt_u32 s74, 13
	s_cbranch_scc0 .LBB0_113
	s_and_b64 vcc, exec, s[14:15]
	s_movk_i32 s74, 0x4000
	s_mov_b64 s[72:73], s[92:93]
	s_cbranch_vccz .LBB0_116
	s_barrier

; #define PG8_STAGE(bufoff, gbase, voff) do { _Pragma("unroll") for (int _i = 0; _i < 2; ++_i) \
;         __builtin_amdgcn_global_load_lds((const unsigned*)((const char*)(gbase) + (voff)[_i]), (LAS unsigned*)(lds + (bufoff) + ldsw + _i * 8192), 16, 0, 0); } while (0)
; #define PG8_LDA(dst, b, h) do { _Pragma("unroll") for (int m = 0; m < 4; ++m) _Pragma("unroll") for (int k = 0; k < 2; ++k) dst[m][k] = *(const LAS bf16x8*)(lds + PG8_SA(b, h) + aoff + m * 2048 + k * 1024); } while (0)
; #define PG8_LDB(dst, b, h) do { _Pragma("unroll") for (int n = 0; n < 2; ++n) _Pragma("unroll") for (int k = 0; k < 2; ++k) dst[n][k] = *(const LAS bf16x8*)(lds + PG8_SB(b, h) + boff + n * 2048 + k * 1024); } while (0)
; #define PG8_MMA(ai, bj, At, Bt) do { __builtin_amdgcn_s_setprio(1); _Pragma("unroll") for (int m = 0; m < 4; ++m) _Pragma("unroll") for (int n = 0; n < 2; ++n) _Pragma("unroll") for (int k = 0; k < 2; ++k) \
;         acc[ai][bj][m][n] = __builtin_amdgcn_mfma_f32_16x16x32_bf16(Bt[n][k], At[m][k], acc[ai][bj][m][n], 0, 0, 0); __builtin_amdgcn_s_setprio(0); } while (0)
; #define PG8_WAIT_V(n) asm volatile("s_waitcnt vmcnt(" #n ")" ::: "memory")
; #define PG8_WAIT_L(n) asm volatile("s_waitcnt lgkmcnt(" #n ")" ::: "memory")
; #define PG8_BAR __builtin_amdgcn_s_barrier()
; #define PG8_SCHED __builtin_amdgcn_sched_barrier(0)
; template <class Epi>
; DI void gemm_phase(int wv, LAS unsigned char* lds, LAS unsigned char* scr, const Sched& S, const Epi& E) {
;     ...
;             const bool last = (t == nt - 2);
;             const char* a1 = cA + (size_t)(t + 1) * kstep;
;             const char* a2 = last ? nA : cA + (size_t)(t + 2) * kstep; const char* b2 = last ? nB : cB + (size_t)(t + 2) * kstep;
;             const char* a3 = a2 + kstep; const char* b3 = b2 + kstep;
;             PG8_LDB(B0, 0, 0); PG8_LDB(B1, 0, 1); PG8_SCHED; PG8_LDA(At, 0, 0); PG8_STAGE(PG8_SA(1, 1), a1 + hstepA, voffA);
;             PG8_WAIT_V(8); PG8_WAIT_L(0); PG8_BAR; PG8_MMA(0, 0, At, B0); PG8_MMA(0, 1, At, B1); PG8_BAR; PG8_SCHED;
;             PG8_LDA(At, 0, 1); PG8_STAGE(PG8_SB(0, 0), b2, voffB); PG8_STAGE(PG8_SB(0, 1), b2 + hstepB, voffB); PG8_STAGE(PG8_SA(0, 0), a2, voffA);
.LBB0_137:
	s_add_u32 s34, s30, 0xfffc0080
	s_addc_u32 s35, s31, -1
	s_add_i32 s65, 0, 0x10000
	s_cmp_eq_u32 s64, 12
	s_cselect_b32 s37, s25, s35
	s_cselect_b32 s36, s60, s34
	v_add_u32_e32 v143, s65, v140
	s_cselect_b32 s35, s23, s63
	s_cselect_b32 s34, s61, s62
	s_add_i32 s68, 0, 0x14000
	ds_read_b128 v[144:147], v143
	ds_read_b128 v[148:151], v143 offset:1024
	ds_read_b128 v[152:155], v143 offset:2048
	ds_read_b128 v[156:159], v143 offset:3072
	v_add_u32_e32 v143, s68, v140
	ds_read_b128 v[160:163], v143
	ds_read_b128 v[164:167], v143 offset:1024
	ds_read_b128 v[168:171], v143 offset:2048
	ds_read_b128 v[172:175], v143 offset:3072
	v_lshl_add_u64 v[210:211], s[30:31], 0, v[138:139]
	s_add_i32 m0, s17, 0xc000
	ds_read_b128 v[176:179], v142
	ds_read_b128 v[180:183], v142 offset:1024
	ds_read_b128 v[184:187], v142 offset:2048
	ds_read_b128 v[188:191], v142 offset:3072
	ds_read_b128 v[194:197], v142 offset:4096
	ds_read_b128 v[198:201], v142 offset:5120
	ds_read_b128 v[202:205], v142 offset:6144
	ds_read_b128 v[206:209], v142 offset:7168
	global_load_lds_dwordx4 v[210:211], off
	v_lshl_add_u64 v[210:211], s[30:31], 0, v[136:137]
	s_add_i32 m0, s17, 0xe000
	s_nop 0
	global_load_lds_dwordx4 v[210:211], off
	s_waitcnt vmcnt(8)
	s_waitcnt lgkmcnt(0)
	s_barrier
	v_mfma_f32_16x16x32_bf16 v[124:127], v[144:147], v[176:179], v[124:127]
	v_mfma_f32_16x16x32_bf16 v[120:123], v[152:155], v[176:179], v[120:123]
	v_mfma_f32_16x16x32_bf16 v[116:119], v[144:147], v[184:187], v[116:119]
	v_mfma_f32_16x16x32_bf16 v[112:115], v[152:155], v[184:187], v[112:115]
	v_mfma_f32_16x16x32_bf16 v[100:103], v[144:147], v[194:197], v[100:103]
	v_mfma_f32_16x16x32_bf16 v[96:99], v[152:155], v[194:197], v[96:99]
	v_mfma_f32_16x16x32_bf16 v[84:87], v[144:147], v[202:205], v[84:87]
	v_mfma_f32_16x16x32_bf16 v[80:83], v[152:155], v[202:205], v[80:83]
	v_mfma_f32_16x16x32_bf16 v[124:127], v[148:151], v[180:183], v[124:127]
	v_mfma_f32_16x16x32_bf16 v[120:123], v[156:159], v[180:183], v[120:123]
	v_mfma_f32_16x16x32_bf16 v[116:119], v[148:151], v[188:191], v[116:119]
	v_mfma_f32_16x16x32_bf16 v[112:115], v[156:159], v[188:191], v[112:115]
	v_mfma_f32_16x16x32_bf16 v[100:103], v[148:151], v[198:201], v[100:103]
	v_mfma_f32_16x16x32_bf16 v[96:99], v[156:159], v[198:201], v[96:99]
	v_mfma_f32_16x16x32_bf16 v[84:87], v[148:151], v[206:209], v[84:87]
	v_mfma_f32_16x16x32_bf16 v[80:83], v[156:159], v[206:209], v[80:83]
	v_mfma_f32_16x16x32_bf16 v[108:111], v[160:163], v[176:179], v[108:111]
	v_mfma_f32_16x16x32_bf16 v[104:107], v[168:171], v[176:179], v[104:107]
	v_mfma_f32_16x16x32_bf16 v[92:95], v[160:163], v[184:187], v[92:95]
	v_mfma_f32_16x16x32_bf16 v[88:91], v[168:171], v[184:187], v[88:91]
	v_mfma_f32_16x16x32_bf16 v[76:79], v[160:163], v[194:197], v[76:79]
	v_mfma_f32_16x16x32_bf16 v[72:75], v[168:171], v[194:197], v[72:75]
	v_mfma_f32_16x16x32_bf16 v[68:71], v[160:163], v[202:205], v[68:71]
	v_mfma_f32_16x16x32_bf16 v[64:67], v[168:171], v[202:205], v[64:67]
	v_mfma_f32_16x16x32_bf16 v[108:111], v[164:167], v[180:183], v[108:111]
	v_mfma_f32_16x16x32_bf16 v[104:107], v[172:175], v[180:183], v[104:107]
	v_mfma_f32_16x16x32_bf16 v[92:95], v[164:167], v[188:191], v[92:95]
	v_mfma_f32_16x16x32_bf16 v[88:91], v[172:175], v[188:191], v[88:91]
	v_mfma_f32_16x16x32_bf16 v[76:79], v[164:167], v[198:201], v[76:79]
	v_mfma_f32_16x16x32_bf16 v[72:75], v[172:175], v[198:201], v[72:75]
	v_mfma_f32_16x16x32_bf16 v[68:71], v[164:167], v[206:209], v[68:71]
	v_mfma_f32_16x16x32_bf16 v[64:67], v[172:175], v[206:209], v[64:67]
	s_barrier
	s_add_i32 s65, s65, s39
	v_lshl_add_u64 v[210:211], s[34:35], 0, v[192:193]
	s_mov_b32 m0, s65
	ds_read_b128 v[176:179], v142 offset:16384
	ds_read_b128 v[180:183], v142 offset:17408
	ds_read_b128 v[184:187], v142 offset:18432
	ds_read_b128 v[188:191], v142 offset:19456
	ds_read_b128 v[194:197], v142 offset:20480
	ds_read_b128 v[198:201], v142 offset:21504
	ds_read_b128 v[202:205], v142 offset:22528
	ds_read_b128 v[206:209], v142 offset:23552
	global_load_lds_dwordx4 v[210:211], off
	s_add_i32 m0, s65, 0x2000
	s_add_u32 s66, s34, 0x40000
	v_lshl_add_u64 v[212:213], s[34:35], 0, v[132:133]
	s_addc_u32 s67, s35, 0
	s_add_i32 s65, s68, s39
	global_load_lds_dwordx4 v[212:213], off
	v_lshl_add_u64 v[214:215], s[66:67], 0, v[192:193]
	s_mov_b32 m0, s65
	v_lshl_add_u64 v[216:217], s[36:37], 0, v[130:131]
	global_load_lds_dwordx4 v[214:215], off
	v_lshl_add_u64 v[214:215], s[66:67], 0, v[132:133]
	s_add_i32 m0, s65, 0x2000
	s_nop 0
	global_load_lds_dwordx4 v[214:215], off
	v_lshl_add_u64 v[214:215], s[36:37], 0, v[128:129]
	s_mov_b32 m0, s17
	s_nop 0
	global_load_lds_dwordx4 v[214:215], off
	s_mov_b32 m0, s21
	s_nop 0
	global_load_lds_dwordx4 v[216:217], off
	s_waitcnt vmcnt(8)
	s_waitcnt lgkmcnt(0)
	s_barrier
; #define PG8_STAGE(bufoff, gbase, voff) do { _Pragma("unroll") for (int _i = 0; _i < 2; ++_i) \
;         __builtin_amdgcn_global_load_lds((const unsigned*)((const char*)(gbase) + (voff)[_i]), (LAS unsigned*)(lds + (bufoff) + ldsw + _i * 8192), 16, 0, 0); } while (0)
; #define PG8_LDA(dst, b, h) do { _Pragma("unroll") for (int m = 0; m < 4; ++m) _Pragma("unroll") for (int k = 0; k < 2; ++k) dst[m][k] = *(const LAS bf16x8*)(lds + PG8_SA(b, h) + aoff + m * 2048 + k * 1024); } while (0)
; #define PG8_LDB(dst, b, h) do { _Pragma("unroll") for (int n = 0; n < 2; ++n) _Pragma("unroll") for (int k = 0; k < 2; ++k) dst[n][k] = *(const LAS bf16x8*)(lds + PG8_SB(b, h) + boff + n * 2048 + k * 1024); } while (0)
; #define PG8_MMA(ai, bj, At, Bt) do { __builtin_amdgcn_s_setprio(1); _Pragma("unroll") for (int m = 0; m < 4; ++m) _Pragma("unroll") for (int n = 0; n < 2; ++n) _Pragma("unroll") for (int k = 0; k < 2; ++k) \
;         acc[ai][bj][m][n] = __builtin_amdgcn_mfma_f32_16x16x32_bf16(Bt[n][k], At[m][k], acc[ai][bj][m][n], 0, 0, 0); __builtin_amdgcn_s_setprio(0); } while (0)
; #define PG8_WAIT_V(n) asm volatile("s_waitcnt vmcnt(" #n ")" ::: "memory")
; #define PG8_WAIT_L(n) asm volatile("s_waitcnt lgkmcnt(" #n ")" ::: "memory")
; #define PG8_BAR __builtin_amdgcn_s_barrier()
; #define PG8_SCHED __builtin_amdgcn_sched_barrier(0)
; template <class Epi>
; DI void gemm_phase(int wv, LAS unsigned char* lds, LAS unsigned char* scr, const Sched& S, const Epi& E) {
;     ...
;             PG8_WAIT_V(8); PG8_WAIT_L(0); PG8_BAR; PG8_MMA(1, 0, At, B0); PG8_MMA(1, 1, At, B1); PG8_BAR; PG8_SCHED;
;             PG8_LDB(B0, 1, 0); PG8_LDB(B1, 1, 1); PG8_SCHED; PG8_LDA(At, 1, 0); PG8_STAGE(PG8_SA(0, 1), a2 + hstepA, voffA);
;             PG8_WAIT_V(8); PG8_WAIT_L(0); PG8_BAR; PG8_MMA(0, 0, At, B0); PG8_MMA(0, 1, At, B1); PG8_BAR; PG8_SCHED;
	v_mfma_f32_16x16x32_bf16 v[60:63], v[144:147], v[176:179], v[60:63]
	v_mfma_f32_16x16x32_bf16 v[56:59], v[152:155], v[176:179], v[56:59]
	v_mfma_f32_16x16x32_bf16 v[52:55], v[144:147], v[184:187], v[52:55]
	v_mfma_f32_16x16x32_bf16 v[48:51], v[152:155], v[184:187], v[48:51]
	v_mfma_f32_16x16x32_bf16 v[36:39], v[144:147], v[194:197], v[36:39]
	v_mfma_f32_16x16x32_bf16 v[32:35], v[152:155], v[194:197], v[32:35]
	v_mfma_f32_16x16x32_bf16 v[20:23], v[144:147], v[202:205], v[20:23]
	v_mfma_f32_16x16x32_bf16 v[16:19], v[152:155], v[202:205], v[16:19]
	v_mfma_f32_16x16x32_bf16 v[60:63], v[148:151], v[180:183], v[60:63]
	v_mfma_f32_16x16x32_bf16 v[56:59], v[156:159], v[180:183], v[56:59]
	v_mfma_f32_16x16x32_bf16 v[52:55], v[148:151], v[188:191], v[52:55]
	v_mfma_f32_16x16x32_bf16 v[48:51], v[156:159], v[188:191], v[48:51]
	v_mfma_f32_16x16x32_bf16 v[36:39], v[148:151], v[198:201], v[36:39]
	v_mfma_f32_16x16x32_bf16 v[32:35], v[156:159], v[198:201], v[32:35]
	v_mfma_f32_16x16x32_bf16 v[20:23], v[148:151], v[206:209], v[20:23]
	v_mfma_f32_16x16x32_bf16 v[16:19], v[156:159], v[206:209], v[16:19]
	v_mfma_f32_16x16x32_bf16 v[44:47], v[160:163], v[176:179], v[44:47]
	v_mfma_f32_16x16x32_bf16 v[40:43], v[168:171], v[176:179], v[40:43]
	v_mfma_f32_16x16x32_bf16 v[28:31], v[160:163], v[184:187], v[28:31]
	v_mfma_f32_16x16x32_bf16 v[24:27], v[168:171], v[184:187], v[24:27]
	v_mfma_f32_16x16x32_bf16 v[12:15], v[160:163], v[194:197], v[12:15]
	v_mfma_f32_16x16x32_bf16 v[8:11], v[168:171], v[194:197], v[8:11]
	v_mfma_f32_16x16x32_bf16 v[4:7], v[160:163], v[202:205], v[4:7]
	v_mfma_f32_16x16x32_bf16 v[0:3], v[168:171], v[202:205], v[0:3]
	v_mfma_f32_16x16x32_bf16 v[44:47], v[164:167], v[180:183], v[44:47]
	v_mfma_f32_16x16x32_bf16 v[40:43], v[172:175], v[180:183], v[40:43]
	v_mfma_f32_16x16x32_bf16 v[28:31], v[164:167], v[188:191], v[28:31]
	v_mfma_f32_16x16x32_bf16 v[24:27], v[172:175], v[188:191], v[24:27]
	v_mfma_f32_16x16x32_bf16 v[12:15], v[164:167], v[198:201], v[12:15]
	v_mfma_f32_16x16x32_bf16 v[8:11], v[172:175], v[198:201], v[8:11]
	v_mfma_f32_16x16x32_bf16 v[4:7], v[164:167], v[206:209], v[4:7]
	v_mfma_f32_16x16x32_bf16 v[0:3], v[172:175], v[206:209], v[0:3]
	s_barrier
	s_add_i32 s65, 0, 0x18000
	v_add_u32_e32 v143, s65, v140
	s_add_i32 s66, 0, 0x1c000
	ds_read_b128 v[144:147], v143
	ds_read_b128 v[148:151], v143 offset:1024
	ds_read_b128 v[152:155], v143 offset:2048
	ds_read_b128 v[156:159], v143 offset:3072
	v_add_u32_e32 v143, s66, v140
	ds_read_b128 v[160:163], v143
	ds_read_b128 v[164:167], v143 offset:1024
	ds_read_b128 v[168:171], v143 offset:2048
	ds_read_b128 v[172:175], v143 offset:3072
	s_add_u32 s36, s36, 0x40000
	s_addc_u32 s37, s37, 0
	s_mov_b32 m0, s42
	v_lshl_add_u64 v[218:219], s[36:37], 0, v[128:129]
	ds_read_b128 v[176:179], v142 offset:32768
	ds_read_b128 v[180:183], v142 offset:33792
	ds_read_b128 v[184:187], v142 offset:34816
	ds_read_b128 v[188:191], v142 offset:35840
	ds_read_b128 v[194:197], v142 offset:36864
	ds_read_b128 v[198:201], v142 offset:37888
	ds_read_b128 v[202:205], v142 offset:38912
	ds_read_b128 v[206:209], v142 offset:39936
	global_load_lds_dwordx4 v[218:219], off
	v_lshl_add_u64 v[218:219], s[36:37], 0, v[130:131]
	s_mov_b32 m0, s43
	s_nop 0
	global_load_lds_dwordx4 v[218:219], off
	s_waitcnt vmcnt(8)
	s_waitcnt lgkmcnt(0)
	s_barrier
	v_mfma_f32_16x16x32_bf16 v[124:127], v[144:147], v[176:179], v[124:127]
	v_mfma_f32_16x16x32_bf16 v[120:123], v[152:155], v[176:179], v[120:123]
	v_mfma_f32_16x16x32_bf16 v[116:119], v[144:147], v[184:187], v[116:119]
	v_mfma_f32_16x16x32_bf16 v[112:115], v[152:155], v[184:187], v[112:115]
	v_mfma_f32_16x16x32_bf16 v[100:103], v[144:147], v[194:197], v[100:103]
	v_mfma_f32_16x16x32_bf16 v[96:99], v[152:155], v[194:197], v[96:99]
	v_mfma_f32_16x16x32_bf16 v[84:87], v[144:147], v[202:205], v[84:87]
	v_mfma_f32_16x16x32_bf16 v[80:83], v[152:155], v[202:205], v[80:83]
	v_mfma_f32_16x16x32_bf16 v[124:127], v[148:151], v[180:183], v[124:127]
	v_mfma_f32_16x16x32_bf16 v[120:123], v[156:159], v[180:183], v[120:123]
	v_mfma_f32_16x16x32_bf16 v[116:119], v[148:151], v[188:191], v[116:119]
	v_mfma_f32_16x16x32_bf16 v[112:115], v[156:159], v[188:191], v[112:115]
	v_mfma_f32_16x16x32_bf16 v[100:103], v[148:151], v[198:201], v[100:103]
	v_mfma_f32_16x16x32_bf16 v[96:99], v[156:159], v[198:201], v[96:99]
	v_mfma_f32_16x16x32_bf16 v[84:87], v[148:151], v[206:209], v[84:87]
	v_mfma_f32_16x16x32_bf16 v[80:83], v[156:159], v[206:209], v[80:83]
	v_mfma_f32_16x16x32_bf16 v[108:111], v[160:163], v[176:179], v[108:111]
	v_mfma_f32_16x16x32_bf16 v[104:107], v[168:171], v[176:179], v[104:107]
	v_mfma_f32_16x16x32_bf16 v[92:95], v[160:163], v[184:187], v[92:95]
	v_mfma_f32_16x16x32_bf16 v[88:91], v[168:171], v[184:187], v[88:91]
	v_mfma_f32_16x16x32_bf16 v[76:79], v[160:163], v[194:197], v[76:79]
	v_mfma_f32_16x16x32_bf16 v[72:75], v[168:171], v[194:197], v[72:75]
	v_mfma_f32_16x16x32_bf16 v[68:71], v[160:163], v[202:205], v[68:71]
	v_mfma_f32_16x16x32_bf16 v[64:67], v[168:171], v[202:205], v[64:67]
	v_mfma_f32_16x16x32_bf16 v[108:111], v[164:167], v[180:183], v[108:111]
	v_mfma_f32_16x16x32_bf16 v[104:107], v[172:175], v[180:183], v[104:107]
	v_mfma_f32_16x16x32_bf16 v[92:95], v[164:167], v[188:191], v[92:95]
	v_mfma_f32_16x16x32_bf16 v[88:91], v[172:175], v[188:191], v[88:91]
	v_mfma_f32_16x16x32_bf16 v[76:79], v[164:167], v[198:201], v[76:79]
	v_mfma_f32_16x16x32_bf16 v[72:75], v[172:175], v[198:201], v[72:75]
	v_mfma_f32_16x16x32_bf16 v[68:71], v[164:167], v[206:209], v[68:71]
	v_mfma_f32_16x16x32_bf16 v[64:67], v[172:175], v[206:209], v[64:67]
	s_barrier
; #define PG8_STAGE(bufoff, gbase, voff) do { _Pragma("unroll") for (int _i = 0; _i < 2; ++_i) \
;         __builtin_amdgcn_global_load_lds((const unsigned*)((const char*)(gbase) + (voff)[_i]), (LAS unsigned*)(lds + (bufoff) + ldsw + _i * 8192), 16, 0, 0); } while (0)
; #define PG8_LDA(dst, b, h) do { _Pragma("unroll") for (int m = 0; m < 4; ++m) _Pragma("unroll") for (int k = 0; k < 2; ++k) dst[m][k] = *(const LAS bf16x8*)(lds + PG8_SA(b, h) + aoff + m * 2048 + k * 1024); } while (0)
; #define PG8_MMA(ai, bj, At, Bt) do { __builtin_amdgcn_s_setprio(1); _Pragma("unroll") for (int m = 0; m < 4; ++m) _Pragma("unroll") for (int n = 0; n < 2; ++n) _Pragma("unroll") for (int k = 0; k < 2; ++k) \
;         acc[ai][bj][m][n] = __builtin_amdgcn_mfma_f32_16x16x32_bf16(Bt[n][k], At[m][k], acc[ai][bj][m][n], 0, 0, 0); __builtin_amdgcn_s_setprio(0); } while (0)
; #define PG8_WAIT_V(n) asm volatile("s_waitcnt vmcnt(" #n ")" ::: "memory")
; #define PG8_WAIT_L(n) asm volatile("s_waitcnt lgkmcnt(" #n ")" ::: "memory")
; #define PG8_BAR __builtin_amdgcn_s_barrier()
; #define PG8_SCHED __builtin_amdgcn_sched_barrier(0)
; template <class Epi>
; DI void gemm_phase(int wv, LAS unsigned char* lds, LAS unsigned char* scr, const Sched& S, const Epi& E) {
;     ...
;             PG8_LDA(At, 1, 1); PG8_STAGE(PG8_SB(1, 0), b3, voffB); PG8_STAGE(PG8_SB(1, 1), b3 + hstepB, voffB); PG8_STAGE(PG8_SA(1, 0), a3, voffA);
;             PG8_WAIT_V(8); PG8_WAIT_L(0); PG8_BAR; PG8_MMA(1, 0, At, B0); PG8_MMA(1, 1, At, B1); PG8_BAR; PG8_SCHED;
;         }
;         if (wr == 0) PG8_BAR;
	s_add_i32 s36, s65, s39
	v_lshl_add_u64 v[210:211], v[210:211], 0, s[2:3]
	s_mov_b32 m0, s36
	ds_read_b128 v[176:179], v142 offset:49152
	ds_read_b128 v[180:183], v142 offset:50176
	ds_read_b128 v[184:187], v142 offset:51200
	ds_read_b128 v[188:191], v142 offset:52224
	ds_read_b128 v[194:197], v142 offset:53248
	ds_read_b128 v[198:201], v142 offset:54272
	ds_read_b128 v[202:205], v142 offset:55296
	ds_read_b128 v[206:209], v142 offset:56320
	global_load_lds_dwordx4 v[210:211], off
	s_add_i32 m0, s36, 0x2000
	s_add_u32 s34, s34, 0x40080
	v_lshl_add_u64 v[210:211], v[212:213], 0, s[2:3]
	s_addc_u32 s35, s35, 0
	s_add_i32 s36, s66, s39
	global_load_lds_dwordx4 v[210:211], off
	v_lshl_add_u64 v[210:211], s[34:35], 0, v[192:193]
	s_mov_b32 m0, s36
	s_nop 0
	global_load_lds_dwordx4 v[210:211], off
	v_lshl_add_u64 v[210:211], s[34:35], 0, v[132:133]
	s_add_i32 m0, s36, 0x2000
	s_nop 0
	global_load_lds_dwordx4 v[210:211], off
	v_lshl_add_u64 v[210:211], v[214:215], 0, s[2:3]
	s_mov_b32 m0, s44
	s_nop 0
	global_load_lds_dwordx4 v[210:211], off
	v_lshl_add_u64 v[210:211], v[216:217], 0, s[2:3]
	s_mov_b32 m0, s45
	s_nop 0
	global_load_lds_dwordx4 v[210:211], off
	s_waitcnt vmcnt(8)
	s_waitcnt lgkmcnt(0)
	s_barrier
	v_mfma_f32_16x16x32_bf16 v[60:63], v[144:147], v[176:179], v[60:63]
	v_mfma_f32_16x16x32_bf16 v[56:59], v[152:155], v[176:179], v[56:59]
	v_mfma_f32_16x16x32_bf16 v[52:55], v[144:147], v[184:187], v[52:55]
	v_mfma_f32_16x16x32_bf16 v[48:51], v[152:155], v[184:187], v[48:51]
	v_mfma_f32_16x16x32_bf16 v[36:39], v[144:147], v[194:197], v[36:39]
	v_mfma_f32_16x16x32_bf16 v[32:35], v[152:155], v[194:197], v[32:35]
	v_mfma_f32_16x16x32_bf16 v[20:23], v[144:147], v[202:205], v[20:23]
	v_mfma_f32_16x16x32_bf16 v[16:19], v[152:155], v[202:205], v[16:19]
	v_mfma_f32_16x16x32_bf16 v[60:63], v[148:151], v[180:183], v[60:63]
	v_mfma_f32_16x16x32_bf16 v[56:59], v[156:159], v[180:183], v[56:59]
	v_mfma_f32_16x16x32_bf16 v[52:55], v[148:151], v[188:191], v[52:55]
	v_mfma_f32_16x16x32_bf16 v[48:51], v[156:159], v[188:191], v[48:51]
	v_mfma_f32_16x16x32_bf16 v[36:39], v[148:151], v[198:201], v[36:39]
	v_mfma_f32_16x16x32_bf16 v[32:35], v[156:159], v[198:201], v[32:35]
	v_mfma_f32_16x16x32_bf16 v[20:23], v[148:151], v[206:209], v[20:23]
	v_mfma_f32_16x16x32_bf16 v[16:19], v[156:159], v[206:209], v[16:19]
	v_mfma_f32_16x16x32_bf16 v[44:47], v[160:163], v[176:179], v[44:47]
	v_mfma_f32_16x16x32_bf16 v[40:43], v[168:171], v[176:179], v[40:43]
	v_mfma_f32_16x16x32_bf16 v[28:31], v[160:163], v[184:187], v[28:31]
	v_mfma_f32_16x16x32_bf16 v[24:27], v[168:171], v[184:187], v[24:27]
	v_mfma_f32_16x16x32_bf16 v[12:15], v[160:163], v[194:197], v[12:15]
	v_mfma_f32_16x16x32_bf16 v[8:11], v[168:171], v[194:197], v[8:11]
	v_mfma_f32_16x16x32_bf16 v[4:7], v[160:163], v[202:205], v[4:7]
	v_mfma_f32_16x16x32_bf16 v[0:3], v[168:171], v[202:205], v[0:3]
	v_mfma_f32_16x16x32_bf16 v[44:47], v[164:167], v[180:183], v[44:47]
	v_mfma_f32_16x16x32_bf16 v[40:43], v[172:175], v[180:183], v[40:43]
	v_mfma_f32_16x16x32_bf16 v[28:31], v[164:167], v[188:191], v[28:31]
	v_mfma_f32_16x16x32_bf16 v[24:27], v[172:175], v[188:191], v[24:27]
	v_mfma_f32_16x16x32_bf16 v[12:15], v[164:167], v[198:201], v[12:15]
	v_mfma_f32_16x16x32_bf16 v[8:11], v[172:175], v[198:201], v[8:11]
	v_mfma_f32_16x16x32_bf16 v[4:7], v[164:167], v[206:209], v[4:7]
	v_mfma_f32_16x16x32_bf16 v[0:3], v[172:175], v[206:209], v[0:3]
	s_barrier
	s_add_i32 s64, s64, 2
	s_add_u32 s62, s62, 0x100
	s_addc_u32 s63, s63, 0
	s_add_u32 s30, s30, 0x100
	s_addc_u32 s31, s31, 0
	s_cmp_gt_u32 s64, 13
	s_cbranch_scc0 .LBB0_137
	s_and_b64 vcc, exec, s[18:19]
	s_cbranch_vccz .LBB0_140
	s_barrier

; #define PG8_STAGE(bufoff, gbase, voff) do { _Pragma("unroll") for (int _i = 0; _i < 2; ++_i) \
;         __builtin_amdgcn_global_load_lds((const unsigned*)((const char*)(gbase) + (voff)[_i]), (LAS unsigned*)(lds + (bufoff) + ldsw + _i * 8192), 16, 0, 0); } while (0)
; #define PG8_LDA(dst, b, h) do { _Pragma("unroll") for (int m = 0; m < 4; ++m) _Pragma("unroll") for (int k = 0; k < 2; ++k) dst[m][k] = *(const LAS bf16x8*)(lds + PG8_SA(b, h) + aoff + m * 2048 + k * 1024); } while (0)
; #define PG8_LDB(dst, b, h) do { _Pragma("unroll") for (int n = 0; n < 2; ++n) _Pragma("unroll") for (int k = 0; k < 2; ++k) dst[n][k] = *(const LAS bf16x8*)(lds + PG8_SB(b, h) + boff + n * 2048 + k * 1024); } while (0)
; #define PG8_MMA(ai, bj, At, Bt) do { __builtin_amdgcn_s_setprio(1); _Pragma("unroll") for (int m = 0; m < 4; ++m) _Pragma("unroll") for (int n = 0; n < 2; ++n) _Pragma("unroll") for (int k = 0; k < 2; ++k) \
;         acc[ai][bj][m][n] = __builtin_amdgcn_mfma_f32_16x16x32_bf16(Bt[n][k], At[m][k], acc[ai][bj][m][n], 0, 0, 0); __builtin_amdgcn_s_setprio(0); } while (0)
; #define PG8_WAIT_V(n) asm volatile("s_waitcnt vmcnt(" #n ")" ::: "memory")
; #define PG8_WAIT_L(n) asm volatile("s_waitcnt lgkmcnt(" #n ")" ::: "memory")
; #define PG8_BAR __builtin_amdgcn_s_barrier()
; #define PG8_SCHED __builtin_amdgcn_sched_barrier(0)
; template <class Epi>
; DI void gemm_phase(int wv, LAS unsigned char* lds, LAS unsigned char* scr, const Sched& S, const Epi& E) {
;     ...
;             const bool last = (t == nt - 2);
;             const char* a1 = cA + (size_t)(t + 1) * kstep;
;             const char* a2 = last ? nA : cA + (size_t)(t + 2) * kstep; const char* b2 = last ? nB : cB + (size_t)(t + 2) * kstep;
;             const char* a3 = a2 + kstep; const char* b3 = b2 + kstep;
;             PG8_LDB(B0, 0, 0); PG8_LDB(B1, 0, 1); PG8_SCHED; PG8_LDA(At, 0, 0); PG8_STAGE(PG8_SA(1, 1), a1 + hstepA, voffA);
;             PG8_WAIT_V(8); PG8_WAIT_L(0); PG8_BAR; PG8_MMA(0, 0, At, B0); PG8_MMA(0, 1, At, B1); PG8_BAR; PG8_SCHED;
;             PG8_LDA(At, 0, 1); PG8_STAGE(PG8_SB(0, 0), b2, voffB); PG8_STAGE(PG8_SB(0, 1), b2 + hstepB, voffB); PG8_STAGE(PG8_SA(0, 0), a2, voffA);
.LBB0_163:
	s_add_u32 s26, s6, 0xfffc0080
	s_addc_u32 s27, s7, -1
	s_add_i32 s62, 0, 0x10000
	s_cmp_eq_u32 s61, 12
	s_cselect_b32 s29, s21, s27
	s_cselect_b32 s28, s40, s26
	v_add_u32_e32 v143, s62, v140
	s_cselect_b32 s27, s23, s60
	s_cselect_b32 s26, s22, s55
	s_add_i32 s64, 0, 0x14000
	ds_read_b128 v[144:147], v143
	ds_read_b128 v[148:151], v143 offset:1024
	ds_read_b128 v[152:155], v143 offset:2048
	ds_read_b128 v[156:159], v143 offset:3072
	v_add_u32_e32 v143, s64, v140
	ds_read_b128 v[160:163], v143
	ds_read_b128 v[164:167], v143 offset:1024
	ds_read_b128 v[168:171], v143 offset:2048
	ds_read_b128 v[172:175], v143 offset:3072
	v_lshl_add_u64 v[210:211], s[6:7], 0, v[138:139]
	s_add_i32 m0, s37, 0xc000
	ds_read_b128 v[176:179], v142
	ds_read_b128 v[180:183], v142 offset:1024
	ds_read_b128 v[184:187], v142 offset:2048
	ds_read_b128 v[188:191], v142 offset:3072
	ds_read_b128 v[194:197], v142 offset:4096
	ds_read_b128 v[198:201], v142 offset:5120
	ds_read_b128 v[202:205], v142 offset:6144
	ds_read_b128 v[206:209], v142 offset:7168
	global_load_lds_dwordx4 v[210:211], off
	v_lshl_add_u64 v[210:211], s[6:7], 0, v[136:137]
	s_add_i32 m0, s37, 0xe000
	s_nop 0
	global_load_lds_dwordx4 v[210:211], off
	s_waitcnt vmcnt(8)
	s_waitcnt lgkmcnt(0)
	s_barrier
	v_mfma_f32_16x16x32_bf16 v[124:127], v[144:147], v[176:179], v[124:127]
	v_mfma_f32_16x16x32_bf16 v[120:123], v[152:155], v[176:179], v[120:123]
	v_mfma_f32_16x16x32_bf16 v[116:119], v[144:147], v[184:187], v[116:119]
	v_mfma_f32_16x16x32_bf16 v[112:115], v[152:155], v[184:187], v[112:115]
	v_mfma_f32_16x16x32_bf16 v[100:103], v[144:147], v[194:197], v[100:103]
	v_mfma_f32_16x16x32_bf16 v[96:99], v[152:155], v[194:197], v[96:99]
	v_mfma_f32_16x16x32_bf16 v[84:87], v[144:147], v[202:205], v[84:87]
	v_mfma_f32_16x16x32_bf16 v[80:83], v[152:155], v[202:205], v[80:83]
	v_mfma_f32_16x16x32_bf16 v[124:127], v[148:151], v[180:183], v[124:127]
	v_mfma_f32_16x16x32_bf16 v[120:123], v[156:159], v[180:183], v[120:123]
	v_mfma_f32_16x16x32_bf16 v[116:119], v[148:151], v[188:191], v[116:119]
	v_mfma_f32_16x16x32_bf16 v[112:115], v[156:159], v[188:191], v[112:115]
	v_mfma_f32_16x16x32_bf16 v[100:103], v[148:151], v[198:201], v[100:103]
	v_mfma_f32_16x16x32_bf16 v[96:99], v[156:159], v[198:201], v[96:99]
	v_mfma_f32_16x16x32_bf16 v[84:87], v[148:151], v[206:209], v[84:87]
	v_mfma_f32_16x16x32_bf16 v[80:83], v[156:159], v[206:209], v[80:83]
	v_mfma_f32_16x16x32_bf16 v[108:111], v[160:163], v[176:179], v[108:111]
	v_mfma_f32_16x16x32_bf16 v[104:107], v[168:171], v[176:179], v[104:107]
	v_mfma_f32_16x16x32_bf16 v[92:95], v[160:163], v[184:187], v[92:95]
	v_mfma_f32_16x16x32_bf16 v[88:91], v[168:171], v[184:187], v[88:91]
	v_mfma_f32_16x16x32_bf16 v[76:79], v[160:163], v[194:197], v[76:79]
	v_mfma_f32_16x16x32_bf16 v[72:75], v[168:171], v[194:197], v[72:75]
	v_mfma_f32_16x16x32_bf16 v[68:71], v[160:163], v[202:205], v[68:71]
	v_mfma_f32_16x16x32_bf16 v[64:67], v[168:171], v[202:205], v[64:67]
	v_mfma_f32_16x16x32_bf16 v[108:111], v[164:167], v[180:183], v[108:111]
	v_mfma_f32_16x16x32_bf16 v[104:107], v[172:175], v[180:183], v[104:107]
	v_mfma_f32_16x16x32_bf16 v[92:95], v[164:167], v[188:191], v[92:95]
	v_mfma_f32_16x16x32_bf16 v[88:91], v[172:175], v[188:191], v[88:91]
	v_mfma_f32_16x16x32_bf16 v[76:79], v[164:167], v[198:201], v[76:79]
	v_mfma_f32_16x16x32_bf16 v[72:75], v[172:175], v[198:201], v[72:75]
	v_mfma_f32_16x16x32_bf16 v[68:71], v[164:167], v[206:209], v[68:71]
	v_mfma_f32_16x16x32_bf16 v[64:67], v[172:175], v[206:209], v[64:67]
	s_barrier
	s_add_i32 s62, s62, s33
	v_lshl_add_u64 v[210:211], s[26:27], 0, v[192:193]
	s_mov_b32 m0, s62
	ds_read_b128 v[176:179], v142 offset:16384
	ds_read_b128 v[180:183], v142 offset:17408
	ds_read_b128 v[184:187], v142 offset:18432
	ds_read_b128 v[188:191], v142 offset:19456
	ds_read_b128 v[194:197], v142 offset:20480
	ds_read_b128 v[198:201], v142 offset:21504
	ds_read_b128 v[202:205], v142 offset:22528
	ds_read_b128 v[206:209], v142 offset:23552
	global_load_lds_dwordx4 v[210:211], off
	s_add_i32 m0, s62, 0x2000
	s_add_u32 s62, s26, 0x100000
	v_lshl_add_u64 v[212:213], s[26:27], 0, v[132:133]
	s_addc_u32 s63, s27, 0
	s_add_i32 s64, s64, s33
	global_load_lds_dwordx4 v[212:213], off
	v_lshl_add_u64 v[214:215], s[62:63], 0, v[192:193]
	s_mov_b32 m0, s64
	v_lshl_add_u64 v[216:217], s[28:29], 0, v[130:131]
	global_load_lds_dwordx4 v[214:215], off
	v_lshl_add_u64 v[214:215], s[62:63], 0, v[132:133]
	s_add_i32 m0, s64, 0x2000
	s_nop 0
	global_load_lds_dwordx4 v[214:215], off
	v_lshl_add_u64 v[214:215], s[28:29], 0, v[128:129]
	s_mov_b32 m0, s37
	s_nop 0
	global_load_lds_dwordx4 v[214:215], off
	s_mov_b32 m0, s38
	s_nop 0
	global_load_lds_dwordx4 v[216:217], off
	s_waitcnt vmcnt(8)
	s_waitcnt lgkmcnt(0)
	s_barrier
; #define PG8_STAGE(bufoff, gbase, voff) do { _Pragma("unroll") for (int _i = 0; _i < 2; ++_i) \
;         __builtin_amdgcn_global_load_lds((const unsigned*)((const char*)(gbase) + (voff)[_i]), (LAS unsigned*)(lds + (bufoff) + ldsw + _i * 8192), 16, 0, 0); } while (0)
; #define PG8_LDA(dst, b, h) do { _Pragma("unroll") for (int m = 0; m < 4; ++m) _Pragma("unroll") for (int k = 0; k < 2; ++k) dst[m][k] = *(const LAS bf16x8*)(lds + PG8_SA(b, h) + aoff + m * 2048 + k * 1024); } while (0)
; #define PG8_LDB(dst, b, h) do { _Pragma("unroll") for (int n = 0; n < 2; ++n) _Pragma("unroll") for (int k = 0; k < 2; ++k) dst[n][k] = *(const LAS bf16x8*)(lds + PG8_SB(b, h) + boff + n * 2048 + k * 1024); } while (0)
; #define PG8_MMA(ai, bj, At, Bt) do { __builtin_amdgcn_s_setprio(1); _Pragma("unroll") for (int m = 0; m < 4; ++m) _Pragma("unroll") for (int n = 0; n < 2; ++n) _Pragma("unroll") for (int k = 0; k < 2; ++k) \
;         acc[ai][bj][m][n] = __builtin_amdgcn_mfma_f32_16x16x32_bf16(Bt[n][k], At[m][k], acc[ai][bj][m][n], 0, 0, 0); __builtin_amdgcn_s_setprio(0); } while (0)
; #define PG8_WAIT_V(n) asm volatile("s_waitcnt vmcnt(" #n ")" ::: "memory")
; #define PG8_WAIT_L(n) asm volatile("s_waitcnt lgkmcnt(" #n ")" ::: "memory")
; #define PG8_BAR __builtin_amdgcn_s_barrier()
; #define PG8_SCHED __builtin_amdgcn_sched_barrier(0)
; template <class Epi>
; DI void gemm_phase(int wv, LAS unsigned char* lds, LAS unsigned char* scr, const Sched& S, const Epi& E) {
;     ...
;             PG8_WAIT_V(8); PG8_WAIT_L(0); PG8_BAR; PG8_MMA(1, 0, At, B0); PG8_MMA(1, 1, At, B1); PG8_BAR; PG8_SCHED;
;             PG8_LDB(B0, 1, 0); PG8_LDB(B1, 1, 1); PG8_SCHED; PG8_LDA(At, 1, 0); PG8_STAGE(PG8_SA(0, 1), a2 + hstepA, voffA);
;             PG8_WAIT_V(8); PG8_WAIT_L(0); PG8_BAR; PG8_MMA(0, 0, At, B0); PG8_MMA(0, 1, At, B1); PG8_BAR; PG8_SCHED;
	v_mfma_f32_16x16x32_bf16 v[60:63], v[144:147], v[176:179], v[60:63]
	v_mfma_f32_16x16x32_bf16 v[56:59], v[152:155], v[176:179], v[56:59]
	v_mfma_f32_16x16x32_bf16 v[52:55], v[144:147], v[184:187], v[52:55]
	v_mfma_f32_16x16x32_bf16 v[48:51], v[152:155], v[184:187], v[48:51]
	v_mfma_f32_16x16x32_bf16 v[36:39], v[144:147], v[194:197], v[36:39]
	v_mfma_f32_16x16x32_bf16 v[32:35], v[152:155], v[194:197], v[32:35]
	v_mfma_f32_16x16x32_bf16 v[20:23], v[144:147], v[202:205], v[20:23]
	v_mfma_f32_16x16x32_bf16 v[16:19], v[152:155], v[202:205], v[16:19]
	v_mfma_f32_16x16x32_bf16 v[60:63], v[148:151], v[180:183], v[60:63]
	v_mfma_f32_16x16x32_bf16 v[56:59], v[156:159], v[180:183], v[56:59]
	v_mfma_f32_16x16x32_bf16 v[52:55], v[148:151], v[188:191], v[52:55]
	v_mfma_f32_16x16x32_bf16 v[48:51], v[156:159], v[188:191], v[48:51]
	v_mfma_f32_16x16x32_bf16 v[36:39], v[148:151], v[198:201], v[36:39]
	v_mfma_f32_16x16x32_bf16 v[32:35], v[156:159], v[198:201], v[32:35]
	v_mfma_f32_16x16x32_bf16 v[20:23], v[148:151], v[206:209], v[20:23]
	v_mfma_f32_16x16x32_bf16 v[16:19], v[156:159], v[206:209], v[16:19]
	v_mfma_f32_16x16x32_bf16 v[44:47], v[160:163], v[176:179], v[44:47]
	v_mfma_f32_16x16x32_bf16 v[40:43], v[168:171], v[176:179], v[40:43]
	v_mfma_f32_16x16x32_bf16 v[28:31], v[160:163], v[184:187], v[28:31]
	v_mfma_f32_16x16x32_bf16 v[24:27], v[168:171], v[184:187], v[24:27]
	v_mfma_f32_16x16x32_bf16 v[12:15], v[160:163], v[194:197], v[12:15]
	v_mfma_f32_16x16x32_bf16 v[8:11], v[168:171], v[194:197], v[8:11]
	v_mfma_f32_16x16x32_bf16 v[4:7], v[160:163], v[202:205], v[4:7]
	v_mfma_f32_16x16x32_bf16 v[0:3], v[168:171], v[202:205], v[0:3]
	v_mfma_f32_16x16x32_bf16 v[44:47], v[164:167], v[180:183], v[44:47]
	v_mfma_f32_16x16x32_bf16 v[40:43], v[172:175], v[180:183], v[40:43]
	v_mfma_f32_16x16x32_bf16 v[28:31], v[164:167], v[188:191], v[28:31]
	v_mfma_f32_16x16x32_bf16 v[24:27], v[172:175], v[188:191], v[24:27]
	v_mfma_f32_16x16x32_bf16 v[12:15], v[164:167], v[198:201], v[12:15]
	v_mfma_f32_16x16x32_bf16 v[8:11], v[172:175], v[198:201], v[8:11]
	v_mfma_f32_16x16x32_bf16 v[4:7], v[164:167], v[206:209], v[4:7]
	v_mfma_f32_16x16x32_bf16 v[0:3], v[172:175], v[206:209], v[0:3]
	s_barrier
	s_add_i32 s62, 0, 0x18000
	v_add_u32_e32 v143, s62, v140
	s_add_i32 s63, 0, 0x1c000
	ds_read_b128 v[144:147], v143
	ds_read_b128 v[148:151], v143 offset:1024
	ds_read_b128 v[152:155], v143 offset:2048
	ds_read_b128 v[156:159], v143 offset:3072
	v_add_u32_e32 v143, s63, v140
	ds_read_b128 v[160:163], v143
	ds_read_b128 v[164:167], v143 offset:1024
	ds_read_b128 v[168:171], v143 offset:2048
	ds_read_b128 v[172:175], v143 offset:3072
	s_add_u32 s28, s28, 0x40000
	s_addc_u32 s29, s29, 0
	s_mov_b32 m0, s39
	v_lshl_add_u64 v[218:219], s[28:29], 0, v[128:129]
	ds_read_b128 v[176:179], v142 offset:32768
	ds_read_b128 v[180:183], v142 offset:33792
	ds_read_b128 v[184:187], v142 offset:34816
	ds_read_b128 v[188:191], v142 offset:35840
	ds_read_b128 v[194:197], v142 offset:36864
	ds_read_b128 v[198:201], v142 offset:37888
	ds_read_b128 v[202:205], v142 offset:38912
	ds_read_b128 v[206:209], v142 offset:39936
	global_load_lds_dwordx4 v[218:219], off
	v_lshl_add_u64 v[218:219], s[28:29], 0, v[130:131]
	s_mov_b32 m0, s42
	s_nop 0
	global_load_lds_dwordx4 v[218:219], off
	s_waitcnt vmcnt(8)
	s_waitcnt lgkmcnt(0)
	s_barrier
	v_mfma_f32_16x16x32_bf16 v[124:127], v[144:147], v[176:179], v[124:127]
	v_mfma_f32_16x16x32_bf16 v[120:123], v[152:155], v[176:179], v[120:123]
	v_mfma_f32_16x16x32_bf16 v[116:119], v[144:147], v[184:187], v[116:119]
	v_mfma_f32_16x16x32_bf16 v[112:115], v[152:155], v[184:187], v[112:115]
	v_mfma_f32_16x16x32_bf16 v[100:103], v[144:147], v[194:197], v[100:103]
	v_mfma_f32_16x16x32_bf16 v[96:99], v[152:155], v[194:197], v[96:99]
	v_mfma_f32_16x16x32_bf16 v[84:87], v[144:147], v[202:205], v[84:87]
	v_mfma_f32_16x16x32_bf16 v[80:83], v[152:155], v[202:205], v[80:83]
	v_mfma_f32_16x16x32_bf16 v[124:127], v[148:151], v[180:183], v[124:127]
	v_mfma_f32_16x16x32_bf16 v[120:123], v[156:159], v[180:183], v[120:123]
	v_mfma_f32_16x16x32_bf16 v[116:119], v[148:151], v[188:191], v[116:119]
	v_mfma_f32_16x16x32_bf16 v[112:115], v[156:159], v[188:191], v[112:115]
	v_mfma_f32_16x16x32_bf16 v[100:103], v[148:151], v[198:201], v[100:103]
	v_mfma_f32_16x16x32_bf16 v[96:99], v[156:159], v[198:201], v[96:99]
	v_mfma_f32_16x16x32_bf16 v[84:87], v[148:151], v[206:209], v[84:87]
	v_mfma_f32_16x16x32_bf16 v[80:83], v[156:159], v[206:209], v[80:83]
	v_mfma_f32_16x16x32_bf16 v[108:111], v[160:163], v[176:179], v[108:111]
	v_mfma_f32_16x16x32_bf16 v[104:107], v[168:171], v[176:179], v[104:107]
	v_mfma_f32_16x16x32_bf16 v[92:95], v[160:163], v[184:187], v[92:95]
	v_mfma_f32_16x16x32_bf16 v[88:91], v[168:171], v[184:187], v[88:91]
	v_mfma_f32_16x16x32_bf16 v[76:79], v[160:163], v[194:197], v[76:79]
	v_mfma_f32_16x16x32_bf16 v[72:75], v[168:171], v[194:197], v[72:75]
	v_mfma_f32_16x16x32_bf16 v[68:71], v[160:163], v[202:205], v[68:71]
	v_mfma_f32_16x16x32_bf16 v[64:67], v[168:171], v[202:205], v[64:67]
	v_mfma_f32_16x16x32_bf16 v[108:111], v[164:167], v[180:183], v[108:111]
	v_mfma_f32_16x16x32_bf16 v[104:107], v[172:175], v[180:183], v[104:107]
	v_mfma_f32_16x16x32_bf16 v[92:95], v[164:167], v[188:191], v[92:95]
	v_mfma_f32_16x16x32_bf16 v[88:91], v[172:175], v[188:191], v[88:91]
	v_mfma_f32_16x16x32_bf16 v[76:79], v[164:167], v[198:201], v[76:79]
	v_mfma_f32_16x16x32_bf16 v[72:75], v[172:175], v[198:201], v[72:75]
	v_mfma_f32_16x16x32_bf16 v[68:71], v[164:167], v[206:209], v[68:71]
	v_mfma_f32_16x16x32_bf16 v[64:67], v[172:175], v[206:209], v[64:67]
	s_barrier
; #define PG8_STAGE(bufoff, gbase, voff) do { _Pragma("unroll") for (int _i = 0; _i < 2; ++_i) \
;         __builtin_amdgcn_global_load_lds((const unsigned*)((const char*)(gbase) + (voff)[_i]), (LAS unsigned*)(lds + (bufoff) + ldsw + _i * 8192), 16, 0, 0); } while (0)
; #define PG8_LDA(dst, b, h) do { _Pragma("unroll") for (int m = 0; m < 4; ++m) _Pragma("unroll") for (int k = 0; k < 2; ++k) dst[m][k] = *(const LAS bf16x8*)(lds + PG8_SA(b, h) + aoff + m * 2048 + k * 1024); } while (0)
; #define PG8_MMA(ai, bj, At, Bt) do { __builtin_amdgcn_s_setprio(1); _Pragma("unroll") for (int m = 0; m < 4; ++m) _Pragma("unroll") for (int n = 0; n < 2; ++n) _Pragma("unroll") for (int k = 0; k < 2; ++k) \
;         acc[ai][bj][m][n] = __builtin_amdgcn_mfma_f32_16x16x32_bf16(Bt[n][k], At[m][k], acc[ai][bj][m][n], 0, 0, 0); __builtin_amdgcn_s_setprio(0); } while (0)
; #define PG8_WAIT_V(n) asm volatile("s_waitcnt vmcnt(" #n ")" ::: "memory")
; #define PG8_WAIT_L(n) asm volatile("s_waitcnt lgkmcnt(" #n ")" ::: "memory")
; #define PG8_BAR __builtin_amdgcn_s_barrier()
; #define PG8_SCHED __builtin_amdgcn_sched_barrier(0)
; template <class Epi>
; DI void gemm_phase(int wv, LAS unsigned char* lds, LAS unsigned char* scr, const Sched& S, const Epi& E) {
;     ...
;             PG8_LDA(At, 1, 1); PG8_STAGE(PG8_SB(1, 0), b3, voffB); PG8_STAGE(PG8_SB(1, 1), b3 + hstepB, voffB); PG8_STAGE(PG8_SA(1, 0), a3, voffA);
;             PG8_WAIT_V(8); PG8_WAIT_L(0); PG8_BAR; PG8_MMA(1, 0, At, B0); PG8_MMA(1, 1, At, B1); PG8_BAR; PG8_SCHED;
;         }
;         if (wr == 0) PG8_BAR;
	s_add_i32 s28, s62, s33
	v_lshl_add_u64 v[210:211], v[210:211], 0, s[2:3]
	s_mov_b32 m0, s28
	ds_read_b128 v[176:179], v142 offset:49152
	ds_read_b128 v[180:183], v142 offset:50176
	ds_read_b128 v[184:187], v142 offset:51200
	ds_read_b128 v[188:191], v142 offset:52224
	ds_read_b128 v[194:197], v142 offset:53248
	ds_read_b128 v[198:201], v142 offset:54272
	ds_read_b128 v[202:205], v142 offset:55296
	ds_read_b128 v[206:209], v142 offset:56320
	global_load_lds_dwordx4 v[210:211], off
	s_add_i32 m0, s28, 0x2000
	s_add_u32 s26, s26, 0x100080
	v_lshl_add_u64 v[210:211], v[212:213], 0, s[2:3]
	s_addc_u32 s27, s27, 0
	s_add_i32 s28, s63, s33
	global_load_lds_dwordx4 v[210:211], off
	v_lshl_add_u64 v[210:211], s[26:27], 0, v[192:193]
	s_mov_b32 m0, s28
	s_nop 0
	global_load_lds_dwordx4 v[210:211], off
	v_lshl_add_u64 v[210:211], s[26:27], 0, v[132:133]
	s_add_i32 m0, s28, 0x2000
	s_nop 0
	global_load_lds_dwordx4 v[210:211], off
	v_lshl_add_u64 v[210:211], v[214:215], 0, s[2:3]
	s_mov_b32 m0, s43
	s_nop 0
	global_load_lds_dwordx4 v[210:211], off
	v_lshl_add_u64 v[210:211], v[216:217], 0, s[2:3]
	s_mov_b32 m0, s44
	s_nop 0
	global_load_lds_dwordx4 v[210:211], off
	s_waitcnt vmcnt(8)
	s_waitcnt lgkmcnt(0)
	s_barrier
	v_mfma_f32_16x16x32_bf16 v[60:63], v[144:147], v[176:179], v[60:63]
	v_mfma_f32_16x16x32_bf16 v[56:59], v[152:155], v[176:179], v[56:59]
	v_mfma_f32_16x16x32_bf16 v[52:55], v[144:147], v[184:187], v[52:55]
	v_mfma_f32_16x16x32_bf16 v[48:51], v[152:155], v[184:187], v[48:51]
	v_mfma_f32_16x16x32_bf16 v[36:39], v[144:147], v[194:197], v[36:39]
	v_mfma_f32_16x16x32_bf16 v[32:35], v[152:155], v[194:197], v[32:35]
	v_mfma_f32_16x16x32_bf16 v[20:23], v[144:147], v[202:205], v[20:23]
	v_mfma_f32_16x16x32_bf16 v[16:19], v[152:155], v[202:205], v[16:19]
	v_mfma_f32_16x16x32_bf16 v[60:63], v[148:151], v[180:183], v[60:63]
	v_mfma_f32_16x16x32_bf16 v[56:59], v[156:159], v[180:183], v[56:59]
	v_mfma_f32_16x16x32_bf16 v[52:55], v[148:151], v[188:191], v[52:55]
	v_mfma_f32_16x16x32_bf16 v[48:51], v[156:159], v[188:191], v[48:51]
	v_mfma_f32_16x16x32_bf16 v[36:39], v[148:151], v[198:201], v[36:39]
	v_mfma_f32_16x16x32_bf16 v[32:35], v[156:159], v[198:201], v[32:35]
	v_mfma_f32_16x16x32_bf16 v[20:23], v[148:151], v[206:209], v[20:23]
	v_mfma_f32_16x16x32_bf16 v[16:19], v[156:159], v[206:209], v[16:19]
	v_mfma_f32_16x16x32_bf16 v[44:47], v[160:163], v[176:179], v[44:47]
	v_mfma_f32_16x16x32_bf16 v[40:43], v[168:171], v[176:179], v[40:43]
	v_mfma_f32_16x16x32_bf16 v[28:31], v[160:163], v[184:187], v[28:31]
	v_mfma_f32_16x16x32_bf16 v[24:27], v[168:171], v[184:187], v[24:27]
	v_mfma_f32_16x16x32_bf16 v[12:15], v[160:163], v[194:197], v[12:15]
	v_mfma_f32_16x16x32_bf16 v[8:11], v[168:171], v[194:197], v[8:11]
	v_mfma_f32_16x16x32_bf16 v[4:7], v[160:163], v[202:205], v[4:7]
	v_mfma_f32_16x16x32_bf16 v[0:3], v[168:171], v[202:205], v[0:3]
	v_mfma_f32_16x16x32_bf16 v[44:47], v[164:167], v[180:183], v[44:47]
	v_mfma_f32_16x16x32_bf16 v[40:43], v[172:175], v[180:183], v[40:43]
	v_mfma_f32_16x16x32_bf16 v[28:31], v[164:167], v[188:191], v[28:31]
	v_mfma_f32_16x16x32_bf16 v[24:27], v[172:175], v[188:191], v[24:27]
	v_mfma_f32_16x16x32_bf16 v[12:15], v[164:167], v[198:201], v[12:15]
	v_mfma_f32_16x16x32_bf16 v[8:11], v[172:175], v[198:201], v[8:11]
	v_mfma_f32_16x16x32_bf16 v[4:7], v[164:167], v[206:209], v[4:7]
	v_mfma_f32_16x16x32_bf16 v[0:3], v[172:175], v[206:209], v[0:3]
	s_barrier
	s_add_i32 s61, s61, 2
	s_add_u32 s55, s55, 0x100
	s_addc_u32 s60, s60, 0
	s_add_u32 s6, s6, 0x100
	s_addc_u32 s7, s7, 0
	s_cmp_gt_u32 s61, 13
	s_cbranch_scc0 .LBB0_163
	s_and_b64 vcc, exec, s[18:19]
	s_cbranch_vccz .LBB0_166
	s_barrier

; #define PG8_STAGE(bufoff, gbase, voff) do { _Pragma("unroll") for (int _i = 0; _i < 2; ++_i) \
;         __builtin_amdgcn_global_load_lds((const unsigned*)((const char*)(gbase) + (voff)[_i]), (LAS unsigned*)(lds + (bufoff) + ldsw + _i * 8192), 16, 0, 0); } while (0)
; #define PG8_LDA(dst, b, h) do { _Pragma("unroll") for (int m = 0; m < 4; ++m) _Pragma("unroll") for (int k = 0; k < 2; ++k) dst[m][k] = *(const LAS bf16x8*)(lds + PG8_SA(b, h) + aoff + m * 2048 + k * 1024); } while (0)
; #define PG8_LDB(dst, b, h) do { _Pragma("unroll") for (int n = 0; n < 2; ++n) _Pragma("unroll") for (int k = 0; k < 2; ++k) dst[n][k] = *(const LAS bf16x8*)(lds + PG8_SB(b, h) + boff + n * 2048 + k * 1024); } while (0)
; #define PG8_MMA(ai, bj, At, Bt) do { __builtin_amdgcn_s_setprio(1); _Pragma("unroll") for (int m = 0; m < 4; ++m) _Pragma("unroll") for (int n = 0; n < 2; ++n) _Pragma("unroll") for (int k = 0; k < 2; ++k) \
;         acc[ai][bj][m][n] = __builtin_amdgcn_mfma_f32_16x16x32_bf16(Bt[n][k], At[m][k], acc[ai][bj][m][n], 0, 0, 0); __builtin_amdgcn_s_setprio(0); } while (0)
; #define PG8_WAIT_V(n) asm volatile("s_waitcnt vmcnt(" #n ")" ::: "memory")
; #define PG8_WAIT_L(n) asm volatile("s_waitcnt lgkmcnt(" #n ")" ::: "memory")
; #define PG8_BAR __builtin_amdgcn_s_barrier()
; #define PG8_SCHED __builtin_amdgcn_sched_barrier(0)
; template <class Epi>
; DI void gemm_phase(int wv, LAS unsigned char* lds, LAS unsigned char* scr, const Sched& S, const Epi& E) {
;     ...
;             const bool last = (t == nt - 2);
;             const char* a1 = cA + (size_t)(t + 1) * kstep;
;             const char* a2 = last ? nA : cA + (size_t)(t + 2) * kstep; const char* b2 = last ? nB : cB + (size_t)(t + 2) * kstep;
;             const char* a3 = a2 + kstep; const char* b3 = b2 + kstep;
;             PG8_LDB(B0, 0, 0); PG8_LDB(B1, 0, 1); PG8_SCHED; PG8_LDA(At, 0, 0); PG8_STAGE(PG8_SA(1, 1), a1 + hstepA, voffA);
;             PG8_WAIT_V(8); PG8_WAIT_L(0); PG8_BAR; PG8_MMA(0, 0, At, B0); PG8_MMA(0, 1, At, B1); PG8_BAR; PG8_SCHED;
;             PG8_LDA(At, 0, 1); PG8_STAGE(PG8_SB(0, 0), b2, voffB); PG8_STAGE(PG8_SB(0, 1), b2 + hstepB, voffB); PG8_STAGE(PG8_SA(0, 0), a2, voffA);
.LBB0_189:
	s_add_u32 s26, s6, 0xfffc0080
	s_addc_u32 s27, s7, -1
	s_add_i32 s59, 0, 0x10000
	s_cmp_eq_u32 s55, 12
	s_cselect_b32 s29, s21, s27
	s_cselect_b32 s28, s40, s26
	v_add_u32_e32 v143, s59, v140
	s_cselect_b32 s27, s23, s54
	s_cselect_b32 s26, s22, s51
	s_add_i32 s62, 0, 0x14000
	ds_read_b128 v[144:147], v143
	ds_read_b128 v[148:151], v143 offset:1024
	ds_read_b128 v[152:155], v143 offset:2048
	ds_read_b128 v[156:159], v143 offset:3072
	v_add_u32_e32 v143, s62, v140
	ds_read_b128 v[160:163], v143
	ds_read_b128 v[164:167], v143 offset:1024
	ds_read_b128 v[168:171], v143 offset:2048
	ds_read_b128 v[172:175], v143 offset:3072
	v_lshl_add_u64 v[210:211], s[6:7], 0, v[138:139]
	s_add_i32 m0, s37, 0xc000
	ds_read_b128 v[176:179], v142
	ds_read_b128 v[180:183], v142 offset:1024
	ds_read_b128 v[184:187], v142 offset:2048
	ds_read_b128 v[188:191], v142 offset:3072
	ds_read_b128 v[194:197], v142 offset:4096
	ds_read_b128 v[198:201], v142 offset:5120
	ds_read_b128 v[202:205], v142 offset:6144
	ds_read_b128 v[206:209], v142 offset:7168
	global_load_lds_dwordx4 v[210:211], off
	v_lshl_add_u64 v[210:211], s[6:7], 0, v[136:137]
	s_add_i32 m0, s37, 0xe000
	s_nop 0
	global_load_lds_dwordx4 v[210:211], off
	s_waitcnt vmcnt(8)
	s_waitcnt lgkmcnt(0)
	s_barrier
	v_mfma_f32_16x16x32_bf16 v[124:127], v[144:147], v[176:179], v[124:127]
	v_mfma_f32_16x16x32_bf16 v[120:123], v[152:155], v[176:179], v[120:123]
	v_mfma_f32_16x16x32_bf16 v[116:119], v[144:147], v[184:187], v[116:119]
	v_mfma_f32_16x16x32_bf16 v[112:115], v[152:155], v[184:187], v[112:115]
	v_mfma_f32_16x16x32_bf16 v[100:103], v[144:147], v[194:197], v[100:103]
	v_mfma_f32_16x16x32_bf16 v[96:99], v[152:155], v[194:197], v[96:99]
	v_mfma_f32_16x16x32_bf16 v[84:87], v[144:147], v[202:205], v[84:87]
	v_mfma_f32_16x16x32_bf16 v[80:83], v[152:155], v[202:205], v[80:83]
	v_mfma_f32_16x16x32_bf16 v[124:127], v[148:151], v[180:183], v[124:127]
	v_mfma_f32_16x16x32_bf16 v[120:123], v[156:159], v[180:183], v[120:123]
	v_mfma_f32_16x16x32_bf16 v[116:119], v[148:151], v[188:191], v[116:119]
	v_mfma_f32_16x16x32_bf16 v[112:115], v[156:159], v[188:191], v[112:115]
	v_mfma_f32_16x16x32_bf16 v[100:103], v[148:151], v[198:201], v[100:103]
	v_mfma_f32_16x16x32_bf16 v[96:99], v[156:159], v[198:201], v[96:99]
	v_mfma_f32_16x16x32_bf16 v[84:87], v[148:151], v[206:209], v[84:87]
	v_mfma_f32_16x16x32_bf16 v[80:83], v[156:159], v[206:209], v[80:83]
	v_mfma_f32_16x16x32_bf16 v[108:111], v[160:163], v[176:179], v[108:111]
	v_mfma_f32_16x16x32_bf16 v[104:107], v[168:171], v[176:179], v[104:107]
	v_mfma_f32_16x16x32_bf16 v[92:95], v[160:163], v[184:187], v[92:95]
	v_mfma_f32_16x16x32_bf16 v[88:91], v[168:171], v[184:187], v[88:91]
	v_mfma_f32_16x16x32_bf16 v[76:79], v[160:163], v[194:197], v[76:79]
	v_mfma_f32_16x16x32_bf16 v[72:75], v[168:171], v[194:197], v[72:75]
	v_mfma_f32_16x16x32_bf16 v[68:71], v[160:163], v[202:205], v[68:71]
	v_mfma_f32_16x16x32_bf16 v[64:67], v[168:171], v[202:205], v[64:67]
	v_mfma_f32_16x16x32_bf16 v[108:111], v[164:167], v[180:183], v[108:111]
	v_mfma_f32_16x16x32_bf16 v[104:107], v[172:175], v[180:183], v[104:107]
	v_mfma_f32_16x16x32_bf16 v[92:95], v[164:167], v[188:191], v[92:95]
	v_mfma_f32_16x16x32_bf16 v[88:91], v[172:175], v[188:191], v[88:91]
	v_mfma_f32_16x16x32_bf16 v[76:79], v[164:167], v[198:201], v[76:79]
	v_mfma_f32_16x16x32_bf16 v[72:75], v[172:175], v[198:201], v[72:75]
	v_mfma_f32_16x16x32_bf16 v[68:71], v[164:167], v[206:209], v[68:71]
	v_mfma_f32_16x16x32_bf16 v[64:67], v[172:175], v[206:209], v[64:67]
	s_barrier
	s_add_i32 s59, s59, s33
	v_lshl_add_u64 v[210:211], s[26:27], 0, v[192:193]
	s_mov_b32 m0, s59
	ds_read_b128 v[176:179], v142 offset:16384
	ds_read_b128 v[180:183], v142 offset:17408
	ds_read_b128 v[184:187], v142 offset:18432
	ds_read_b128 v[188:191], v142 offset:19456
	ds_read_b128 v[194:197], v142 offset:20480
	ds_read_b128 v[198:201], v142 offset:21504
	ds_read_b128 v[202:205], v142 offset:22528
	ds_read_b128 v[206:209], v142 offset:23552
	global_load_lds_dwordx4 v[210:211], off
	s_add_i32 m0, s59, 0x2000
	s_add_u32 s60, s26, 0x400000
	v_lshl_add_u64 v[212:213], s[26:27], 0, v[132:133]
	s_addc_u32 s61, s27, 0
	s_add_i32 s59, s62, s33
	global_load_lds_dwordx4 v[212:213], off
	v_lshl_add_u64 v[214:215], s[60:61], 0, v[192:193]
	s_mov_b32 m0, s59
	v_lshl_add_u64 v[216:217], s[28:29], 0, v[130:131]
	global_load_lds_dwordx4 v[214:215], off
	v_lshl_add_u64 v[214:215], s[60:61], 0, v[132:133]
	s_add_i32 m0, s59, 0x2000
	s_nop 0
	global_load_lds_dwordx4 v[214:215], off
	v_lshl_add_u64 v[214:215], s[28:29], 0, v[128:129]
	s_mov_b32 m0, s37
	s_nop 0
	global_load_lds_dwordx4 v[214:215], off
	s_mov_b32 m0, s38
	s_nop 0
	global_load_lds_dwordx4 v[216:217], off
	s_waitcnt vmcnt(8)
	s_waitcnt lgkmcnt(0)
	s_barrier
; #define PG8_STAGE(bufoff, gbase, voff) do { _Pragma("unroll") for (int _i = 0; _i < 2; ++_i) \
;         __builtin_amdgcn_global_load_lds((const unsigned*)((const char*)(gbase) + (voff)[_i]), (LAS unsigned*)(lds + (bufoff) + ldsw + _i * 8192), 16, 0, 0); } while (0)
; #define PG8_LDA(dst, b, h) do { _Pragma("unroll") for (int m = 0; m < 4; ++m) _Pragma("unroll") for (int k = 0; k < 2; ++k) dst[m][k] = *(const LAS bf16x8*)(lds + PG8_SA(b, h) + aoff + m * 2048 + k * 1024); } while (0)
; #define PG8_LDB(dst, b, h) do { _Pragma("unroll") for (int n = 0; n < 2; ++n) _Pragma("unroll") for (int k = 0; k < 2; ++k) dst[n][k] = *(const LAS bf16x8*)(lds + PG8_SB(b, h) + boff + n * 2048 + k * 1024); } while (0)
; #define PG8_MMA(ai, bj, At, Bt) do { __builtin_amdgcn_s_setprio(1); _Pragma("unroll") for (int m = 0; m < 4; ++m) _Pragma("unroll") for (int n = 0; n < 2; ++n) _Pragma("unroll") for (int k = 0; k < 2; ++k) \
;         acc[ai][bj][m][n] = __builtin_amdgcn_mfma_f32_16x16x32_bf16(Bt[n][k], At[m][k], acc[ai][bj][m][n], 0, 0, 0); __builtin_amdgcn_s_setprio(0); } while (0)
; #define PG8_WAIT_V(n) asm volatile("s_waitcnt vmcnt(" #n ")" ::: "memory")
; #define PG8_WAIT_L(n) asm volatile("s_waitcnt lgkmcnt(" #n ")" ::: "memory")
; #define PG8_BAR __builtin_amdgcn_s_barrier()
; #define PG8_SCHED __builtin_amdgcn_sched_barrier(0)
; template <class Epi>
; DI void gemm_phase(int wv, LAS unsigned char* lds, LAS unsigned char* scr, const Sched& S, const Epi& E) {
;     ...
;             PG8_WAIT_V(8); PG8_WAIT_L(0); PG8_BAR; PG8_MMA(1, 0, At, B0); PG8_MMA(1, 1, At, B1); PG8_BAR; PG8_SCHED;
;             PG8_LDB(B0, 1, 0); PG8_LDB(B1, 1, 1); PG8_SCHED; PG8_LDA(At, 1, 0); PG8_STAGE(PG8_SA(0, 1), a2 + hstepA, voffA);
;             PG8_WAIT_V(8); PG8_WAIT_L(0); PG8_BAR; PG8_MMA(0, 0, At, B0); PG8_MMA(0, 1, At, B1); PG8_BAR; PG8_SCHED;
	v_mfma_f32_16x16x32_bf16 v[60:63], v[144:147], v[176:179], v[60:63]
	v_mfma_f32_16x16x32_bf16 v[56:59], v[152:155], v[176:179], v[56:59]
	v_mfma_f32_16x16x32_bf16 v[52:55], v[144:147], v[184:187], v[52:55]
	v_mfma_f32_16x16x32_bf16 v[48:51], v[152:155], v[184:187], v[48:51]
	v_mfma_f32_16x16x32_bf16 v[36:39], v[144:147], v[194:197], v[36:39]
	v_mfma_f32_16x16x32_bf16 v[32:35], v[152:155], v[194:197], v[32:35]
	v_mfma_f32_16x16x32_bf16 v[20:23], v[144:147], v[202:205], v[20:23]
	v_mfma_f32_16x16x32_bf16 v[16:19], v[152:155], v[202:205], v[16:19]
	v_mfma_f32_16x16x32_bf16 v[60:63], v[148:151], v[180:183], v[60:63]
	v_mfma_f32_16x16x32_bf16 v[56:59], v[156:159], v[180:183], v[56:59]
	v_mfma_f32_16x16x32_bf16 v[52:55], v[148:151], v[188:191], v[52:55]
	v_mfma_f32_16x16x32_bf16 v[48:51], v[156:159], v[188:191], v[48:51]
	v_mfma_f32_16x16x32_bf16 v[36:39], v[148:151], v[198:201], v[36:39]
	v_mfma_f32_16x16x32_bf16 v[32:35], v[156:159], v[198:201], v[32:35]
	v_mfma_f32_16x16x32_bf16 v[20:23], v[148:151], v[206:209], v[20:23]
	v_mfma_f32_16x16x32_bf16 v[16:19], v[156:159], v[206:209], v[16:19]
	v_mfma_f32_16x16x32_bf16 v[44:47], v[160:163], v[176:179], v[44:47]
	v_mfma_f32_16x16x32_bf16 v[40:43], v[168:171], v[176:179], v[40:43]
	v_mfma_f32_16x16x32_bf16 v[28:31], v[160:163], v[184:187], v[28:31]
	v_mfma_f32_16x16x32_bf16 v[24:27], v[168:171], v[184:187], v[24:27]
	v_mfma_f32_16x16x32_bf16 v[12:15], v[160:163], v[194:197], v[12:15]
	v_mfma_f32_16x16x32_bf16 v[8:11], v[168:171], v[194:197], v[8:11]
	v_mfma_f32_16x16x32_bf16 v[4:7], v[160:163], v[202:205], v[4:7]
	v_mfma_f32_16x16x32_bf16 v[0:3], v[168:171], v[202:205], v[0:3]
	v_mfma_f32_16x16x32_bf16 v[44:47], v[164:167], v[180:183], v[44:47]
	v_mfma_f32_16x16x32_bf16 v[40:43], v[172:175], v[180:183], v[40:43]
	v_mfma_f32_16x16x32_bf16 v[28:31], v[164:167], v[188:191], v[28:31]
	v_mfma_f32_16x16x32_bf16 v[24:27], v[172:175], v[188:191], v[24:27]
	v_mfma_f32_16x16x32_bf16 v[12:15], v[164:167], v[198:201], v[12:15]
	v_mfma_f32_16x16x32_bf16 v[8:11], v[172:175], v[198:201], v[8:11]
	v_mfma_f32_16x16x32_bf16 v[4:7], v[164:167], v[206:209], v[4:7]
	v_mfma_f32_16x16x32_bf16 v[0:3], v[172:175], v[206:209], v[0:3]
	s_barrier
	s_add_i32 s59, 0, 0x18000
	v_add_u32_e32 v143, s59, v140
	s_add_i32 s60, 0, 0x1c000
	ds_read_b128 v[144:147], v143
	ds_read_b128 v[148:151], v143 offset:1024
	ds_read_b128 v[152:155], v143 offset:2048
	ds_read_b128 v[156:159], v143 offset:3072
	v_add_u32_e32 v143, s60, v140
	ds_read_b128 v[160:163], v143
	ds_read_b128 v[164:167], v143 offset:1024
	ds_read_b128 v[168:171], v143 offset:2048
	ds_read_b128 v[172:175], v143 offset:3072
	s_add_u32 s28, s28, 0x40000
	s_addc_u32 s29, s29, 0
	s_mov_b32 m0, s39
	v_lshl_add_u64 v[218:219], s[28:29], 0, v[128:129]
	ds_read_b128 v[176:179], v142 offset:32768
	ds_read_b128 v[180:183], v142 offset:33792
	ds_read_b128 v[184:187], v142 offset:34816
	ds_read_b128 v[188:191], v142 offset:35840
	ds_read_b128 v[194:197], v142 offset:36864
	ds_read_b128 v[198:201], v142 offset:37888
	ds_read_b128 v[202:205], v142 offset:38912
	ds_read_b128 v[206:209], v142 offset:39936
	global_load_lds_dwordx4 v[218:219], off
	v_lshl_add_u64 v[218:219], s[28:29], 0, v[130:131]
	s_mov_b32 m0, s42
	s_nop 0
	global_load_lds_dwordx4 v[218:219], off
	s_waitcnt vmcnt(8)
	s_waitcnt lgkmcnt(0)
	s_barrier
	v_mfma_f32_16x16x32_bf16 v[124:127], v[144:147], v[176:179], v[124:127]
	v_mfma_f32_16x16x32_bf16 v[120:123], v[152:155], v[176:179], v[120:123]
	v_mfma_f32_16x16x32_bf16 v[116:119], v[144:147], v[184:187], v[116:119]
	v_mfma_f32_16x16x32_bf16 v[112:115], v[152:155], v[184:187], v[112:115]
	v_mfma_f32_16x16x32_bf16 v[100:103], v[144:147], v[194:197], v[100:103]
	v_mfma_f32_16x16x32_bf16 v[96:99], v[152:155], v[194:197], v[96:99]
	v_mfma_f32_16x16x32_bf16 v[84:87], v[144:147], v[202:205], v[84:87]
	v_mfma_f32_16x16x32_bf16 v[80:83], v[152:155], v[202:205], v[80:83]
	v_mfma_f32_16x16x32_bf16 v[124:127], v[148:151], v[180:183], v[124:127]
	v_mfma_f32_16x16x32_bf16 v[120:123], v[156:159], v[180:183], v[120:123]
	v_mfma_f32_16x16x32_bf16 v[116:119], v[148:151], v[188:191], v[116:119]
	v_mfma_f32_16x16x32_bf16 v[112:115], v[156:159], v[188:191], v[112:115]
	v_mfma_f32_16x16x32_bf16 v[100:103], v[148:151], v[198:201], v[100:103]
	v_mfma_f32_16x16x32_bf16 v[96:99], v[156:159], v[198:201], v[96:99]
	v_mfma_f32_16x16x32_bf16 v[84:87], v[148:151], v[206:209], v[84:87]
	v_mfma_f32_16x16x32_bf16 v[80:83], v[156:159], v[206:209], v[80:83]
	v_mfma_f32_16x16x32_bf16 v[108:111], v[160:163], v[176:179], v[108:111]
	v_mfma_f32_16x16x32_bf16 v[104:107], v[168:171], v[176:179], v[104:107]
	v_mfma_f32_16x16x32_bf16 v[92:95], v[160:163], v[184:187], v[92:95]
	v_mfma_f32_16x16x32_bf16 v[88:91], v[168:171], v[184:187], v[88:91]
	v_mfma_f32_16x16x32_bf16 v[76:79], v[160:163], v[194:197], v[76:79]
	v_mfma_f32_16x16x32_bf16 v[72:75], v[168:171], v[194:197], v[72:75]
	v_mfma_f32_16x16x32_bf16 v[68:71], v[160:163], v[202:205], v[68:71]
	v_mfma_f32_16x16x32_bf16 v[64:67], v[168:171], v[202:205], v[64:67]
	v_mfma_f32_16x16x32_bf16 v[108:111], v[164:167], v[180:183], v[108:111]
	v_mfma_f32_16x16x32_bf16 v[104:107], v[172:175], v[180:183], v[104:107]
	v_mfma_f32_16x16x32_bf16 v[92:95], v[164:167], v[188:191], v[92:95]
	v_mfma_f32_16x16x32_bf16 v[88:91], v[172:175], v[188:191], v[88:91]
	v_mfma_f32_16x16x32_bf16 v[76:79], v[164:167], v[198:201], v[76:79]
	v_mfma_f32_16x16x32_bf16 v[72:75], v[172:175], v[198:201], v[72:75]
	v_mfma_f32_16x16x32_bf16 v[68:71], v[164:167], v[206:209], v[68:71]
	v_mfma_f32_16x16x32_bf16 v[64:67], v[172:175], v[206:209], v[64:67]
	s_barrier
; #define PG8_STAGE(bufoff, gbase, voff) do { _Pragma("unroll") for (int _i = 0; _i < 2; ++_i) \
;         __builtin_amdgcn_global_load_lds((const unsigned*)((const char*)(gbase) + (voff)[_i]), (LAS unsigned*)(lds + (bufoff) + ldsw + _i * 8192), 16, 0, 0); } while (0)
; #define PG8_LDA(dst, b, h) do { _Pragma("unroll") for (int m = 0; m < 4; ++m) _Pragma("unroll") for (int k = 0; k < 2; ++k) dst[m][k] = *(const LAS bf16x8*)(lds + PG8_SA(b, h) + aoff + m * 2048 + k * 1024); } while (0)
; #define PG8_MMA(ai, bj, At, Bt) do { __builtin_amdgcn_s_setprio(1); _Pragma("unroll") for (int m = 0; m < 4; ++m) _Pragma("unroll") for (int n = 0; n < 2; ++n) _Pragma("unroll") for (int k = 0; k < 2; ++k) \
;         acc[ai][bj][m][n] = __builtin_amdgcn_mfma_f32_16x16x32_bf16(Bt[n][k], At[m][k], acc[ai][bj][m][n], 0, 0, 0); __builtin_amdgcn_s_setprio(0); } while (0)
; #define PG8_WAIT_V(n) asm volatile("s_waitcnt vmcnt(" #n ")" ::: "memory")
; #define PG8_WAIT_L(n) asm volatile("s_waitcnt lgkmcnt(" #n ")" ::: "memory")
; #define PG8_BAR __builtin_amdgcn_s_barrier()
; #define PG8_SCHED __builtin_amdgcn_sched_barrier(0)
; template <class Epi>
; DI void gemm_phase(int wv, LAS unsigned char* lds, LAS unsigned char* scr, const Sched& S, const Epi& E) {
;     ...
;             PG8_LDA(At, 1, 1); PG8_STAGE(PG8_SB(1, 0), b3, voffB); PG8_STAGE(PG8_SB(1, 1), b3 + hstepB, voffB); PG8_STAGE(PG8_SA(1, 0), a3, voffA);
;             PG8_WAIT_V(8); PG8_WAIT_L(0); PG8_BAR; PG8_MMA(1, 0, At, B0); PG8_MMA(1, 1, At, B1); PG8_BAR; PG8_SCHED;
;         }
;         if (wr == 0) PG8_BAR;
	s_add_i32 s28, s59, s33
	v_lshl_add_u64 v[210:211], v[210:211], 0, s[2:3]
	s_mov_b32 m0, s28
	ds_read_b128 v[176:179], v142 offset:49152
	ds_read_b128 v[180:183], v142 offset:50176
	ds_read_b128 v[184:187], v142 offset:51200
	ds_read_b128 v[188:191], v142 offset:52224
	ds_read_b128 v[194:197], v142 offset:53248
	ds_read_b128 v[198:201], v142 offset:54272
	ds_read_b128 v[202:205], v142 offset:55296
	ds_read_b128 v[206:209], v142 offset:56320
	global_load_lds_dwordx4 v[210:211], off
	s_add_i32 m0, s28, 0x2000
	s_add_u32 s26, s26, 0x400080
	v_lshl_add_u64 v[210:211], v[212:213], 0, s[2:3]
	s_addc_u32 s27, s27, 0
	s_add_i32 s28, s60, s33
	global_load_lds_dwordx4 v[210:211], off
	v_lshl_add_u64 v[210:211], s[26:27], 0, v[192:193]
	s_mov_b32 m0, s28
	s_nop 0
	global_load_lds_dwordx4 v[210:211], off
	v_lshl_add_u64 v[210:211], s[26:27], 0, v[132:133]
	s_add_i32 m0, s28, 0x2000
	s_nop 0
	global_load_lds_dwordx4 v[210:211], off
	v_lshl_add_u64 v[210:211], v[214:215], 0, s[2:3]
	s_mov_b32 m0, s43
	s_nop 0
	global_load_lds_dwordx4 v[210:211], off
	v_lshl_add_u64 v[210:211], v[216:217], 0, s[2:3]
	s_mov_b32 m0, s44
	s_nop 0
	global_load_lds_dwordx4 v[210:211], off
	s_waitcnt vmcnt(8)
	s_waitcnt lgkmcnt(0)
	s_barrier
	v_mfma_f32_16x16x32_bf16 v[60:63], v[144:147], v[176:179], v[60:63]
	v_mfma_f32_16x16x32_bf16 v[56:59], v[152:155], v[176:179], v[56:59]
	v_mfma_f32_16x16x32_bf16 v[52:55], v[144:147], v[184:187], v[52:55]
	v_mfma_f32_16x16x32_bf16 v[48:51], v[152:155], v[184:187], v[48:51]
	v_mfma_f32_16x16x32_bf16 v[36:39], v[144:147], v[194:197], v[36:39]
	v_mfma_f32_16x16x32_bf16 v[32:35], v[152:155], v[194:197], v[32:35]
	v_mfma_f32_16x16x32_bf16 v[20:23], v[144:147], v[202:205], v[20:23]
	v_mfma_f32_16x16x32_bf16 v[16:19], v[152:155], v[202:205], v[16:19]
	v_mfma_f32_16x16x32_bf16 v[60:63], v[148:151], v[180:183], v[60:63]
	v_mfma_f32_16x16x32_bf16 v[56:59], v[156:159], v[180:183], v[56:59]
	v_mfma_f32_16x16x32_bf16 v[52:55], v[148:151], v[188:191], v[52:55]
	v_mfma_f32_16x16x32_bf16 v[48:51], v[156:159], v[188:191], v[48:51]
	v_mfma_f32_16x16x32_bf16 v[36:39], v[148:151], v[198:201], v[36:39]
	v_mfma_f32_16x16x32_bf16 v[32:35], v[156:159], v[198:201], v[32:35]
	v_mfma_f32_16x16x32_bf16 v[20:23], v[148:151], v[206:209], v[20:23]
	v_mfma_f32_16x16x32_bf16 v[16:19], v[156:159], v[206:209], v[16:19]
	v_mfma_f32_16x16x32_bf16 v[44:47], v[160:163], v[176:179], v[44:47]
	v_mfma_f32_16x16x32_bf16 v[40:43], v[168:171], v[176:179], v[40:43]
	v_mfma_f32_16x16x32_bf16 v[28:31], v[160:163], v[184:187], v[28:31]
	v_mfma_f32_16x16x32_bf16 v[24:27], v[168:171], v[184:187], v[24:27]
	v_mfma_f32_16x16x32_bf16 v[12:15], v[160:163], v[194:197], v[12:15]
	v_mfma_f32_16x16x32_bf16 v[8:11], v[168:171], v[194:197], v[8:11]
	v_mfma_f32_16x16x32_bf16 v[4:7], v[160:163], v[202:205], v[4:7]
	v_mfma_f32_16x16x32_bf16 v[0:3], v[168:171], v[202:205], v[0:3]
	v_mfma_f32_16x16x32_bf16 v[44:47], v[164:167], v[180:183], v[44:47]
	v_mfma_f32_16x16x32_bf16 v[40:43], v[172:175], v[180:183], v[40:43]
	v_mfma_f32_16x16x32_bf16 v[28:31], v[164:167], v[188:191], v[28:31]
	v_mfma_f32_16x16x32_bf16 v[24:27], v[172:175], v[188:191], v[24:27]
	v_mfma_f32_16x16x32_bf16 v[12:15], v[164:167], v[198:201], v[12:15]
	v_mfma_f32_16x16x32_bf16 v[8:11], v[172:175], v[198:201], v[8:11]
	v_mfma_f32_16x16x32_bf16 v[4:7], v[164:167], v[206:209], v[4:7]
	v_mfma_f32_16x16x32_bf16 v[0:3], v[172:175], v[206:209], v[0:3]
	s_barrier
	s_add_i32 s55, s55, 2
	s_add_u32 s51, s51, 0x100
	s_addc_u32 s54, s54, 0
	s_add_u32 s6, s6, 0x100
	s_addc_u32 s7, s7, 0
	s_cmp_gt_u32 s55, 13
	s_cbranch_scc0 .LBB0_189
	s_and_b64 vcc, exec, s[18:19]
	s_cbranch_vccz .LBB0_192
	s_barrier

; #define PG8_STAGE(bufoff, gbase, voff) do { _Pragma("unroll") for (int _i = 0; _i < 2; ++_i) \
;         __builtin_amdgcn_global_load_lds((const unsigned*)((const char*)(gbase) + (voff)[_i]), (LAS unsigned*)(lds + (bufoff) + ldsw + _i * 8192), 16, 0, 0); } while (0)
; #define PG8_LDA(dst, b, h) do { _Pragma("unroll") for (int m = 0; m < 4; ++m) _Pragma("unroll") for (int k = 0; k < 2; ++k) dst[m][k] = *(const LAS bf16x8*)(lds + PG8_SA(b, h) + aoff + m * 2048 + k * 1024); } while (0)
; #define PG8_LDB(dst, b, h) do { _Pragma("unroll") for (int n = 0; n < 2; ++n) _Pragma("unroll") for (int k = 0; k < 2; ++k) dst[n][k] = *(const LAS bf16x8*)(lds + PG8_SB(b, h) + boff + n * 2048 + k * 1024); } while (0)
; #define PG8_MMA(ai, bj, At, Bt) do { __builtin_amdgcn_s_setprio(1); _Pragma("unroll") for (int m = 0; m < 4; ++m) _Pragma("unroll") for (int n = 0; n < 2; ++n) _Pragma("unroll") for (int k = 0; k < 2; ++k) \
;         acc[ai][bj][m][n] = __builtin_amdgcn_mfma_f32_16x16x32_bf16(Bt[n][k], At[m][k], acc[ai][bj][m][n], 0, 0, 0); __builtin_amdgcn_s_setprio(0); } while (0)
; #define PG8_WAIT_V(n) asm volatile("s_waitcnt vmcnt(" #n ")" ::: "memory")
; #define PG8_WAIT_L(n) asm volatile("s_waitcnt lgkmcnt(" #n ")" ::: "memory")
; #define PG8_BAR __builtin_amdgcn_s_barrier()
; #define PG8_SCHED __builtin_amdgcn_sched_barrier(0)
; template <class Epi>
; DI void gemm_phase(int wv, LAS unsigned char* lds, LAS unsigned char* scr, const Sched& S, const Epi& E) {
;     ...
;         for (int t = 0; t < nt; t += 2) {
;             const bool last = (t == nt - 2);
;             const char* a1 = cA + (size_t)(t + 1) * kstep;
;             const char* a2 = last ? nA : cA + (size_t)(t + 2) * kstep; const char* b2 = last ? nB : cB + (size_t)(t + 2) * kstep;
;             const char* a3 = a2 + kstep; const char* b3 = b2 + kstep;
;             PG8_LDB(B0, 0, 0); PG8_LDB(B1, 0, 1); PG8_SCHED; PG8_LDA(At, 0, 0); PG8_STAGE(PG8_SA(1, 1), a1 + hstepA, voffA);
;             PG8_WAIT_V(8); PG8_WAIT_L(0); PG8_BAR; PG8_MMA(0, 0, At, B0); PG8_MMA(0, 1, At, B1); PG8_BAR; PG8_SCHED;
;             PG8_LDA(At, 0, 1); PG8_STAGE(PG8_SB(0, 0), b2, voffB); PG8_STAGE(PG8_SB(0, 1), b2 + hstepB, voffB); PG8_STAGE(PG8_SA(0, 0), a2, voffA);
.LBB0_256:
	s_add_u32 s21, s16, s13
	s_addc_u32 s23, s17, 0
	s_add_u32 s30, s21, 0x100
	s_addc_u32 s31, s23, 0
	s_and_b64 s[28:29], s[26:27], exec
	s_cselect_b32 s31, s9, s31
	s_cselect_b32 s30, s8, s30
	s_add_u32 s13, s18, s13
	s_addc_u32 s28, s19, 0
	s_add_u32 s13, s13, 0x100
	s_addc_u32 s28, s28, 0
	s_add_i32 s64, 0, 0x10000
	s_and_b64 s[26:27], s[26:27], exec
	s_cselect_b32 s35, s15, s28
	s_cselect_b32 s34, s14, s13
	s_add_i32 s27, 0, 0x14000
	s_add_u32 s38, s21, 0x40080
	s_addc_u32 s39, s23, 0
	s_add_i32 s63, s64, s45
	s_add_i32 m0, s46, 0xc000
	s_add_i32 s66, s46, 0xe000
	s_add_i32 s60, s63, 0x2000
	v_add_u32_e32 v138, s64, v140
	s_add_u32 s36, s34, 0x40000
	ds_read_b128 v[142:145], v138
	ds_read_b128 v[146:149], v138 offset:1024
	ds_read_b128 v[150:153], v138 offset:2048
	ds_read_b128 v[154:157], v138 offset:3072
	v_add_u32_e32 v138, s27, v140
	s_addc_u32 s37, s35, 0
	s_add_i32 s62, s27, s45
	ds_read_b128 v[158:161], v138
	ds_read_b128 v[162:165], v138 offset:1024
	ds_read_b128 v[166:169], v138 offset:2048
	ds_read_b128 v[170:173], v138 offset:3072
	s_add_i32 s61, s62, 0x2000
	s_add_i32 s59, 0, 0x18000
	s_add_i32 s23, 0, 0x1c000
	s_add_u32 s28, s30, 0x40000
	s_addc_u32 s29, s31, 0
	s_add_i32 s21, s59, s45
	s_add_i32 s13, s21, 0x2000
	s_add_u32 s26, s34, 0x40080
	s_addc_u32 s27, s35, 0
	s_add_i32 s65, s23, s45
	s_add_i32 s64, s65, 0x2000
	v_lshl_add_u64 v[138:139], s[38:39], 0, v[134:135]
	ds_read_b128 v[174:177], v141
	ds_read_b128 v[178:181], v141 offset:1024
	ds_read_b128 v[182:185], v141 offset:2048
	ds_read_b128 v[186:189], v141 offset:3072
	ds_read_b128 v[194:197], v141 offset:4096
	ds_read_b128 v[198:201], v141 offset:5120
	ds_read_b128 v[202:205], v141 offset:6144
	ds_read_b128 v[206:209], v141 offset:7168
	global_load_lds_dwordx4 v[138:139], off
	v_lshl_add_u64 v[138:139], s[38:39], 0, v[130:131]
	s_mov_b32 m0, s66
	s_nop 0
	global_load_lds_dwordx4 v[138:139], off
	s_waitcnt vmcnt(8)
	s_waitcnt lgkmcnt(0)
	s_barrier
	v_mfma_f32_16x16x32_bf16 v[124:127], v[142:145], v[174:177], v[124:127]
	v_mfma_f32_16x16x32_bf16 v[120:123], v[150:153], v[174:177], v[120:123]
	v_mfma_f32_16x16x32_bf16 v[116:119], v[142:145], v[182:185], v[116:119]
	v_mfma_f32_16x16x32_bf16 v[108:111], v[150:153], v[182:185], v[108:111]
	v_mfma_f32_16x16x32_bf16 v[100:103], v[142:145], v[194:197], v[100:103]
	v_mfma_f32_16x16x32_bf16 v[92:95], v[150:153], v[194:197], v[92:95]
	v_mfma_f32_16x16x32_bf16 v[84:87], v[142:145], v[202:205], v[84:87]
	v_mfma_f32_16x16x32_bf16 v[76:79], v[150:153], v[202:205], v[76:79]
	v_mfma_f32_16x16x32_bf16 v[124:127], v[146:149], v[178:181], v[124:127]
	v_mfma_f32_16x16x32_bf16 v[120:123], v[154:157], v[178:181], v[120:123]
	v_mfma_f32_16x16x32_bf16 v[116:119], v[146:149], v[186:189], v[116:119]
	v_mfma_f32_16x16x32_bf16 v[108:111], v[154:157], v[186:189], v[108:111]
	v_mfma_f32_16x16x32_bf16 v[100:103], v[146:149], v[198:201], v[100:103]
	v_mfma_f32_16x16x32_bf16 v[92:95], v[154:157], v[198:201], v[92:95]
	v_mfma_f32_16x16x32_bf16 v[84:87], v[146:149], v[206:209], v[84:87]
	v_mfma_f32_16x16x32_bf16 v[76:79], v[154:157], v[206:209], v[76:79]
	v_mfma_f32_16x16x32_bf16 v[112:115], v[158:161], v[174:177], v[112:115]
	v_mfma_f32_16x16x32_bf16 v[104:107], v[166:169], v[174:177], v[104:107]
	v_mfma_f32_16x16x32_bf16 v[96:99], v[158:161], v[182:185], v[96:99]
	v_mfma_f32_16x16x32_bf16 v[88:91], v[166:169], v[182:185], v[88:91]
	v_mfma_f32_16x16x32_bf16 v[80:83], v[158:161], v[194:197], v[80:83]
	v_mfma_f32_16x16x32_bf16 v[72:75], v[166:169], v[194:197], v[72:75]
	v_mfma_f32_16x16x32_bf16 v[68:71], v[158:161], v[202:205], v[68:71]
	v_mfma_f32_16x16x32_bf16 v[64:67], v[166:169], v[202:205], v[64:67]
	v_mfma_f32_16x16x32_bf16 v[112:115], v[162:165], v[178:181], v[112:115]
	v_mfma_f32_16x16x32_bf16 v[104:107], v[170:173], v[178:181], v[104:107]
	v_mfma_f32_16x16x32_bf16 v[96:99], v[162:165], v[186:189], v[96:99]
	v_mfma_f32_16x16x32_bf16 v[88:91], v[170:173], v[186:189], v[88:91]
	v_mfma_f32_16x16x32_bf16 v[80:83], v[162:165], v[198:201], v[80:83]
	v_mfma_f32_16x16x32_bf16 v[72:75], v[170:173], v[198:201], v[72:75]
	v_mfma_f32_16x16x32_bf16 v[68:71], v[162:165], v[206:209], v[68:71]
	v_mfma_f32_16x16x32_bf16 v[64:67], v[170:173], v[206:209], v[64:67]
	s_barrier
	s_mov_b32 m0, s63
	v_lshl_add_u64 v[138:139], s[34:35], 0, v[132:133]
	ds_read_b128 v[174:177], v141 offset:16384
	ds_read_b128 v[178:181], v141 offset:17408
	ds_read_b128 v[182:185], v141 offset:18432
	ds_read_b128 v[186:189], v141 offset:19456
	ds_read_b128 v[194:197], v141 offset:20480
	ds_read_b128 v[198:201], v141 offset:21504
	ds_read_b128 v[202:205], v141 offset:22528
	ds_read_b128 v[206:209], v141 offset:23552
	global_load_lds_dwordx4 v[138:139], off
	v_lshl_add_u64 v[190:191], s[34:35], 0, v[128:129]
	s_mov_b32 m0, s60
	v_lshl_add_u64 v[210:211], s[36:37], 0, v[132:133]
	global_load_lds_dwordx4 v[190:191], off
	s_mov_b32 m0, s62
	v_lshl_add_u64 v[212:213], s[30:31], 0, v[130:131]
	global_load_lds_dwordx4 v[210:211], off
	v_lshl_add_u64 v[210:211], s[36:37], 0, v[128:129]
	s_mov_b32 m0, s61
	s_nop 0
	global_load_lds_dwordx4 v[210:211], off
	v_lshl_add_u64 v[210:211], s[30:31], 0, v[134:135]
	s_mov_b32 m0, s46
	s_nop 0
	global_load_lds_dwordx4 v[210:211], off
	s_mov_b32 m0, s47
	s_nop 0
	global_load_lds_dwordx4 v[212:213], off
	s_waitcnt vmcnt(8)
	s_waitcnt lgkmcnt(0)
	s_barrier
; #define PG8_STAGE(bufoff, gbase, voff) do { _Pragma("unroll") for (int _i = 0; _i < 2; ++_i) \
;         __builtin_amdgcn_global_load_lds((const unsigned*)((const char*)(gbase) + (voff)[_i]), (LAS unsigned*)(lds + (bufoff) + ldsw + _i * 8192), 16, 0, 0); } while (0)
; #define PG8_LDA(dst, b, h) do { _Pragma("unroll") for (int m = 0; m < 4; ++m) _Pragma("unroll") for (int k = 0; k < 2; ++k) dst[m][k] = *(const LAS bf16x8*)(lds + PG8_SA(b, h) + aoff + m * 2048 + k * 1024); } while (0)
; #define PG8_LDB(dst, b, h) do { _Pragma("unroll") for (int n = 0; n < 2; ++n) _Pragma("unroll") for (int k = 0; k < 2; ++k) dst[n][k] = *(const LAS bf16x8*)(lds + PG8_SB(b, h) + boff + n * 2048 + k * 1024); } while (0)
; #define PG8_MMA(ai, bj, At, Bt) do { __builtin_amdgcn_s_setprio(1); _Pragma("unroll") for (int m = 0; m < 4; ++m) _Pragma("unroll") for (int n = 0; n < 2; ++n) _Pragma("unroll") for (int k = 0; k < 2; ++k) \
;         acc[ai][bj][m][n] = __builtin_amdgcn_mfma_f32_16x16x32_bf16(Bt[n][k], At[m][k], acc[ai][bj][m][n], 0, 0, 0); __builtin_amdgcn_s_setprio(0); } while (0)
; #define PG8_WAIT_V(n) asm volatile("s_waitcnt vmcnt(" #n ")" ::: "memory")
; #define PG8_WAIT_L(n) asm volatile("s_waitcnt lgkmcnt(" #n ")" ::: "memory")
; #define PG8_BAR __builtin_amdgcn_s_barrier()
; #define PG8_SCHED __builtin_amdgcn_sched_barrier(0)
; template <class Epi>
; DI void gemm_phase(int wv, LAS unsigned char* lds, LAS unsigned char* scr, const Sched& S, const Epi& E) {
;     ...
;             PG8_WAIT_V(8); PG8_WAIT_L(0); PG8_BAR; PG8_MMA(1, 0, At, B0); PG8_MMA(1, 1, At, B1); PG8_BAR; PG8_SCHED;
;             PG8_LDB(B0, 1, 0); PG8_LDB(B1, 1, 1); PG8_SCHED; PG8_LDA(At, 1, 0); PG8_STAGE(PG8_SA(0, 1), a2 + hstepA, voffA);
;             PG8_WAIT_V(8); PG8_WAIT_L(0); PG8_BAR; PG8_MMA(0, 0, At, B0); PG8_MMA(0, 1, At, B1); PG8_BAR; PG8_SCHED;
	v_mfma_f32_16x16x32_bf16 v[60:63], v[142:145], v[174:177], v[60:63]
	v_mfma_f32_16x16x32_bf16 v[56:59], v[150:153], v[174:177], v[56:59]
	v_mfma_f32_16x16x32_bf16 v[52:55], v[142:145], v[182:185], v[52:55]
	v_mfma_f32_16x16x32_bf16 v[44:47], v[150:153], v[182:185], v[44:47]
	v_mfma_f32_16x16x32_bf16 v[36:39], v[142:145], v[194:197], v[36:39]
	v_mfma_f32_16x16x32_bf16 v[28:31], v[150:153], v[194:197], v[28:31]
	v_mfma_f32_16x16x32_bf16 v[20:23], v[142:145], v[202:205], v[20:23]
	v_mfma_f32_16x16x32_bf16 v[12:15], v[150:153], v[202:205], v[12:15]
	v_mfma_f32_16x16x32_bf16 v[60:63], v[146:149], v[178:181], v[60:63]
	v_mfma_f32_16x16x32_bf16 v[56:59], v[154:157], v[178:181], v[56:59]
	v_mfma_f32_16x16x32_bf16 v[52:55], v[146:149], v[186:189], v[52:55]
	v_mfma_f32_16x16x32_bf16 v[44:47], v[154:157], v[186:189], v[44:47]
	v_mfma_f32_16x16x32_bf16 v[36:39], v[146:149], v[198:201], v[36:39]
	v_mfma_f32_16x16x32_bf16 v[28:31], v[154:157], v[198:201], v[28:31]
	v_mfma_f32_16x16x32_bf16 v[20:23], v[146:149], v[206:209], v[20:23]
	v_mfma_f32_16x16x32_bf16 v[12:15], v[154:157], v[206:209], v[12:15]
	v_mfma_f32_16x16x32_bf16 v[48:51], v[158:161], v[174:177], v[48:51]
	v_mfma_f32_16x16x32_bf16 v[40:43], v[166:169], v[174:177], v[40:43]
	v_mfma_f32_16x16x32_bf16 v[32:35], v[158:161], v[182:185], v[32:35]
	v_mfma_f32_16x16x32_bf16 v[24:27], v[166:169], v[182:185], v[24:27]
	v_mfma_f32_16x16x32_bf16 v[16:19], v[158:161], v[194:197], v[16:19]
	v_mfma_f32_16x16x32_bf16 v[8:11], v[166:169], v[194:197], v[8:11]
	v_mfma_f32_16x16x32_bf16 v[4:7], v[158:161], v[202:205], v[4:7]
	v_mfma_f32_16x16x32_bf16 v[0:3], v[166:169], v[202:205], v[0:3]
	v_mfma_f32_16x16x32_bf16 v[48:51], v[162:165], v[178:181], v[48:51]
	v_mfma_f32_16x16x32_bf16 v[40:43], v[170:173], v[178:181], v[40:43]
	v_mfma_f32_16x16x32_bf16 v[32:35], v[162:165], v[186:189], v[32:35]
	v_mfma_f32_16x16x32_bf16 v[24:27], v[170:173], v[186:189], v[24:27]
	v_mfma_f32_16x16x32_bf16 v[16:19], v[162:165], v[198:201], v[16:19]
	v_mfma_f32_16x16x32_bf16 v[8:11], v[170:173], v[198:201], v[8:11]
	v_mfma_f32_16x16x32_bf16 v[4:7], v[162:165], v[206:209], v[4:7]
	v_mfma_f32_16x16x32_bf16 v[0:3], v[170:173], v[206:209], v[0:3]
	s_barrier
	v_add_u32_e32 v154, s59, v140
	v_add_u32_e32 v170, s23, v140
	ds_read_b128 v[142:145], v154
	ds_read_b128 v[146:149], v154 offset:1024
	ds_read_b128 v[150:153], v154 offset:2048
	ds_read_b128 v[154:157], v154 offset:3072
	ds_read_b128 v[158:161], v170
	ds_read_b128 v[162:165], v170 offset:1024
	ds_read_b128 v[166:169], v170 offset:2048
	ds_read_b128 v[170:173], v170 offset:3072
	s_mov_b32 m0, s48
	v_lshl_add_u64 v[214:215], s[28:29], 0, v[134:135]
	ds_read_b128 v[174:177], v141 offset:32768
	ds_read_b128 v[178:181], v141 offset:33792
	ds_read_b128 v[182:185], v141 offset:34816
	ds_read_b128 v[186:189], v141 offset:35840
	ds_read_b128 v[194:197], v141 offset:36864
	ds_read_b128 v[198:201], v141 offset:37888
	ds_read_b128 v[202:205], v141 offset:38912
	ds_read_b128 v[206:209], v141 offset:39936
	global_load_lds_dwordx4 v[214:215], off
	v_lshl_add_u64 v[214:215], s[28:29], 0, v[130:131]
	s_mov_b32 m0, s49
	s_nop 0
	global_load_lds_dwordx4 v[214:215], off
	s_waitcnt vmcnt(8)
	s_waitcnt lgkmcnt(0)
	s_barrier
	v_mfma_f32_16x16x32_bf16 v[124:127], v[142:145], v[174:177], v[124:127]
	v_mfma_f32_16x16x32_bf16 v[120:123], v[150:153], v[174:177], v[120:123]
	v_mfma_f32_16x16x32_bf16 v[116:119], v[142:145], v[182:185], v[116:119]
	v_mfma_f32_16x16x32_bf16 v[108:111], v[150:153], v[182:185], v[108:111]
	v_mfma_f32_16x16x32_bf16 v[100:103], v[142:145], v[194:197], v[100:103]
	v_mfma_f32_16x16x32_bf16 v[92:95], v[150:153], v[194:197], v[92:95]
	v_mfma_f32_16x16x32_bf16 v[84:87], v[142:145], v[202:205], v[84:87]
	v_mfma_f32_16x16x32_bf16 v[76:79], v[150:153], v[202:205], v[76:79]
	v_mfma_f32_16x16x32_bf16 v[124:127], v[146:149], v[178:181], v[124:127]
	v_mfma_f32_16x16x32_bf16 v[120:123], v[154:157], v[178:181], v[120:123]
	v_mfma_f32_16x16x32_bf16 v[116:119], v[146:149], v[186:189], v[116:119]
	v_mfma_f32_16x16x32_bf16 v[108:111], v[154:157], v[186:189], v[108:111]
	v_mfma_f32_16x16x32_bf16 v[100:103], v[146:149], v[198:201], v[100:103]
	v_mfma_f32_16x16x32_bf16 v[92:95], v[154:157], v[198:201], v[92:95]
	v_mfma_f32_16x16x32_bf16 v[84:87], v[146:149], v[206:209], v[84:87]
	v_mfma_f32_16x16x32_bf16 v[76:79], v[154:157], v[206:209], v[76:79]
	v_mfma_f32_16x16x32_bf16 v[112:115], v[158:161], v[174:177], v[112:115]
	v_mfma_f32_16x16x32_bf16 v[104:107], v[166:169], v[174:177], v[104:107]
	v_mfma_f32_16x16x32_bf16 v[96:99], v[158:161], v[182:185], v[96:99]
	v_mfma_f32_16x16x32_bf16 v[88:91], v[166:169], v[182:185], v[88:91]
	v_mfma_f32_16x16x32_bf16 v[80:83], v[158:161], v[194:197], v[80:83]
	v_mfma_f32_16x16x32_bf16 v[72:75], v[166:169], v[194:197], v[72:75]
	v_mfma_f32_16x16x32_bf16 v[68:71], v[158:161], v[202:205], v[68:71]
	v_mfma_f32_16x16x32_bf16 v[64:67], v[166:169], v[202:205], v[64:67]
	v_mfma_f32_16x16x32_bf16 v[112:115], v[162:165], v[178:181], v[112:115]
	v_mfma_f32_16x16x32_bf16 v[104:107], v[170:173], v[178:181], v[104:107]
	v_mfma_f32_16x16x32_bf16 v[96:99], v[162:165], v[186:189], v[96:99]
	v_mfma_f32_16x16x32_bf16 v[88:91], v[170:173], v[186:189], v[88:91]
	v_mfma_f32_16x16x32_bf16 v[80:83], v[162:165], v[198:201], v[80:83]
	v_mfma_f32_16x16x32_bf16 v[72:75], v[170:173], v[198:201], v[72:75]
	v_mfma_f32_16x16x32_bf16 v[68:71], v[162:165], v[206:209], v[68:71]
	v_mfma_f32_16x16x32_bf16 v[64:67], v[170:173], v[206:209], v[64:67]
	s_barrier
; #define PG8_STAGE(bufoff, gbase, voff) do { _Pragma("unroll") for (int _i = 0; _i < 2; ++_i) \
;         __builtin_amdgcn_global_load_lds((const unsigned*)((const char*)(gbase) + (voff)[_i]), (LAS unsigned*)(lds + (bufoff) + ldsw + _i * 8192), 16, 0, 0); } while (0)
; #define PG8_LDA(dst, b, h) do { _Pragma("unroll") for (int m = 0; m < 4; ++m) _Pragma("unroll") for (int k = 0; k < 2; ++k) dst[m][k] = *(const LAS bf16x8*)(lds + PG8_SA(b, h) + aoff + m * 2048 + k * 1024); } while (0)
; #define PG8_MMA(ai, bj, At, Bt) do { __builtin_amdgcn_s_setprio(1); _Pragma("unroll") for (int m = 0; m < 4; ++m) _Pragma("unroll") for (int n = 0; n < 2; ++n) _Pragma("unroll") for (int k = 0; k < 2; ++k) \
;         acc[ai][bj][m][n] = __builtin_amdgcn_mfma_f32_16x16x32_bf16(Bt[n][k], At[m][k], acc[ai][bj][m][n], 0, 0, 0); __builtin_amdgcn_s_setprio(0); } while (0)
; #define PG8_WAIT_V(n) asm volatile("s_waitcnt vmcnt(" #n ")" ::: "memory")
; #define PG8_WAIT_L(n) asm volatile("s_waitcnt lgkmcnt(" #n ")" ::: "memory")
; #define PG8_BAR __builtin_amdgcn_s_barrier()
; #define PG8_SCHED __builtin_amdgcn_sched_barrier(0)
; template <class Epi>
; DI void gemm_phase(int wv, LAS unsigned char* lds, LAS unsigned char* scr, const Sched& S, const Epi& E) {
;     ...
;             PG8_LDA(At, 1, 1); PG8_STAGE(PG8_SB(1, 0), b3, voffB); PG8_STAGE(PG8_SB(1, 1), b3 + hstepB, voffB); PG8_STAGE(PG8_SA(1, 0), a3, voffA);
;             PG8_WAIT_V(8); PG8_WAIT_L(0); PG8_BAR; PG8_MMA(1, 0, At, B0); PG8_MMA(1, 1, At, B1); PG8_BAR; PG8_SCHED;
;         }
;         if (wr == 0) PG8_BAR;
	s_mov_b32 m0, s21
	v_lshl_add_u64 v[138:139], v[138:139], 0, s[2:3]
	ds_read_b128 v[174:177], v141 offset:49152
	ds_read_b128 v[178:181], v141 offset:50176
	ds_read_b128 v[182:185], v141 offset:51200
	ds_read_b128 v[186:189], v141 offset:52224
	ds_read_b128 v[194:197], v141 offset:53248
	ds_read_b128 v[198:201], v141 offset:54272
	ds_read_b128 v[202:205], v141 offset:55296
	ds_read_b128 v[206:209], v141 offset:56320
	global_load_lds_dwordx4 v[138:139], off
	v_lshl_add_u64 v[138:139], v[190:191], 0, s[2:3]
	s_mov_b32 m0, s13
	s_nop 0
	global_load_lds_dwordx4 v[138:139], off
	v_lshl_add_u64 v[138:139], s[26:27], 0, v[132:133]
	s_mov_b32 m0, s65
	s_nop 0
	global_load_lds_dwordx4 v[138:139], off
	v_lshl_add_u64 v[138:139], s[26:27], 0, v[128:129]
	s_mov_b32 m0, s64
	s_nop 0
	global_load_lds_dwordx4 v[138:139], off
	v_lshl_add_u64 v[138:139], v[210:211], 0, s[2:3]
	s_mov_b32 m0, s52
	s_nop 0
	global_load_lds_dwordx4 v[138:139], off
	v_lshl_add_u64 v[138:139], v[212:213], 0, s[2:3]
	s_mov_b32 m0, s53
	s_nop 0
	global_load_lds_dwordx4 v[138:139], off
	s_waitcnt vmcnt(8)
	s_waitcnt lgkmcnt(0)
	s_barrier
	v_mfma_f32_16x16x32_bf16 v[60:63], v[142:145], v[174:177], v[60:63]
	v_mfma_f32_16x16x32_bf16 v[56:59], v[150:153], v[174:177], v[56:59]
	v_mfma_f32_16x16x32_bf16 v[52:55], v[142:145], v[182:185], v[52:55]
	v_mfma_f32_16x16x32_bf16 v[44:47], v[150:153], v[182:185], v[44:47]
	v_mfma_f32_16x16x32_bf16 v[36:39], v[142:145], v[194:197], v[36:39]
	v_mfma_f32_16x16x32_bf16 v[28:31], v[150:153], v[194:197], v[28:31]
	v_mfma_f32_16x16x32_bf16 v[20:23], v[142:145], v[202:205], v[20:23]
	v_mfma_f32_16x16x32_bf16 v[12:15], v[150:153], v[202:205], v[12:15]
	v_mfma_f32_16x16x32_bf16 v[60:63], v[146:149], v[178:181], v[60:63]
	v_mfma_f32_16x16x32_bf16 v[56:59], v[154:157], v[178:181], v[56:59]
	v_mfma_f32_16x16x32_bf16 v[52:55], v[146:149], v[186:189], v[52:55]
	v_mfma_f32_16x16x32_bf16 v[44:47], v[154:157], v[186:189], v[44:47]
	v_mfma_f32_16x16x32_bf16 v[36:39], v[146:149], v[198:201], v[36:39]
	v_mfma_f32_16x16x32_bf16 v[28:31], v[154:157], v[198:201], v[28:31]
	v_mfma_f32_16x16x32_bf16 v[20:23], v[146:149], v[206:209], v[20:23]
	v_mfma_f32_16x16x32_bf16 v[12:15], v[154:157], v[206:209], v[12:15]
	v_mfma_f32_16x16x32_bf16 v[48:51], v[158:161], v[174:177], v[48:51]
	v_mfma_f32_16x16x32_bf16 v[40:43], v[166:169], v[174:177], v[40:43]
	v_mfma_f32_16x16x32_bf16 v[32:35], v[158:161], v[182:185], v[32:35]
	v_mfma_f32_16x16x32_bf16 v[24:27], v[166:169], v[182:185], v[24:27]
	v_mfma_f32_16x16x32_bf16 v[16:19], v[158:161], v[194:197], v[16:19]
	v_mfma_f32_16x16x32_bf16 v[8:11], v[166:169], v[194:197], v[8:11]
	v_mfma_f32_16x16x32_bf16 v[4:7], v[158:161], v[202:205], v[4:7]
	v_mfma_f32_16x16x32_bf16 v[0:3], v[166:169], v[202:205], v[0:3]
	v_mfma_f32_16x16x32_bf16 v[48:51], v[162:165], v[178:181], v[48:51]
	v_mfma_f32_16x16x32_bf16 v[40:43], v[170:173], v[178:181], v[40:43]
	v_mfma_f32_16x16x32_bf16 v[32:35], v[162:165], v[186:189], v[32:35]
	v_mfma_f32_16x16x32_bf16 v[24:27], v[170:173], v[186:189], v[24:27]
	v_mfma_f32_16x16x32_bf16 v[16:19], v[162:165], v[198:201], v[16:19]
	v_mfma_f32_16x16x32_bf16 v[8:11], v[170:173], v[198:201], v[8:11]
	v_mfma_f32_16x16x32_bf16 v[4:7], v[162:165], v[206:209], v[4:7]
	v_mfma_f32_16x16x32_bf16 v[0:3], v[170:173], v[206:209], v[0:3]
	s_barrier
	s_movk_i32 s13, 0x100
	s_andn2_b64 vcc, exec, s[24:25]
	s_mov_b64 s[26:27], -1
	s_mov_b64 s[24:25], 0
	s_cbranch_vccz .LBB0_256
	s_and_b64 vcc, exec, s[10:11]
	s_cbranch_vccz .LBB0_259
	s_barrier

; #define PG8_STAGE(bufoff, gbase, voff) do { _Pragma("unroll") for (int _i = 0; _i < 2; ++_i) \
;         __builtin_amdgcn_global_load_lds((const unsigned*)((const char*)(gbase) + (voff)[_i]), (LAS unsigned*)(lds + (bufoff) + ldsw + _i * 8192), 16, 0, 0); } while (0)
; #define PG8_LDA(dst, b, h) do { _Pragma("unroll") for (int m = 0; m < 4; ++m) _Pragma("unroll") for (int k = 0; k < 2; ++k) dst[m][k] = *(const LAS bf16x8*)(lds + PG8_SA(b, h) + aoff + m * 2048 + k * 1024); } while (0)
; #define PG8_LDB(dst, b, h) do { _Pragma("unroll") for (int n = 0; n < 2; ++n) _Pragma("unroll") for (int k = 0; k < 2; ++k) dst[n][k] = *(const LAS bf16x8*)(lds + PG8_SB(b, h) + boff + n * 2048 + k * 1024); } while (0)
; #define PG8_MMA(ai, bj, At, Bt) do { __builtin_amdgcn_s_setprio(1); _Pragma("unroll") for (int m = 0; m < 4; ++m) _Pragma("unroll") for (int n = 0; n < 2; ++n) _Pragma("unroll") for (int k = 0; k < 2; ++k) \
;         acc[ai][bj][m][n] = __builtin_amdgcn_mfma_f32_16x16x32_bf16(Bt[n][k], At[m][k], acc[ai][bj][m][n], 0, 0, 0); __builtin_amdgcn_s_setprio(0); } while (0)
; #define PG8_WAIT_V(n) asm volatile("s_waitcnt vmcnt(" #n ")" ::: "memory")
; #define PG8_WAIT_L(n) asm volatile("s_waitcnt lgkmcnt(" #n ")" ::: "memory")
; #define PG8_BAR __builtin_amdgcn_s_barrier()
; #define PG8_SCHED __builtin_amdgcn_sched_barrier(0)
; template <class Epi>
; DI void gemm_phase(int wv, LAS unsigned char* lds, LAS unsigned char* scr, const Sched& S, const Epi& E) {
;     ...
;         for (int t = 0; t < nt; t += 2) {
;             const bool last = (t == nt - 2);
;             const char* a1 = cA + (size_t)(t + 1) * kstep;
;             const char* a2 = last ? nA : cA + (size_t)(t + 2) * kstep; const char* b2 = last ? nB : cB + (size_t)(t + 2) * kstep;
;             const char* a3 = a2 + kstep; const char* b3 = b2 + kstep;
;             PG8_LDB(B0, 0, 0); PG8_LDB(B1, 0, 1); PG8_SCHED; PG8_LDA(At, 0, 0); PG8_STAGE(PG8_SA(1, 1), a1 + hstepA, voffA);
;             PG8_WAIT_V(8); PG8_WAIT_L(0); PG8_BAR; PG8_MMA(0, 0, At, B0); PG8_MMA(0, 1, At, B1); PG8_BAR; PG8_SCHED;
;             PG8_LDA(At, 0, 1); PG8_STAGE(PG8_SB(0, 0), b2, voffB); PG8_STAGE(PG8_SB(0, 1), b2 + hstepB, voffB); PG8_STAGE(PG8_SA(0, 0), a2, voffA);
.LBB0_277:
	s_add_u32 s21, s14, s13
	s_addc_u32 s34, s15, 0
	s_add_u32 s28, s21, 0x100
	s_addc_u32 s29, s34, 0
	s_and_b64 s[26:27], s[24:25], exec
	s_cselect_b32 s29, s9, s29
	s_cselect_b32 s28, s8, s28
	s_add_u32 s13, s16, s13
	s_addc_u32 s26, s17, 0
	s_add_u32 s13, s13, 0x100
	s_addc_u32 s26, s26, 0
	s_add_i32 s64, 0, 0x10000
	s_and_b64 s[24:25], s[24:25], exec
	s_cselect_b32 s31, s19, s26
	s_cselect_b32 s30, s18, s13
	s_add_i32 s25, 0, 0x14000
	s_add_u32 s36, s21, 0x40080
	s_addc_u32 s37, s34, 0
	s_add_i32 s63, s64, s43
	s_add_i32 m0, s44, 0xc000
	s_add_i32 s66, s44, 0xe000
	s_add_i32 s60, s63, 0x2000
	s_add_u32 s34, s30, 0x40000
	v_add_u32_e32 v152, s64, v138
	v_add_u32_e32 v168, s25, v138
	s_addc_u32 s35, s31, 0
	s_add_i32 s62, s25, s43
	ds_read_b128 v[140:143], v152
	ds_read_b128 v[144:147], v152 offset:1024
	ds_read_b128 v[148:151], v152 offset:2048
	ds_read_b128 v[152:155], v152 offset:3072
	ds_read_b128 v[156:159], v168
	ds_read_b128 v[160:163], v168 offset:1024
	ds_read_b128 v[164:167], v168 offset:2048
	ds_read_b128 v[168:171], v168 offset:3072
	s_add_i32 s61, s62, 0x2000
	s_add_i32 s59, 0, 0x18000
	s_add_i32 s55, 0, 0x1c000
	s_add_u32 s26, s28, 0x40000
	s_addc_u32 s27, s29, 0
	s_add_i32 s21, s59, s43
	s_add_i32 s13, s21, 0x2000
	s_add_u32 s24, s30, 0x40080
	s_addc_u32 s25, s31, 0
	s_add_i32 s65, s55, s43
	s_add_i32 s64, s65, 0x2000
	v_lshl_add_u64 v[206:207], s[36:37], 0, v[134:135]
	ds_read_b128 v[172:175], v139
	ds_read_b128 v[176:179], v139 offset:1024
	ds_read_b128 v[180:183], v139 offset:2048
	ds_read_b128 v[184:187], v139 offset:3072
	ds_read_b128 v[188:191], v139 offset:4096
	ds_read_b128 v[194:197], v139 offset:5120
	ds_read_b128 v[198:201], v139 offset:6144
	ds_read_b128 v[202:205], v139 offset:7168
	global_load_lds_dwordx4 v[206:207], off
	v_lshl_add_u64 v[206:207], s[36:37], 0, v[130:131]
	s_mov_b32 m0, s66
	s_nop 0
	global_load_lds_dwordx4 v[206:207], off
	s_waitcnt vmcnt(8)
	s_waitcnt lgkmcnt(0)
	s_barrier
	v_mfma_f32_16x16x32_bf16 v[124:127], v[140:143], v[172:175], v[124:127]
	v_mfma_f32_16x16x32_bf16 v[120:123], v[148:151], v[172:175], v[120:123]
	v_mfma_f32_16x16x32_bf16 v[116:119], v[140:143], v[180:183], v[116:119]
	v_mfma_f32_16x16x32_bf16 v[112:115], v[148:151], v[180:183], v[112:115]
	v_mfma_f32_16x16x32_bf16 v[100:103], v[140:143], v[188:191], v[100:103]
	v_mfma_f32_16x16x32_bf16 v[96:99], v[148:151], v[188:191], v[96:99]
	v_mfma_f32_16x16x32_bf16 v[84:87], v[140:143], v[198:201], v[84:87]
	v_mfma_f32_16x16x32_bf16 v[80:83], v[148:151], v[198:201], v[80:83]
	v_mfma_f32_16x16x32_bf16 v[124:127], v[144:147], v[176:179], v[124:127]
	v_mfma_f32_16x16x32_bf16 v[120:123], v[152:155], v[176:179], v[120:123]
	v_mfma_f32_16x16x32_bf16 v[116:119], v[144:147], v[184:187], v[116:119]
	v_mfma_f32_16x16x32_bf16 v[112:115], v[152:155], v[184:187], v[112:115]
	v_mfma_f32_16x16x32_bf16 v[100:103], v[144:147], v[194:197], v[100:103]
	v_mfma_f32_16x16x32_bf16 v[96:99], v[152:155], v[194:197], v[96:99]
	v_mfma_f32_16x16x32_bf16 v[84:87], v[144:147], v[202:205], v[84:87]
	v_mfma_f32_16x16x32_bf16 v[80:83], v[152:155], v[202:205], v[80:83]
	v_mfma_f32_16x16x32_bf16 v[108:111], v[156:159], v[172:175], v[108:111]
	v_mfma_f32_16x16x32_bf16 v[104:107], v[164:167], v[172:175], v[104:107]
	v_mfma_f32_16x16x32_bf16 v[92:95], v[156:159], v[180:183], v[92:95]
	v_mfma_f32_16x16x32_bf16 v[88:91], v[164:167], v[180:183], v[88:91]
	v_mfma_f32_16x16x32_bf16 v[76:79], v[156:159], v[188:191], v[76:79]
	v_mfma_f32_16x16x32_bf16 v[72:75], v[164:167], v[188:191], v[72:75]
	v_mfma_f32_16x16x32_bf16 v[68:71], v[156:159], v[198:201], v[68:71]
	v_mfma_f32_16x16x32_bf16 v[64:67], v[164:167], v[198:201], v[64:67]
	v_mfma_f32_16x16x32_bf16 v[108:111], v[160:163], v[176:179], v[108:111]
	v_mfma_f32_16x16x32_bf16 v[104:107], v[168:171], v[176:179], v[104:107]
	v_mfma_f32_16x16x32_bf16 v[92:95], v[160:163], v[184:187], v[92:95]
	v_mfma_f32_16x16x32_bf16 v[88:91], v[168:171], v[184:187], v[88:91]
	v_mfma_f32_16x16x32_bf16 v[76:79], v[160:163], v[194:197], v[76:79]
	v_mfma_f32_16x16x32_bf16 v[72:75], v[168:171], v[194:197], v[72:75]
	v_mfma_f32_16x16x32_bf16 v[68:71], v[160:163], v[202:205], v[68:71]
	v_mfma_f32_16x16x32_bf16 v[64:67], v[168:171], v[202:205], v[64:67]
	s_barrier
	s_mov_b32 m0, s63
	v_lshl_add_u64 v[206:207], s[30:31], 0, v[132:133]
	ds_read_b128 v[172:175], v139 offset:16384
	ds_read_b128 v[176:179], v139 offset:17408
	ds_read_b128 v[180:183], v139 offset:18432
	ds_read_b128 v[184:187], v139 offset:19456
	ds_read_b128 v[188:191], v139 offset:20480
	ds_read_b128 v[194:197], v139 offset:21504
	ds_read_b128 v[198:201], v139 offset:22528
	ds_read_b128 v[202:205], v139 offset:23552
	global_load_lds_dwordx4 v[206:207], off
	v_lshl_add_u64 v[208:209], s[30:31], 0, v[128:129]
	s_mov_b32 m0, s60
	v_lshl_add_u64 v[210:211], s[34:35], 0, v[132:133]
	global_load_lds_dwordx4 v[208:209], off
	s_mov_b32 m0, s62
	v_lshl_add_u64 v[212:213], s[28:29], 0, v[130:131]
	global_load_lds_dwordx4 v[210:211], off
	v_lshl_add_u64 v[210:211], s[34:35], 0, v[128:129]
	s_mov_b32 m0, s61
	s_nop 0
	global_load_lds_dwordx4 v[210:211], off
	v_lshl_add_u64 v[210:211], s[28:29], 0, v[134:135]
	s_mov_b32 m0, s44
	s_nop 0
	global_load_lds_dwordx4 v[210:211], off
	s_mov_b32 m0, s45
	s_nop 0
	global_load_lds_dwordx4 v[212:213], off
	s_waitcnt vmcnt(8)
	s_waitcnt lgkmcnt(0)
	s_barrier
; #define PG8_STAGE(bufoff, gbase, voff) do { _Pragma("unroll") for (int _i = 0; _i < 2; ++_i) \
;         __builtin_amdgcn_global_load_lds((const unsigned*)((const char*)(gbase) + (voff)[_i]), (LAS unsigned*)(lds + (bufoff) + ldsw + _i * 8192), 16, 0, 0); } while (0)
; #define PG8_LDA(dst, b, h) do { _Pragma("unroll") for (int m = 0; m < 4; ++m) _Pragma("unroll") for (int k = 0; k < 2; ++k) dst[m][k] = *(const LAS bf16x8*)(lds + PG8_SA(b, h) + aoff + m * 2048 + k * 1024); } while (0)
; #define PG8_LDB(dst, b, h) do { _Pragma("unroll") for (int n = 0; n < 2; ++n) _Pragma("unroll") for (int k = 0; k < 2; ++k) dst[n][k] = *(const LAS bf16x8*)(lds + PG8_SB(b, h) + boff + n * 2048 + k * 1024); } while (0)
; #define PG8_MMA(ai, bj, At, Bt) do { __builtin_amdgcn_s_setprio(1); _Pragma("unroll") for (int m = 0; m < 4; ++m) _Pragma("unroll") for (int n = 0; n < 2; ++n) _Pragma("unroll") for (int k = 0; k < 2; ++k) \
;         acc[ai][bj][m][n] = __builtin_amdgcn_mfma_f32_16x16x32_bf16(Bt[n][k], At[m][k], acc[ai][bj][m][n], 0, 0, 0); __builtin_amdgcn_s_setprio(0); } while (0)
; #define PG8_WAIT_V(n) asm volatile("s_waitcnt vmcnt(" #n ")" ::: "memory")
; #define PG8_WAIT_L(n) asm volatile("s_waitcnt lgkmcnt(" #n ")" ::: "memory")
; #define PG8_BAR __builtin_amdgcn_s_barrier()
; #define PG8_SCHED __builtin_amdgcn_sched_barrier(0)
; template <class Epi>
; DI void gemm_phase(int wv, LAS unsigned char* lds, LAS unsigned char* scr, const Sched& S, const Epi& E) {
;     ...
;             PG8_WAIT_V(8); PG8_WAIT_L(0); PG8_BAR; PG8_MMA(1, 0, At, B0); PG8_MMA(1, 1, At, B1); PG8_BAR; PG8_SCHED;
;             PG8_LDB(B0, 1, 0); PG8_LDB(B1, 1, 1); PG8_SCHED; PG8_LDA(At, 1, 0); PG8_STAGE(PG8_SA(0, 1), a2 + hstepA, voffA);
;             PG8_WAIT_V(8); PG8_WAIT_L(0); PG8_BAR; PG8_MMA(0, 0, At, B0); PG8_MMA(0, 1, At, B1); PG8_BAR; PG8_SCHED;
	v_mfma_f32_16x16x32_bf16 v[60:63], v[140:143], v[172:175], v[60:63]
	v_mfma_f32_16x16x32_bf16 v[56:59], v[148:151], v[172:175], v[56:59]
	v_mfma_f32_16x16x32_bf16 v[52:55], v[140:143], v[180:183], v[52:55]
	v_mfma_f32_16x16x32_bf16 v[48:51], v[148:151], v[180:183], v[48:51]
	v_mfma_f32_16x16x32_bf16 v[36:39], v[140:143], v[188:191], v[36:39]
	v_mfma_f32_16x16x32_bf16 v[32:35], v[148:151], v[188:191], v[32:35]
	v_mfma_f32_16x16x32_bf16 v[20:23], v[140:143], v[198:201], v[20:23]
	v_mfma_f32_16x16x32_bf16 v[16:19], v[148:151], v[198:201], v[16:19]
	v_mfma_f32_16x16x32_bf16 v[60:63], v[144:147], v[176:179], v[60:63]
	v_mfma_f32_16x16x32_bf16 v[56:59], v[152:155], v[176:179], v[56:59]
	v_mfma_f32_16x16x32_bf16 v[52:55], v[144:147], v[184:187], v[52:55]
	v_mfma_f32_16x16x32_bf16 v[48:51], v[152:155], v[184:187], v[48:51]
	v_mfma_f32_16x16x32_bf16 v[36:39], v[144:147], v[194:197], v[36:39]
	v_mfma_f32_16x16x32_bf16 v[32:35], v[152:155], v[194:197], v[32:35]
	v_mfma_f32_16x16x32_bf16 v[20:23], v[144:147], v[202:205], v[20:23]
	v_mfma_f32_16x16x32_bf16 v[16:19], v[152:155], v[202:205], v[16:19]
	v_mfma_f32_16x16x32_bf16 v[44:47], v[156:159], v[172:175], v[44:47]
	v_mfma_f32_16x16x32_bf16 v[40:43], v[164:167], v[172:175], v[40:43]
	v_mfma_f32_16x16x32_bf16 v[28:31], v[156:159], v[180:183], v[28:31]
	v_mfma_f32_16x16x32_bf16 v[24:27], v[164:167], v[180:183], v[24:27]
	v_mfma_f32_16x16x32_bf16 v[12:15], v[156:159], v[188:191], v[12:15]
	v_mfma_f32_16x16x32_bf16 v[8:11], v[164:167], v[188:191], v[8:11]
	v_mfma_f32_16x16x32_bf16 v[4:7], v[156:159], v[198:201], v[4:7]
	v_mfma_f32_16x16x32_bf16 v[0:3], v[164:167], v[198:201], v[0:3]
	v_mfma_f32_16x16x32_bf16 v[44:47], v[160:163], v[176:179], v[44:47]
	v_mfma_f32_16x16x32_bf16 v[40:43], v[168:171], v[176:179], v[40:43]
	v_mfma_f32_16x16x32_bf16 v[28:31], v[160:163], v[184:187], v[28:31]
	v_mfma_f32_16x16x32_bf16 v[24:27], v[168:171], v[184:187], v[24:27]
	v_mfma_f32_16x16x32_bf16 v[12:15], v[160:163], v[194:197], v[12:15]
	v_mfma_f32_16x16x32_bf16 v[8:11], v[168:171], v[194:197], v[8:11]
	v_mfma_f32_16x16x32_bf16 v[4:7], v[160:163], v[202:205], v[4:7]
	v_mfma_f32_16x16x32_bf16 v[0:3], v[168:171], v[202:205], v[0:3]
	s_barrier
	v_add_u32_e32 v152, s59, v138
	v_add_u32_e32 v168, s55, v138
	ds_read_b128 v[140:143], v152
	ds_read_b128 v[144:147], v152 offset:1024
	ds_read_b128 v[148:151], v152 offset:2048
	ds_read_b128 v[152:155], v152 offset:3072
	ds_read_b128 v[156:159], v168
	ds_read_b128 v[160:163], v168 offset:1024
	ds_read_b128 v[164:167], v168 offset:2048
	ds_read_b128 v[168:171], v168 offset:3072
	s_mov_b32 m0, s46
	v_lshl_add_u64 v[214:215], s[26:27], 0, v[134:135]
	ds_read_b128 v[172:175], v139 offset:32768
	ds_read_b128 v[176:179], v139 offset:33792
	ds_read_b128 v[180:183], v139 offset:34816
	ds_read_b128 v[184:187], v139 offset:35840
	ds_read_b128 v[188:191], v139 offset:36864
	ds_read_b128 v[194:197], v139 offset:37888
	ds_read_b128 v[198:201], v139 offset:38912
	ds_read_b128 v[202:205], v139 offset:39936
	global_load_lds_dwordx4 v[214:215], off
	v_lshl_add_u64 v[214:215], s[26:27], 0, v[130:131]
	s_mov_b32 m0, s47
	s_nop 0
	global_load_lds_dwordx4 v[214:215], off
	s_waitcnt vmcnt(8)
	s_waitcnt lgkmcnt(0)
	s_barrier
	v_mfma_f32_16x16x32_bf16 v[124:127], v[140:143], v[172:175], v[124:127]
	v_mfma_f32_16x16x32_bf16 v[120:123], v[148:151], v[172:175], v[120:123]
	v_mfma_f32_16x16x32_bf16 v[116:119], v[140:143], v[180:183], v[116:119]
	v_mfma_f32_16x16x32_bf16 v[112:115], v[148:151], v[180:183], v[112:115]
	v_mfma_f32_16x16x32_bf16 v[100:103], v[140:143], v[188:191], v[100:103]
	v_mfma_f32_16x16x32_bf16 v[96:99], v[148:151], v[188:191], v[96:99]
	v_mfma_f32_16x16x32_bf16 v[84:87], v[140:143], v[198:201], v[84:87]
	v_mfma_f32_16x16x32_bf16 v[80:83], v[148:151], v[198:201], v[80:83]
	v_mfma_f32_16x16x32_bf16 v[124:127], v[144:147], v[176:179], v[124:127]
	v_mfma_f32_16x16x32_bf16 v[120:123], v[152:155], v[176:179], v[120:123]
	v_mfma_f32_16x16x32_bf16 v[116:119], v[144:147], v[184:187], v[116:119]
	v_mfma_f32_16x16x32_bf16 v[112:115], v[152:155], v[184:187], v[112:115]
	v_mfma_f32_16x16x32_bf16 v[100:103], v[144:147], v[194:197], v[100:103]
	v_mfma_f32_16x16x32_bf16 v[96:99], v[152:155], v[194:197], v[96:99]
	v_mfma_f32_16x16x32_bf16 v[84:87], v[144:147], v[202:205], v[84:87]
	v_mfma_f32_16x16x32_bf16 v[80:83], v[152:155], v[202:205], v[80:83]
	v_mfma_f32_16x16x32_bf16 v[108:111], v[156:159], v[172:175], v[108:111]
	v_mfma_f32_16x16x32_bf16 v[104:107], v[164:167], v[172:175], v[104:107]
	v_mfma_f32_16x16x32_bf16 v[92:95], v[156:159], v[180:183], v[92:95]
	v_mfma_f32_16x16x32_bf16 v[88:91], v[164:167], v[180:183], v[88:91]
	v_mfma_f32_16x16x32_bf16 v[76:79], v[156:159], v[188:191], v[76:79]
	v_mfma_f32_16x16x32_bf16 v[72:75], v[164:167], v[188:191], v[72:75]
	v_mfma_f32_16x16x32_bf16 v[68:71], v[156:159], v[198:201], v[68:71]
	v_mfma_f32_16x16x32_bf16 v[64:67], v[164:167], v[198:201], v[64:67]
	v_mfma_f32_16x16x32_bf16 v[108:111], v[160:163], v[176:179], v[108:111]
	v_mfma_f32_16x16x32_bf16 v[104:107], v[168:171], v[176:179], v[104:107]
	v_mfma_f32_16x16x32_bf16 v[92:95], v[160:163], v[184:187], v[92:95]
	v_mfma_f32_16x16x32_bf16 v[88:91], v[168:171], v[184:187], v[88:91]
	v_mfma_f32_16x16x32_bf16 v[76:79], v[160:163], v[194:197], v[76:79]
	v_mfma_f32_16x16x32_bf16 v[72:75], v[168:171], v[194:197], v[72:75]
	v_mfma_f32_16x16x32_bf16 v[68:71], v[160:163], v[202:205], v[68:71]
	v_mfma_f32_16x16x32_bf16 v[64:67], v[168:171], v[202:205], v[64:67]
	s_barrier
; #define PG8_STAGE(bufoff, gbase, voff) do { _Pragma("unroll") for (int _i = 0; _i < 2; ++_i) \
;         __builtin_amdgcn_global_load_lds((const unsigned*)((const char*)(gbase) + (voff)[_i]), (LAS unsigned*)(lds + (bufoff) + ldsw + _i * 8192), 16, 0, 0); } while (0)
; #define PG8_LDA(dst, b, h) do { _Pragma("unroll") for (int m = 0; m < 4; ++m) _Pragma("unroll") for (int k = 0; k < 2; ++k) dst[m][k] = *(const LAS bf16x8*)(lds + PG8_SA(b, h) + aoff + m * 2048 + k * 1024); } while (0)
; #define PG8_MMA(ai, bj, At, Bt) do { __builtin_amdgcn_s_setprio(1); _Pragma("unroll") for (int m = 0; m < 4; ++m) _Pragma("unroll") for (int n = 0; n < 2; ++n) _Pragma("unroll") for (int k = 0; k < 2; ++k) \
;         acc[ai][bj][m][n] = __builtin_amdgcn_mfma_f32_16x16x32_bf16(Bt[n][k], At[m][k], acc[ai][bj][m][n], 0, 0, 0); __builtin_amdgcn_s_setprio(0); } while (0)
; #define PG8_WAIT_V(n) asm volatile("s_waitcnt vmcnt(" #n ")" ::: "memory")
; #define PG8_WAIT_L(n) asm volatile("s_waitcnt lgkmcnt(" #n ")" ::: "memory")
; #define PG8_BAR __builtin_amdgcn_s_barrier()
; #define PG8_SCHED __builtin_amdgcn_sched_barrier(0)
; template <class Epi>
; DI void gemm_phase(int wv, LAS unsigned char* lds, LAS unsigned char* scr, const Sched& S, const Epi& E) {
;     ...
;             PG8_LDA(At, 1, 1); PG8_STAGE(PG8_SB(1, 0), b3, voffB); PG8_STAGE(PG8_SB(1, 1), b3 + hstepB, voffB); PG8_STAGE(PG8_SA(1, 0), a3, voffA);
;             PG8_WAIT_V(8); PG8_WAIT_L(0); PG8_BAR; PG8_MMA(1, 0, At, B0); PG8_MMA(1, 1, At, B1); PG8_BAR; PG8_SCHED;
;         }
;         if (wr == 0) PG8_BAR;
	s_mov_b32 m0, s21
	v_lshl_add_u64 v[206:207], v[206:207], 0, s[2:3]
	ds_read_b128 v[172:175], v139 offset:49152
	ds_read_b128 v[176:179], v139 offset:50176
	ds_read_b128 v[180:183], v139 offset:51200
	ds_read_b128 v[184:187], v139 offset:52224
	ds_read_b128 v[188:191], v139 offset:53248
	ds_read_b128 v[194:197], v139 offset:54272
	ds_read_b128 v[198:201], v139 offset:55296
	ds_read_b128 v[202:205], v139 offset:56320
	global_load_lds_dwordx4 v[206:207], off
	v_lshl_add_u64 v[206:207], v[208:209], 0, s[2:3]
	s_mov_b32 m0, s13
	s_nop 0
	global_load_lds_dwordx4 v[206:207], off
	v_lshl_add_u64 v[206:207], s[24:25], 0, v[132:133]
	s_mov_b32 m0, s65
	s_nop 0
	global_load_lds_dwordx4 v[206:207], off
	v_lshl_add_u64 v[206:207], s[24:25], 0, v[128:129]
	s_mov_b32 m0, s64
	s_nop 0
	global_load_lds_dwordx4 v[206:207], off
	v_lshl_add_u64 v[206:207], v[210:211], 0, s[2:3]
	s_mov_b32 m0, s50
	s_nop 0
	global_load_lds_dwordx4 v[206:207], off
	v_lshl_add_u64 v[206:207], v[212:213], 0, s[2:3]
	s_mov_b32 m0, s51
	s_nop 0
	global_load_lds_dwordx4 v[206:207], off
	s_waitcnt vmcnt(8)
	s_waitcnt lgkmcnt(0)
	s_barrier
	v_mfma_f32_16x16x32_bf16 v[60:63], v[140:143], v[172:175], v[60:63]
	v_mfma_f32_16x16x32_bf16 v[56:59], v[148:151], v[172:175], v[56:59]
	v_mfma_f32_16x16x32_bf16 v[52:55], v[140:143], v[180:183], v[52:55]
	v_mfma_f32_16x16x32_bf16 v[48:51], v[148:151], v[180:183], v[48:51]
	v_mfma_f32_16x16x32_bf16 v[36:39], v[140:143], v[188:191], v[36:39]
	v_mfma_f32_16x16x32_bf16 v[32:35], v[148:151], v[188:191], v[32:35]
	v_mfma_f32_16x16x32_bf16 v[20:23], v[140:143], v[198:201], v[20:23]
	v_mfma_f32_16x16x32_bf16 v[16:19], v[148:151], v[198:201], v[16:19]
	v_mfma_f32_16x16x32_bf16 v[60:63], v[144:147], v[176:179], v[60:63]
	v_mfma_f32_16x16x32_bf16 v[56:59], v[152:155], v[176:179], v[56:59]
	v_mfma_f32_16x16x32_bf16 v[52:55], v[144:147], v[184:187], v[52:55]
	v_mfma_f32_16x16x32_bf16 v[48:51], v[152:155], v[184:187], v[48:51]
	v_mfma_f32_16x16x32_bf16 v[36:39], v[144:147], v[194:197], v[36:39]
	v_mfma_f32_16x16x32_bf16 v[32:35], v[152:155], v[194:197], v[32:35]
	v_mfma_f32_16x16x32_bf16 v[20:23], v[144:147], v[202:205], v[20:23]
	v_mfma_f32_16x16x32_bf16 v[16:19], v[152:155], v[202:205], v[16:19]
	v_mfma_f32_16x16x32_bf16 v[44:47], v[156:159], v[172:175], v[44:47]
	v_mfma_f32_16x16x32_bf16 v[40:43], v[164:167], v[172:175], v[40:43]
	v_mfma_f32_16x16x32_bf16 v[28:31], v[156:159], v[180:183], v[28:31]
	v_mfma_f32_16x16x32_bf16 v[24:27], v[164:167], v[180:183], v[24:27]
	v_mfma_f32_16x16x32_bf16 v[12:15], v[156:159], v[188:191], v[12:15]
	v_mfma_f32_16x16x32_bf16 v[8:11], v[164:167], v[188:191], v[8:11]
	v_mfma_f32_16x16x32_bf16 v[4:7], v[156:159], v[198:201], v[4:7]
	v_mfma_f32_16x16x32_bf16 v[0:3], v[164:167], v[198:201], v[0:3]
	v_mfma_f32_16x16x32_bf16 v[44:47], v[160:163], v[176:179], v[44:47]
	v_mfma_f32_16x16x32_bf16 v[40:43], v[168:171], v[176:179], v[40:43]
	v_mfma_f32_16x16x32_bf16 v[28:31], v[160:163], v[184:187], v[28:31]
	v_mfma_f32_16x16x32_bf16 v[24:27], v[168:171], v[184:187], v[24:27]
	v_mfma_f32_16x16x32_bf16 v[12:15], v[160:163], v[194:197], v[12:15]
	v_mfma_f32_16x16x32_bf16 v[8:11], v[168:171], v[194:197], v[8:11]
	v_mfma_f32_16x16x32_bf16 v[4:7], v[160:163], v[202:205], v[4:7]
	v_mfma_f32_16x16x32_bf16 v[0:3], v[168:171], v[202:205], v[0:3]
	s_barrier
	s_movk_i32 s13, 0x100
	s_andn2_b64 vcc, exec, s[22:23]
	s_mov_b64 s[24:25], -1
	s_mov_b64 s[22:23], 0
	s_cbranch_vccz .LBB0_277
	s_and_b64 vcc, exec, s[10:11]
	s_cbranch_vccz .LBB0_280
	s_barrier

; #define PG8_STAGE(bufoff, gbase, voff) do { _Pragma("unroll") for (int _i = 0; _i < 2; ++_i) \
;         __builtin_amdgcn_global_load_lds((const unsigned*)((const char*)(gbase) + (voff)[_i]), (LAS unsigned*)(lds + (bufoff) + ldsw + _i * 8192), 16, 0, 0); } while (0)
; #define PG8_LDA(dst, b, h) do { _Pragma("unroll") for (int m = 0; m < 4; ++m) _Pragma("unroll") for (int k = 0; k < 2; ++k) dst[m][k] = *(const LAS bf16x8*)(lds + PG8_SA(b, h) + aoff + m * 2048 + k * 1024); } while (0)
; #define PG8_LDB(dst, b, h) do { _Pragma("unroll") for (int n = 0; n < 2; ++n) _Pragma("unroll") for (int k = 0; k < 2; ++k) dst[n][k] = *(const LAS bf16x8*)(lds + PG8_SB(b, h) + boff + n * 2048 + k * 1024); } while (0)
; #define PG8_MMA(ai, bj, At, Bt) do { __builtin_amdgcn_s_setprio(1); _Pragma("unroll") for (int m = 0; m < 4; ++m) _Pragma("unroll") for (int n = 0; n < 2; ++n) _Pragma("unroll") for (int k = 0; k < 2; ++k) \
;         acc[ai][bj][m][n] = __builtin_amdgcn_mfma_f32_16x16x32_bf16(Bt[n][k], At[m][k], acc[ai][bj][m][n], 0, 0, 0); __builtin_amdgcn_s_setprio(0); } while (0)
; #define PG8_WAIT_V(n) asm volatile("s_waitcnt vmcnt(" #n ")" ::: "memory")
; #define PG8_WAIT_L(n) asm volatile("s_waitcnt lgkmcnt(" #n ")" ::: "memory")
; #define PG8_BAR __builtin_amdgcn_s_barrier()
; #define PG8_SCHED __builtin_amdgcn_sched_barrier(0)
; template <class Epi>
; DI void gemm_phase(int wv, LAS unsigned char* lds, LAS unsigned char* scr, const Sched& S, const Epi& E) {
;     ...
;             const bool last = (t == nt - 2);
;             const char* a1 = cA + (size_t)(t + 1) * kstep;
;             const char* a2 = last ? nA : cA + (size_t)(t + 2) * kstep; const char* b2 = last ? nB : cB + (size_t)(t + 2) * kstep;
;             const char* a3 = a2 + kstep; const char* b3 = b2 + kstep;
;             PG8_LDB(B0, 0, 0); PG8_LDB(B1, 0, 1); PG8_SCHED; PG8_LDA(At, 0, 0); PG8_STAGE(PG8_SA(1, 1), a1 + hstepA, voffA);
;             PG8_WAIT_V(8); PG8_WAIT_L(0); PG8_BAR; PG8_MMA(0, 0, At, B0); PG8_MMA(0, 1, At, B1); PG8_BAR; PG8_SCHED;
;             PG8_LDA(At, 0, 1); PG8_STAGE(PG8_SB(0, 0), b2, voffB); PG8_STAGE(PG8_SB(0, 1), b2 + hstepB, voffB); PG8_STAGE(PG8_SA(0, 0), a2, voffA);
.LBB0_463:
	s_add_u32 s24, s22, 0xfffc0080
	s_addc_u32 s25, s23, -1
	s_add_i32 s48, 0, 0x10000
	s_cmp_eq_u32 s47, 12
	s_cselect_b32 s27, s11, s25
	s_cselect_b32 s26, s15, s24
	v_add_u32_e32 v143, s48, v144
	s_cselect_b32 s25, s13, s46
	s_cselect_b32 s24, s21, s45
	s_add_i32 s50, 0, 0x14000
	ds_read_b128 v[146:149], v143
	ds_read_b128 v[150:153], v143 offset:1024
	ds_read_b128 v[154:157], v143 offset:2048
	ds_read_b128 v[158:161], v143 offset:3072
	v_add_u32_e32 v143, s50, v144
	ds_read_b128 v[162:165], v143
	ds_read_b128 v[166:169], v143 offset:1024
	ds_read_b128 v[170:173], v143 offset:2048
	ds_read_b128 v[174:177], v143 offset:3072
	v_lshl_add_u64 v[190:191], s[22:23], 0, v[140:141]
	s_add_i32 m0, s34, 0xc000
	ds_read_b128 v[178:181], v145
	ds_read_b128 v[182:185], v145 offset:1024
	ds_read_b128 v[186:189], v145 offset:2048
	ds_read_b128 v[194:197], v145 offset:3072
	ds_read_b128 v[198:201], v145 offset:4096
	ds_read_b128 v[202:205], v145 offset:5120
	ds_read_b128 v[206:209], v145 offset:6144
	ds_read_b128 v[210:213], v145 offset:7168
	global_load_lds_dwordx4 v[190:191], off
	v_lshl_add_u64 v[190:191], s[22:23], 0, v[138:139]
	s_add_i32 m0, s34, 0xe000
	s_nop 0
	global_load_lds_dwordx4 v[190:191], off
	s_waitcnt vmcnt(8)
	s_waitcnt lgkmcnt(0)
	s_barrier
	v_mfma_f32_16x16x32_bf16 v[124:127], v[146:149], v[178:181], v[124:127]
	v_mfma_f32_16x16x32_bf16 v[120:123], v[154:157], v[178:181], v[120:123]
	v_mfma_f32_16x16x32_bf16 v[116:119], v[146:149], v[186:189], v[116:119]
	v_mfma_f32_16x16x32_bf16 v[112:115], v[154:157], v[186:189], v[112:115]
	v_mfma_f32_16x16x32_bf16 v[100:103], v[146:149], v[198:201], v[100:103]
	v_mfma_f32_16x16x32_bf16 v[96:99], v[154:157], v[198:201], v[96:99]
	v_mfma_f32_16x16x32_bf16 v[84:87], v[146:149], v[206:209], v[84:87]
	v_mfma_f32_16x16x32_bf16 v[80:83], v[154:157], v[206:209], v[80:83]
	v_mfma_f32_16x16x32_bf16 v[124:127], v[150:153], v[182:185], v[124:127]
	v_mfma_f32_16x16x32_bf16 v[120:123], v[158:161], v[182:185], v[120:123]
	v_mfma_f32_16x16x32_bf16 v[116:119], v[150:153], v[194:197], v[116:119]
	v_mfma_f32_16x16x32_bf16 v[112:115], v[158:161], v[194:197], v[112:115]
	v_mfma_f32_16x16x32_bf16 v[100:103], v[150:153], v[202:205], v[100:103]
	v_mfma_f32_16x16x32_bf16 v[96:99], v[158:161], v[202:205], v[96:99]
	v_mfma_f32_16x16x32_bf16 v[84:87], v[150:153], v[210:213], v[84:87]
	v_mfma_f32_16x16x32_bf16 v[80:83], v[158:161], v[210:213], v[80:83]
	v_mfma_f32_16x16x32_bf16 v[108:111], v[162:165], v[178:181], v[108:111]
	v_mfma_f32_16x16x32_bf16 v[104:107], v[170:173], v[178:181], v[104:107]
	v_mfma_f32_16x16x32_bf16 v[92:95], v[162:165], v[186:189], v[92:95]
	v_mfma_f32_16x16x32_bf16 v[88:91], v[170:173], v[186:189], v[88:91]
	v_mfma_f32_16x16x32_bf16 v[76:79], v[162:165], v[198:201], v[76:79]
	v_mfma_f32_16x16x32_bf16 v[72:75], v[170:173], v[198:201], v[72:75]
	v_mfma_f32_16x16x32_bf16 v[68:71], v[162:165], v[206:209], v[68:71]
	v_mfma_f32_16x16x32_bf16 v[64:67], v[170:173], v[206:209], v[64:67]
	v_mfma_f32_16x16x32_bf16 v[108:111], v[166:169], v[182:185], v[108:111]
	v_mfma_f32_16x16x32_bf16 v[104:107], v[174:177], v[182:185], v[104:107]
	v_mfma_f32_16x16x32_bf16 v[92:95], v[166:169], v[194:197], v[92:95]
	v_mfma_f32_16x16x32_bf16 v[88:91], v[174:177], v[194:197], v[88:91]
	v_mfma_f32_16x16x32_bf16 v[76:79], v[166:169], v[202:205], v[76:79]
	v_mfma_f32_16x16x32_bf16 v[72:75], v[174:177], v[202:205], v[72:75]
	v_mfma_f32_16x16x32_bf16 v[68:71], v[166:169], v[210:213], v[68:71]
	v_mfma_f32_16x16x32_bf16 v[64:67], v[174:177], v[210:213], v[64:67]
	s_barrier
	s_add_i32 s48, s48, s33
	v_lshl_add_u64 v[190:191], s[24:25], 0, v[132:133]
	s_mov_b32 m0, s48
	ds_read_b128 v[178:181], v145 offset:16384
	ds_read_b128 v[182:185], v145 offset:17408
	ds_read_b128 v[186:189], v145 offset:18432
	ds_read_b128 v[194:197], v145 offset:19456
	ds_read_b128 v[198:201], v145 offset:20480
	ds_read_b128 v[202:205], v145 offset:21504
	ds_read_b128 v[206:209], v145 offset:22528
	ds_read_b128 v[210:213], v145 offset:23552
	global_load_lds_dwordx4 v[190:191], off
	s_add_i32 m0, s48, 0x2000
	s_add_u32 s48, s24, 0x40000
	v_lshl_add_u64 v[214:215], s[24:25], 0, v[128:129]
	s_addc_u32 s49, s25, 0
	s_add_i32 s50, s50, s33
	global_load_lds_dwordx4 v[214:215], off
	v_lshl_add_u64 v[216:217], s[48:49], 0, v[132:133]
	s_mov_b32 m0, s50
	v_lshl_add_u64 v[218:219], s[26:27], 0, v[130:131]
	global_load_lds_dwordx4 v[216:217], off
	v_lshl_add_u64 v[216:217], s[48:49], 0, v[128:129]
	s_add_i32 m0, s50, 0x2000
	s_nop 0
	global_load_lds_dwordx4 v[216:217], off
	v_lshl_add_u64 v[216:217], s[26:27], 0, v[134:135]
	s_mov_b32 m0, s34
	s_nop 0
	global_load_lds_dwordx4 v[216:217], off
	s_mov_b32 m0, s35
	s_nop 0
	global_load_lds_dwordx4 v[218:219], off
	s_waitcnt vmcnt(8)
	s_waitcnt lgkmcnt(0)
	s_barrier
; #define PG8_STAGE(bufoff, gbase, voff) do { _Pragma("unroll") for (int _i = 0; _i < 2; ++_i) \
;         __builtin_amdgcn_global_load_lds((const unsigned*)((const char*)(gbase) + (voff)[_i]), (LAS unsigned*)(lds + (bufoff) + ldsw + _i * 8192), 16, 0, 0); } while (0)
; #define PG8_LDA(dst, b, h) do { _Pragma("unroll") for (int m = 0; m < 4; ++m) _Pragma("unroll") for (int k = 0; k < 2; ++k) dst[m][k] = *(const LAS bf16x8*)(lds + PG8_SA(b, h) + aoff + m * 2048 + k * 1024); } while (0)
; #define PG8_LDB(dst, b, h) do { _Pragma("unroll") for (int n = 0; n < 2; ++n) _Pragma("unroll") for (int k = 0; k < 2; ++k) dst[n][k] = *(const LAS bf16x8*)(lds + PG8_SB(b, h) + boff + n * 2048 + k * 1024); } while (0)
; #define PG8_MMA(ai, bj, At, Bt) do { __builtin_amdgcn_s_setprio(1); _Pragma("unroll") for (int m = 0; m < 4; ++m) _Pragma("unroll") for (int n = 0; n < 2; ++n) _Pragma("unroll") for (int k = 0; k < 2; ++k) \
;         acc[ai][bj][m][n] = __builtin_amdgcn_mfma_f32_16x16x32_bf16(Bt[n][k], At[m][k], acc[ai][bj][m][n], 0, 0, 0); __builtin_amdgcn_s_setprio(0); } while (0)
; #define PG8_WAIT_V(n) asm volatile("s_waitcnt vmcnt(" #n ")" ::: "memory")
; #define PG8_WAIT_L(n) asm volatile("s_waitcnt lgkmcnt(" #n ")" ::: "memory")
; #define PG8_BAR __builtin_amdgcn_s_barrier()
; #define PG8_SCHED __builtin_amdgcn_sched_barrier(0)
; template <class Epi>
; DI void gemm_phase(int wv, LAS unsigned char* lds, LAS unsigned char* scr, const Sched& S, const Epi& E) {
;     ...
;             PG8_WAIT_V(8); PG8_WAIT_L(0); PG8_BAR; PG8_MMA(1, 0, At, B0); PG8_MMA(1, 1, At, B1); PG8_BAR; PG8_SCHED;
;             PG8_LDB(B0, 1, 0); PG8_LDB(B1, 1, 1); PG8_SCHED; PG8_LDA(At, 1, 0); PG8_STAGE(PG8_SA(0, 1), a2 + hstepA, voffA);
;             PG8_WAIT_V(8); PG8_WAIT_L(0); PG8_BAR; PG8_MMA(0, 0, At, B0); PG8_MMA(0, 1, At, B1); PG8_BAR; PG8_SCHED;
	v_mfma_f32_16x16x32_bf16 v[60:63], v[146:149], v[178:181], v[60:63]
	v_mfma_f32_16x16x32_bf16 v[56:59], v[154:157], v[178:181], v[56:59]
	v_mfma_f32_16x16x32_bf16 v[52:55], v[146:149], v[186:189], v[52:55]
	v_mfma_f32_16x16x32_bf16 v[48:51], v[154:157], v[186:189], v[48:51]
	v_mfma_f32_16x16x32_bf16 v[36:39], v[146:149], v[198:201], v[36:39]
	v_mfma_f32_16x16x32_bf16 v[32:35], v[154:157], v[198:201], v[32:35]
	v_mfma_f32_16x16x32_bf16 v[20:23], v[146:149], v[206:209], v[20:23]
	v_mfma_f32_16x16x32_bf16 v[16:19], v[154:157], v[206:209], v[16:19]
	v_mfma_f32_16x16x32_bf16 v[60:63], v[150:153], v[182:185], v[60:63]
	v_mfma_f32_16x16x32_bf16 v[56:59], v[158:161], v[182:185], v[56:59]
	v_mfma_f32_16x16x32_bf16 v[52:55], v[150:153], v[194:197], v[52:55]
	v_mfma_f32_16x16x32_bf16 v[48:51], v[158:161], v[194:197], v[48:51]
	v_mfma_f32_16x16x32_bf16 v[36:39], v[150:153], v[202:205], v[36:39]
	v_mfma_f32_16x16x32_bf16 v[32:35], v[158:161], v[202:205], v[32:35]
	v_mfma_f32_16x16x32_bf16 v[20:23], v[150:153], v[210:213], v[20:23]
	v_mfma_f32_16x16x32_bf16 v[16:19], v[158:161], v[210:213], v[16:19]
	v_mfma_f32_16x16x32_bf16 v[44:47], v[162:165], v[178:181], v[44:47]
	v_mfma_f32_16x16x32_bf16 v[40:43], v[170:173], v[178:181], v[40:43]
	v_mfma_f32_16x16x32_bf16 v[28:31], v[162:165], v[186:189], v[28:31]
	v_mfma_f32_16x16x32_bf16 v[24:27], v[170:173], v[186:189], v[24:27]
	v_mfma_f32_16x16x32_bf16 v[12:15], v[162:165], v[198:201], v[12:15]
	v_mfma_f32_16x16x32_bf16 v[8:11], v[170:173], v[198:201], v[8:11]
	v_mfma_f32_16x16x32_bf16 v[4:7], v[162:165], v[206:209], v[4:7]
	v_mfma_f32_16x16x32_bf16 v[0:3], v[170:173], v[206:209], v[0:3]
	v_mfma_f32_16x16x32_bf16 v[44:47], v[166:169], v[182:185], v[44:47]
	v_mfma_f32_16x16x32_bf16 v[40:43], v[174:177], v[182:185], v[40:43]
	v_mfma_f32_16x16x32_bf16 v[28:31], v[166:169], v[194:197], v[28:31]
	v_mfma_f32_16x16x32_bf16 v[24:27], v[174:177], v[194:197], v[24:27]
	v_mfma_f32_16x16x32_bf16 v[12:15], v[166:169], v[202:205], v[12:15]
	v_mfma_f32_16x16x32_bf16 v[8:11], v[174:177], v[202:205], v[8:11]
	v_mfma_f32_16x16x32_bf16 v[4:7], v[166:169], v[210:213], v[4:7]
	v_mfma_f32_16x16x32_bf16 v[0:3], v[174:177], v[210:213], v[0:3]
	s_barrier
	s_add_i32 s48, 0, 0x18000
	v_add_u32_e32 v143, s48, v144
	s_add_i32 s49, 0, 0x1c000
	ds_read_b128 v[146:149], v143
	ds_read_b128 v[150:153], v143 offset:1024
	ds_read_b128 v[154:157], v143 offset:2048
	ds_read_b128 v[158:161], v143 offset:3072
	v_add_u32_e32 v143, s49, v144
	ds_read_b128 v[162:165], v143
	ds_read_b128 v[166:169], v143 offset:1024
	ds_read_b128 v[170:173], v143 offset:2048
	ds_read_b128 v[174:177], v143 offset:3072
	s_add_u32 s26, s26, 0x40000
	s_addc_u32 s27, s27, 0
	s_mov_b32 m0, s36
	v_lshl_add_u64 v[220:221], s[26:27], 0, v[134:135]
	ds_read_b128 v[178:181], v145 offset:32768
	ds_read_b128 v[182:185], v145 offset:33792
	ds_read_b128 v[186:189], v145 offset:34816
	ds_read_b128 v[194:197], v145 offset:35840
	ds_read_b128 v[198:201], v145 offset:36864
	ds_read_b128 v[202:205], v145 offset:37888
	ds_read_b128 v[206:209], v145 offset:38912
	ds_read_b128 v[210:213], v145 offset:39936
	global_load_lds_dwordx4 v[220:221], off
	v_lshl_add_u64 v[220:221], s[26:27], 0, v[130:131]
	s_mov_b32 m0, s37
	s_nop 0
	global_load_lds_dwordx4 v[220:221], off
	s_waitcnt vmcnt(8)
	s_waitcnt lgkmcnt(0)
	s_barrier
	v_mfma_f32_16x16x32_bf16 v[124:127], v[146:149], v[178:181], v[124:127]
	v_mfma_f32_16x16x32_bf16 v[120:123], v[154:157], v[178:181], v[120:123]
	v_mfma_f32_16x16x32_bf16 v[116:119], v[146:149], v[186:189], v[116:119]
	v_mfma_f32_16x16x32_bf16 v[112:115], v[154:157], v[186:189], v[112:115]
	v_mfma_f32_16x16x32_bf16 v[100:103], v[146:149], v[198:201], v[100:103]
	v_mfma_f32_16x16x32_bf16 v[96:99], v[154:157], v[198:201], v[96:99]
	v_mfma_f32_16x16x32_bf16 v[84:87], v[146:149], v[206:209], v[84:87]
	v_mfma_f32_16x16x32_bf16 v[80:83], v[154:157], v[206:209], v[80:83]
	v_mfma_f32_16x16x32_bf16 v[124:127], v[150:153], v[182:185], v[124:127]
	v_mfma_f32_16x16x32_bf16 v[120:123], v[158:161], v[182:185], v[120:123]
	v_mfma_f32_16x16x32_bf16 v[116:119], v[150:153], v[194:197], v[116:119]
	v_mfma_f32_16x16x32_bf16 v[112:115], v[158:161], v[194:197], v[112:115]
	v_mfma_f32_16x16x32_bf16 v[100:103], v[150:153], v[202:205], v[100:103]
	v_mfma_f32_16x16x32_bf16 v[96:99], v[158:161], v[202:205], v[96:99]
	v_mfma_f32_16x16x32_bf16 v[84:87], v[150:153], v[210:213], v[84:87]
	v_mfma_f32_16x16x32_bf16 v[80:83], v[158:161], v[210:213], v[80:83]
	v_mfma_f32_16x16x32_bf16 v[108:111], v[162:165], v[178:181], v[108:111]
	v_mfma_f32_16x16x32_bf16 v[104:107], v[170:173], v[178:181], v[104:107]
	v_mfma_f32_16x16x32_bf16 v[92:95], v[162:165], v[186:189], v[92:95]
	v_mfma_f32_16x16x32_bf16 v[88:91], v[170:173], v[186:189], v[88:91]
	v_mfma_f32_16x16x32_bf16 v[76:79], v[162:165], v[198:201], v[76:79]
	v_mfma_f32_16x16x32_bf16 v[72:75], v[170:173], v[198:201], v[72:75]
	v_mfma_f32_16x16x32_bf16 v[68:71], v[162:165], v[206:209], v[68:71]
	v_mfma_f32_16x16x32_bf16 v[64:67], v[170:173], v[206:209], v[64:67]
	v_mfma_f32_16x16x32_bf16 v[108:111], v[166:169], v[182:185], v[108:111]
	v_mfma_f32_16x16x32_bf16 v[104:107], v[174:177], v[182:185], v[104:107]
	v_mfma_f32_16x16x32_bf16 v[92:95], v[166:169], v[194:197], v[92:95]
	v_mfma_f32_16x16x32_bf16 v[88:91], v[174:177], v[194:197], v[88:91]
	v_mfma_f32_16x16x32_bf16 v[76:79], v[166:169], v[202:205], v[76:79]
	v_mfma_f32_16x16x32_bf16 v[72:75], v[174:177], v[202:205], v[72:75]
	v_mfma_f32_16x16x32_bf16 v[68:71], v[166:169], v[210:213], v[68:71]
	v_mfma_f32_16x16x32_bf16 v[64:67], v[174:177], v[210:213], v[64:67]
	s_barrier
; #define PG8_STAGE(bufoff, gbase, voff) do { _Pragma("unroll") for (int _i = 0; _i < 2; ++_i) \
;         __builtin_amdgcn_global_load_lds((const unsigned*)((const char*)(gbase) + (voff)[_i]), (LAS unsigned*)(lds + (bufoff) + ldsw + _i * 8192), 16, 0, 0); } while (0)
; #define PG8_LDA(dst, b, h) do { _Pragma("unroll") for (int m = 0; m < 4; ++m) _Pragma("unroll") for (int k = 0; k < 2; ++k) dst[m][k] = *(const LAS bf16x8*)(lds + PG8_SA(b, h) + aoff + m * 2048 + k * 1024); } while (0)
; #define PG8_MMA(ai, bj, At, Bt) do { __builtin_amdgcn_s_setprio(1); _Pragma("unroll") for (int m = 0; m < 4; ++m) _Pragma("unroll") for (int n = 0; n < 2; ++n) _Pragma("unroll") for (int k = 0; k < 2; ++k) \
;         acc[ai][bj][m][n] = __builtin_amdgcn_mfma_f32_16x16x32_bf16(Bt[n][k], At[m][k], acc[ai][bj][m][n], 0, 0, 0); __builtin_amdgcn_s_setprio(0); } while (0)
; #define PG8_WAIT_V(n) asm volatile("s_waitcnt vmcnt(" #n ")" ::: "memory")
; #define PG8_WAIT_L(n) asm volatile("s_waitcnt lgkmcnt(" #n ")" ::: "memory")
; #define PG8_BAR __builtin_amdgcn_s_barrier()
; #define PG8_SCHED __builtin_amdgcn_sched_barrier(0)
; template <class Epi>
; DI void gemm_phase(int wv, LAS unsigned char* lds, LAS unsigned char* scr, const Sched& S, const Epi& E) {
;     ...
;             PG8_LDA(At, 1, 1); PG8_STAGE(PG8_SB(1, 0), b3, voffB); PG8_STAGE(PG8_SB(1, 1), b3 + hstepB, voffB); PG8_STAGE(PG8_SA(1, 0), a3, voffA);
;             PG8_WAIT_V(8); PG8_WAIT_L(0); PG8_BAR; PG8_MMA(1, 0, At, B0); PG8_MMA(1, 1, At, B1); PG8_BAR; PG8_SCHED;
;         }
;         if (wr == 0) PG8_BAR;
	s_add_i32 s26, s48, s33
	v_lshl_add_u64 v[190:191], v[190:191], 0, s[2:3]
	s_mov_b32 m0, s26
	ds_read_b128 v[178:181], v145 offset:49152
	ds_read_b128 v[182:185], v145 offset:50176
	ds_read_b128 v[186:189], v145 offset:51200
	ds_read_b128 v[194:197], v145 offset:52224
	ds_read_b128 v[198:201], v145 offset:53248
	ds_read_b128 v[202:205], v145 offset:54272
	ds_read_b128 v[206:209], v145 offset:55296
	ds_read_b128 v[210:213], v145 offset:56320
	global_load_lds_dwordx4 v[190:191], off
	s_add_i32 m0, s26, 0x2000
	s_add_u32 s24, s24, 0x40080
	v_lshl_add_u64 v[190:191], v[214:215], 0, s[2:3]
	s_addc_u32 s25, s25, 0
	s_add_i32 s26, s49, s33
	global_load_lds_dwordx4 v[190:191], off
	v_lshl_add_u64 v[190:191], s[24:25], 0, v[132:133]
	s_mov_b32 m0, s26
	s_nop 0
	global_load_lds_dwordx4 v[190:191], off
	v_lshl_add_u64 v[190:191], s[24:25], 0, v[128:129]
	s_add_i32 m0, s26, 0x2000
	s_nop 0
	global_load_lds_dwordx4 v[190:191], off
	v_lshl_add_u64 v[190:191], v[216:217], 0, s[2:3]
	s_mov_b32 m0, s42
	s_nop 0
	global_load_lds_dwordx4 v[190:191], off
	v_lshl_add_u64 v[190:191], v[218:219], 0, s[2:3]
	s_mov_b32 m0, s43
	s_nop 0
	global_load_lds_dwordx4 v[190:191], off
	s_waitcnt vmcnt(8)
	s_waitcnt lgkmcnt(0)
	s_barrier
	v_mfma_f32_16x16x32_bf16 v[60:63], v[146:149], v[178:181], v[60:63]
	v_mfma_f32_16x16x32_bf16 v[56:59], v[154:157], v[178:181], v[56:59]
	v_mfma_f32_16x16x32_bf16 v[52:55], v[146:149], v[186:189], v[52:55]
	v_mfma_f32_16x16x32_bf16 v[48:51], v[154:157], v[186:189], v[48:51]
	v_mfma_f32_16x16x32_bf16 v[36:39], v[146:149], v[198:201], v[36:39]
	v_mfma_f32_16x16x32_bf16 v[32:35], v[154:157], v[198:201], v[32:35]
	v_mfma_f32_16x16x32_bf16 v[20:23], v[146:149], v[206:209], v[20:23]
	v_mfma_f32_16x16x32_bf16 v[16:19], v[154:157], v[206:209], v[16:19]
	v_mfma_f32_16x16x32_bf16 v[60:63], v[150:153], v[182:185], v[60:63]
	v_mfma_f32_16x16x32_bf16 v[56:59], v[158:161], v[182:185], v[56:59]
	v_mfma_f32_16x16x32_bf16 v[52:55], v[150:153], v[194:197], v[52:55]
	v_mfma_f32_16x16x32_bf16 v[48:51], v[158:161], v[194:197], v[48:51]
	v_mfma_f32_16x16x32_bf16 v[36:39], v[150:153], v[202:205], v[36:39]
	v_mfma_f32_16x16x32_bf16 v[32:35], v[158:161], v[202:205], v[32:35]
	v_mfma_f32_16x16x32_bf16 v[20:23], v[150:153], v[210:213], v[20:23]
	v_mfma_f32_16x16x32_bf16 v[16:19], v[158:161], v[210:213], v[16:19]
	v_mfma_f32_16x16x32_bf16 v[44:47], v[162:165], v[178:181], v[44:47]
	v_mfma_f32_16x16x32_bf16 v[40:43], v[170:173], v[178:181], v[40:43]
	v_mfma_f32_16x16x32_bf16 v[28:31], v[162:165], v[186:189], v[28:31]
	v_mfma_f32_16x16x32_bf16 v[24:27], v[170:173], v[186:189], v[24:27]
	v_mfma_f32_16x16x32_bf16 v[12:15], v[162:165], v[198:201], v[12:15]
	v_mfma_f32_16x16x32_bf16 v[8:11], v[170:173], v[198:201], v[8:11]
	v_mfma_f32_16x16x32_bf16 v[4:7], v[162:165], v[206:209], v[4:7]
	v_mfma_f32_16x16x32_bf16 v[0:3], v[170:173], v[206:209], v[0:3]
	v_mfma_f32_16x16x32_bf16 v[44:47], v[166:169], v[182:185], v[44:47]
	v_mfma_f32_16x16x32_bf16 v[40:43], v[174:177], v[182:185], v[40:43]
	v_mfma_f32_16x16x32_bf16 v[28:31], v[166:169], v[194:197], v[28:31]
	v_mfma_f32_16x16x32_bf16 v[24:27], v[174:177], v[194:197], v[24:27]
	v_mfma_f32_16x16x32_bf16 v[12:15], v[166:169], v[202:205], v[12:15]
	v_mfma_f32_16x16x32_bf16 v[8:11], v[174:177], v[202:205], v[8:11]
	v_mfma_f32_16x16x32_bf16 v[4:7], v[166:169], v[210:213], v[4:7]
	v_mfma_f32_16x16x32_bf16 v[0:3], v[174:177], v[210:213], v[0:3]
	s_barrier
	s_add_i32 s47, s47, 2
	s_add_u32 s45, s45, 0x100
	s_addc_u32 s46, s46, 0
	s_add_u32 s22, s22, 0x100
	s_addc_u32 s23, s23, 0
	s_cmp_gt_u32 s47, 13
	s_cbranch_scc0 .LBB0_463
	s_and_b64 vcc, exec, s[8:9]
	s_cbranch_vccz .LBB0_466
	s_barrier

; #define PG8_STAGE(bufoff, gbase, voff) do { _Pragma("unroll") for (int _i = 0; _i < 2; ++_i) \
;         __builtin_amdgcn_global_load_lds((const unsigned*)((const char*)(gbase) + (voff)[_i]), (LAS unsigned*)(lds + (bufoff) + ldsw + _i * 8192), 16, 0, 0); } while (0)
; #define PG8_LDA(dst, b, h) do { _Pragma("unroll") for (int m = 0; m < 4; ++m) _Pragma("unroll") for (int k = 0; k < 2; ++k) dst[m][k] = *(const LAS bf16x8*)(lds + PG8_SA(b, h) + aoff + m * 2048 + k * 1024); } while (0)
; #define PG8_LDB(dst, b, h) do { _Pragma("unroll") for (int n = 0; n < 2; ++n) _Pragma("unroll") for (int k = 0; k < 2; ++k) dst[n][k] = *(const LAS bf16x8*)(lds + PG8_SB(b, h) + boff + n * 2048 + k * 1024); } while (0)
; #define PG8_MMA(ai, bj, At, Bt) do { __builtin_amdgcn_s_setprio(1); _Pragma("unroll") for (int m = 0; m < 4; ++m) _Pragma("unroll") for (int n = 0; n < 2; ++n) _Pragma("unroll") for (int k = 0; k < 2; ++k) \
;         acc[ai][bj][m][n] = __builtin_amdgcn_mfma_f32_16x16x32_bf16(Bt[n][k], At[m][k], acc[ai][bj][m][n], 0, 0, 0); __builtin_amdgcn_s_setprio(0); } while (0)
; #define PG8_WAIT_V(n) asm volatile("s_waitcnt vmcnt(" #n ")" ::: "memory")
; #define PG8_WAIT_L(n) asm volatile("s_waitcnt lgkmcnt(" #n ")" ::: "memory")
; #define PG8_BAR __builtin_amdgcn_s_barrier()
; #define PG8_SCHED __builtin_amdgcn_sched_barrier(0)
; template <class Epi>
; DI void gemm_phase(int wv, LAS unsigned char* lds, LAS unsigned char* scr, const Sched& S, const Epi& E) {
;     ...
;             const bool last = (t == nt - 2);
;             const char* a1 = cA + (size_t)(t + 1) * kstep;
;             const char* a2 = last ? nA : cA + (size_t)(t + 2) * kstep; const char* b2 = last ? nB : cB + (size_t)(t + 2) * kstep;
;             const char* a3 = a2 + kstep; const char* b3 = b2 + kstep;
;             PG8_LDB(B0, 0, 0); PG8_LDB(B1, 0, 1); PG8_SCHED; PG8_LDA(At, 0, 0); PG8_STAGE(PG8_SA(1, 1), a1 + hstepA, voffA);
;             PG8_WAIT_V(8); PG8_WAIT_L(0); PG8_BAR; PG8_MMA(0, 0, At, B0); PG8_MMA(0, 1, At, B1); PG8_BAR; PG8_SCHED;
;             PG8_LDA(At, 0, 1); PG8_STAGE(PG8_SB(0, 0), b2, voffB); PG8_STAGE(PG8_SB(0, 1), b2 + hstepB, voffB); PG8_STAGE(PG8_SA(0, 0), a2, voffA);
.LBB0_588:
	s_add_u32 s28, s12, 0xfffc0080
	s_addc_u32 s29, s13, -1
	s_add_i32 s49, 0, 0x10000
	s_cmp_eq_u32 s33, 12
	s_cselect_b32 s31, s17, s29
	s_cselect_b32 s30, s19, s28
	v_add_u32_e32 v143, s49, v146
	s_cselect_b32 s29, s21, s27
	s_cselect_b32 s28, s20, s25
	s_add_i32 s52, 0, 0x14000
	ds_read_b128 v[168:171], v143
	ds_read_b128 v[172:175], v143 offset:1024
	ds_read_b128 v[176:179], v143 offset:2048
	ds_read_b128 v[180:183], v143 offset:3072
	v_add_u32_e32 v143, s52, v146
	ds_read_b128 v[184:187], v143
	ds_read_b128 v[188:191], v143 offset:1024
	ds_read_b128 v[194:197], v143 offset:2048
	ds_read_b128 v[198:201], v143 offset:3072
	v_lshl_add_u64 v[144:145], s[12:13], 0, v[140:141]
	s_add_i32 m0, s39, 0xc000
	ds_read_b128 v[202:205], v166
	ds_read_b128 v[206:209], v166 offset:1024
	ds_read_b128 v[210:213], v166 offset:2048
	ds_read_b128 v[214:217], v166 offset:3072
	ds_read_b128 v[218:221], v166 offset:4096
	ds_read_b128 v[222:225], v166 offset:5120
	ds_read_b128 v[226:229], v166 offset:6144
	ds_read_b128 v[230:233], v166 offset:7168
	global_load_lds_dwordx4 v[144:145], off
	v_lshl_add_u64 v[144:145], s[12:13], 0, v[138:139]
	s_add_i32 m0, s39, 0xe000
	s_nop 0
	global_load_lds_dwordx4 v[144:145], off
	s_waitcnt vmcnt(8)
	s_waitcnt lgkmcnt(0)
	s_barrier
	v_mfma_f32_16x16x32_bf16 v[124:127], v[168:171], v[202:205], v[124:127]
	v_mfma_f32_16x16x32_bf16 v[120:123], v[176:179], v[202:205], v[120:123]
	v_mfma_f32_16x16x32_bf16 v[108:111], v[168:171], v[210:213], v[108:111]
	v_mfma_f32_16x16x32_bf16 v[104:107], v[176:179], v[210:213], v[104:107]
	v_mfma_f32_16x16x32_bf16 v[92:95], v[168:171], v[218:221], v[92:95]
	v_mfma_f32_16x16x32_bf16 v[88:91], v[176:179], v[218:221], v[88:91]
	v_mfma_f32_16x16x32_bf16 v[76:79], v[168:171], v[226:229], v[76:79]
	v_mfma_f32_16x16x32_bf16 v[72:75], v[176:179], v[226:229], v[72:75]
	v_mfma_f32_16x16x32_bf16 v[124:127], v[172:175], v[206:209], v[124:127]
	v_mfma_f32_16x16x32_bf16 v[120:123], v[180:183], v[206:209], v[120:123]
	v_mfma_f32_16x16x32_bf16 v[108:111], v[172:175], v[214:217], v[108:111]
	v_mfma_f32_16x16x32_bf16 v[104:107], v[180:183], v[214:217], v[104:107]
	v_mfma_f32_16x16x32_bf16 v[92:95], v[172:175], v[222:225], v[92:95]
	v_mfma_f32_16x16x32_bf16 v[88:91], v[180:183], v[222:225], v[88:91]
	v_mfma_f32_16x16x32_bf16 v[76:79], v[172:175], v[230:233], v[76:79]
	v_mfma_f32_16x16x32_bf16 v[72:75], v[180:183], v[230:233], v[72:75]
	v_mfma_f32_16x16x32_bf16 v[116:119], v[184:187], v[202:205], v[116:119]
	v_mfma_f32_16x16x32_bf16 v[112:115], v[194:197], v[202:205], v[112:115]
	v_mfma_f32_16x16x32_bf16 v[100:103], v[184:187], v[210:213], v[100:103]
	v_mfma_f32_16x16x32_bf16 v[96:99], v[194:197], v[210:213], v[96:99]
	v_mfma_f32_16x16x32_bf16 v[84:87], v[184:187], v[218:221], v[84:87]
	v_mfma_f32_16x16x32_bf16 v[80:83], v[194:197], v[218:221], v[80:83]
	v_mfma_f32_16x16x32_bf16 v[68:71], v[184:187], v[226:229], v[68:71]
	v_mfma_f32_16x16x32_bf16 v[64:67], v[194:197], v[226:229], v[64:67]
	v_mfma_f32_16x16x32_bf16 v[116:119], v[188:191], v[206:209], v[116:119]
	v_mfma_f32_16x16x32_bf16 v[112:115], v[198:201], v[206:209], v[112:115]
	v_mfma_f32_16x16x32_bf16 v[100:103], v[188:191], v[214:217], v[100:103]
	v_mfma_f32_16x16x32_bf16 v[96:99], v[198:201], v[214:217], v[96:99]
	v_mfma_f32_16x16x32_bf16 v[84:87], v[188:191], v[222:225], v[84:87]
	v_mfma_f32_16x16x32_bf16 v[80:83], v[198:201], v[222:225], v[80:83]
	v_mfma_f32_16x16x32_bf16 v[68:71], v[188:191], v[230:233], v[68:71]
	v_mfma_f32_16x16x32_bf16 v[64:67], v[198:201], v[230:233], v[64:67]
	s_barrier
	s_add_i32 s49, s49, s38
	v_lshl_add_u64 v[144:145], s[28:29], 0, v[130:131]
	s_mov_b32 m0, s49
	ds_read_b128 v[202:205], v166 offset:16384
	ds_read_b128 v[206:209], v166 offset:17408
	ds_read_b128 v[210:213], v166 offset:18432
	ds_read_b128 v[214:217], v166 offset:19456
	ds_read_b128 v[218:221], v166 offset:20480
	ds_read_b128 v[222:225], v166 offset:21504
	ds_read_b128 v[226:229], v166 offset:22528
	ds_read_b128 v[230:233], v166 offset:23552
	global_load_lds_dwordx4 v[144:145], off
	s_add_i32 m0, s49, 0x2000
	s_add_u32 s50, s28, 0x40000
	v_lshl_add_u64 v[234:235], s[28:29], 0, v[134:135]
	s_addc_u32 s51, s29, 0
	s_add_i32 s49, s52, s38
	global_load_lds_dwordx4 v[234:235], off
	v_lshl_add_u64 v[236:237], s[50:51], 0, v[130:131]
	s_mov_b32 m0, s49
	v_lshl_add_u64 v[238:239], s[30:31], 0, v[132:133]
	global_load_lds_dwordx4 v[236:237], off
	v_lshl_add_u64 v[236:237], s[50:51], 0, v[134:135]
	s_add_i32 m0, s49, 0x2000
	s_nop 0
	global_load_lds_dwordx4 v[236:237], off
	v_lshl_add_u64 v[236:237], s[30:31], 0, v[128:129]
	s_mov_b32 m0, s39
	s_nop 0
	global_load_lds_dwordx4 v[236:237], off
	s_mov_b32 m0, s42
	s_nop 0
	global_load_lds_dwordx4 v[238:239], off
	s_waitcnt vmcnt(8)
	s_waitcnt lgkmcnt(0)
	s_barrier
; #define PG8_STAGE(bufoff, gbase, voff) do { _Pragma("unroll") for (int _i = 0; _i < 2; ++_i) \
;         __builtin_amdgcn_global_load_lds((const unsigned*)((const char*)(gbase) + (voff)[_i]), (LAS unsigned*)(lds + (bufoff) + ldsw + _i * 8192), 16, 0, 0); } while (0)
; #define PG8_LDA(dst, b, h) do { _Pragma("unroll") for (int m = 0; m < 4; ++m) _Pragma("unroll") for (int k = 0; k < 2; ++k) dst[m][k] = *(const LAS bf16x8*)(lds + PG8_SA(b, h) + aoff + m * 2048 + k * 1024); } while (0)
; #define PG8_LDB(dst, b, h) do { _Pragma("unroll") for (int n = 0; n < 2; ++n) _Pragma("unroll") for (int k = 0; k < 2; ++k) dst[n][k] = *(const LAS bf16x8*)(lds + PG8_SB(b, h) + boff + n * 2048 + k * 1024); } while (0)
; #define PG8_MMA(ai, bj, At, Bt) do { __builtin_amdgcn_s_setprio(1); _Pragma("unroll") for (int m = 0; m < 4; ++m) _Pragma("unroll") for (int n = 0; n < 2; ++n) _Pragma("unroll") for (int k = 0; k < 2; ++k) \
;         acc[ai][bj][m][n] = __builtin_amdgcn_mfma_f32_16x16x32_bf16(Bt[n][k], At[m][k], acc[ai][bj][m][n], 0, 0, 0); __builtin_amdgcn_s_setprio(0); } while (0)
; #define PG8_WAIT_V(n) asm volatile("s_waitcnt vmcnt(" #n ")" ::: "memory")
; #define PG8_WAIT_L(n) asm volatile("s_waitcnt lgkmcnt(" #n ")" ::: "memory")
; #define PG8_BAR __builtin_amdgcn_s_barrier()
; #define PG8_SCHED __builtin_amdgcn_sched_barrier(0)
; template <class Epi>
; DI void gemm_phase(int wv, LAS unsigned char* lds, LAS unsigned char* scr, const Sched& S, const Epi& E) {
;     ...
;             PG8_WAIT_V(8); PG8_WAIT_L(0); PG8_BAR; PG8_MMA(1, 0, At, B0); PG8_MMA(1, 1, At, B1); PG8_BAR; PG8_SCHED;
;             PG8_LDB(B0, 1, 0); PG8_LDB(B1, 1, 1); PG8_SCHED; PG8_LDA(At, 1, 0); PG8_STAGE(PG8_SA(0, 1), a2 + hstepA, voffA);
;             PG8_WAIT_V(8); PG8_WAIT_L(0); PG8_BAR; PG8_MMA(0, 0, At, B0); PG8_MMA(0, 1, At, B1); PG8_BAR; PG8_SCHED;
	v_mfma_f32_16x16x32_bf16 v[60:63], v[168:171], v[202:205], v[60:63]
	v_mfma_f32_16x16x32_bf16 v[56:59], v[176:179], v[202:205], v[56:59]
	v_mfma_f32_16x16x32_bf16 v[44:47], v[168:171], v[210:213], v[44:47]
	v_mfma_f32_16x16x32_bf16 v[40:43], v[176:179], v[210:213], v[40:43]
	v_mfma_f32_16x16x32_bf16 v[28:31], v[168:171], v[218:221], v[28:31]
	v_mfma_f32_16x16x32_bf16 v[24:27], v[176:179], v[218:221], v[24:27]
	v_mfma_f32_16x16x32_bf16 v[12:15], v[168:171], v[226:229], v[12:15]
	v_mfma_f32_16x16x32_bf16 v[8:11], v[176:179], v[226:229], v[8:11]
	v_mfma_f32_16x16x32_bf16 v[60:63], v[172:175], v[206:209], v[60:63]
	v_mfma_f32_16x16x32_bf16 v[56:59], v[180:183], v[206:209], v[56:59]
	v_mfma_f32_16x16x32_bf16 v[44:47], v[172:175], v[214:217], v[44:47]
	v_mfma_f32_16x16x32_bf16 v[40:43], v[180:183], v[214:217], v[40:43]
	v_mfma_f32_16x16x32_bf16 v[28:31], v[172:175], v[222:225], v[28:31]
	v_mfma_f32_16x16x32_bf16 v[24:27], v[180:183], v[222:225], v[24:27]
	v_mfma_f32_16x16x32_bf16 v[12:15], v[172:175], v[230:233], v[12:15]
	v_mfma_f32_16x16x32_bf16 v[8:11], v[180:183], v[230:233], v[8:11]
	v_mfma_f32_16x16x32_bf16 v[52:55], v[184:187], v[202:205], v[52:55]
	v_mfma_f32_16x16x32_bf16 v[48:51], v[194:197], v[202:205], v[48:51]
	v_mfma_f32_16x16x32_bf16 v[36:39], v[184:187], v[210:213], v[36:39]
	v_mfma_f32_16x16x32_bf16 v[32:35], v[194:197], v[210:213], v[32:35]
	v_mfma_f32_16x16x32_bf16 v[20:23], v[184:187], v[218:221], v[20:23]
	v_mfma_f32_16x16x32_bf16 v[16:19], v[194:197], v[218:221], v[16:19]
	v_mfma_f32_16x16x32_bf16 v[4:7], v[184:187], v[226:229], v[4:7]
	v_mfma_f32_16x16x32_bf16 v[0:3], v[194:197], v[226:229], v[0:3]
	v_mfma_f32_16x16x32_bf16 v[52:55], v[188:191], v[206:209], v[52:55]
	v_mfma_f32_16x16x32_bf16 v[48:51], v[198:201], v[206:209], v[48:51]
	v_mfma_f32_16x16x32_bf16 v[36:39], v[188:191], v[214:217], v[36:39]
	v_mfma_f32_16x16x32_bf16 v[32:35], v[198:201], v[214:217], v[32:35]
	v_mfma_f32_16x16x32_bf16 v[20:23], v[188:191], v[222:225], v[20:23]
	v_mfma_f32_16x16x32_bf16 v[16:19], v[198:201], v[222:225], v[16:19]
	v_mfma_f32_16x16x32_bf16 v[4:7], v[188:191], v[230:233], v[4:7]
	v_mfma_f32_16x16x32_bf16 v[0:3], v[198:201], v[230:233], v[0:3]
	s_barrier
	s_add_i32 s49, 0, 0x18000
	v_add_u32_e32 v143, s49, v146
	s_add_i32 s50, 0, 0x1c000
	ds_read_b128 v[168:171], v143
	ds_read_b128 v[172:175], v143 offset:1024
	ds_read_b128 v[176:179], v143 offset:2048
	ds_read_b128 v[180:183], v143 offset:3072
	v_add_u32_e32 v143, s50, v146
	ds_read_b128 v[184:187], v143
	ds_read_b128 v[188:191], v143 offset:1024
	ds_read_b128 v[194:197], v143 offset:2048
	ds_read_b128 v[198:201], v143 offset:3072
	s_add_u32 s30, s30, 0x40000
	s_addc_u32 s31, s31, 0
	s_mov_b32 m0, s43
	v_lshl_add_u64 v[240:241], s[30:31], 0, v[128:129]
	ds_read_b128 v[202:205], v166 offset:32768
	ds_read_b128 v[206:209], v166 offset:33792
	ds_read_b128 v[210:213], v166 offset:34816
	ds_read_b128 v[214:217], v166 offset:35840
	ds_read_b128 v[218:221], v166 offset:36864
	ds_read_b128 v[222:225], v166 offset:37888
	ds_read_b128 v[226:229], v166 offset:38912
	ds_read_b128 v[230:233], v166 offset:39936
	global_load_lds_dwordx4 v[240:241], off
	v_lshl_add_u64 v[240:241], s[30:31], 0, v[132:133]
	s_mov_b32 m0, s44
	s_nop 0
	global_load_lds_dwordx4 v[240:241], off
	s_waitcnt vmcnt(8)
	s_waitcnt lgkmcnt(0)
	s_barrier
	v_mfma_f32_16x16x32_bf16 v[124:127], v[168:171], v[202:205], v[124:127]
	v_mfma_f32_16x16x32_bf16 v[120:123], v[176:179], v[202:205], v[120:123]
	v_mfma_f32_16x16x32_bf16 v[108:111], v[168:171], v[210:213], v[108:111]
	v_mfma_f32_16x16x32_bf16 v[104:107], v[176:179], v[210:213], v[104:107]
	v_mfma_f32_16x16x32_bf16 v[92:95], v[168:171], v[218:221], v[92:95]
	v_mfma_f32_16x16x32_bf16 v[88:91], v[176:179], v[218:221], v[88:91]
	v_mfma_f32_16x16x32_bf16 v[76:79], v[168:171], v[226:229], v[76:79]
	v_mfma_f32_16x16x32_bf16 v[72:75], v[176:179], v[226:229], v[72:75]
	v_mfma_f32_16x16x32_bf16 v[124:127], v[172:175], v[206:209], v[124:127]
	v_mfma_f32_16x16x32_bf16 v[120:123], v[180:183], v[206:209], v[120:123]
	v_mfma_f32_16x16x32_bf16 v[108:111], v[172:175], v[214:217], v[108:111]
	v_mfma_f32_16x16x32_bf16 v[104:107], v[180:183], v[214:217], v[104:107]
	v_mfma_f32_16x16x32_bf16 v[92:95], v[172:175], v[222:225], v[92:95]
	v_mfma_f32_16x16x32_bf16 v[88:91], v[180:183], v[222:225], v[88:91]
	v_mfma_f32_16x16x32_bf16 v[76:79], v[172:175], v[230:233], v[76:79]
	v_mfma_f32_16x16x32_bf16 v[72:75], v[180:183], v[230:233], v[72:75]
	v_mfma_f32_16x16x32_bf16 v[116:119], v[184:187], v[202:205], v[116:119]
	v_mfma_f32_16x16x32_bf16 v[112:115], v[194:197], v[202:205], v[112:115]
	v_mfma_f32_16x16x32_bf16 v[100:103], v[184:187], v[210:213], v[100:103]
	v_mfma_f32_16x16x32_bf16 v[96:99], v[194:197], v[210:213], v[96:99]
	v_mfma_f32_16x16x32_bf16 v[84:87], v[184:187], v[218:221], v[84:87]
	v_mfma_f32_16x16x32_bf16 v[80:83], v[194:197], v[218:221], v[80:83]
	v_mfma_f32_16x16x32_bf16 v[68:71], v[184:187], v[226:229], v[68:71]
	v_mfma_f32_16x16x32_bf16 v[64:67], v[194:197], v[226:229], v[64:67]
	v_mfma_f32_16x16x32_bf16 v[116:119], v[188:191], v[206:209], v[116:119]
	v_mfma_f32_16x16x32_bf16 v[112:115], v[198:201], v[206:209], v[112:115]
	v_mfma_f32_16x16x32_bf16 v[100:103], v[188:191], v[214:217], v[100:103]
	v_mfma_f32_16x16x32_bf16 v[96:99], v[198:201], v[214:217], v[96:99]
	v_mfma_f32_16x16x32_bf16 v[84:87], v[188:191], v[222:225], v[84:87]
	v_mfma_f32_16x16x32_bf16 v[80:83], v[198:201], v[222:225], v[80:83]
	v_mfma_f32_16x16x32_bf16 v[68:71], v[188:191], v[230:233], v[68:71]
	v_mfma_f32_16x16x32_bf16 v[64:67], v[198:201], v[230:233], v[64:67]
	s_barrier
; #define PG8_STAGE(bufoff, gbase, voff) do { _Pragma("unroll") for (int _i = 0; _i < 2; ++_i) \
;         __builtin_amdgcn_global_load_lds((const unsigned*)((const char*)(gbase) + (voff)[_i]), (LAS unsigned*)(lds + (bufoff) + ldsw + _i * 8192), 16, 0, 0); } while (0)
; #define PG8_LDA(dst, b, h) do { _Pragma("unroll") for (int m = 0; m < 4; ++m) _Pragma("unroll") for (int k = 0; k < 2; ++k) dst[m][k] = *(const LAS bf16x8*)(lds + PG8_SA(b, h) + aoff + m * 2048 + k * 1024); } while (0)
; #define PG8_MMA(ai, bj, At, Bt) do { __builtin_amdgcn_s_setprio(1); _Pragma("unroll") for (int m = 0; m < 4; ++m) _Pragma("unroll") for (int n = 0; n < 2; ++n) _Pragma("unroll") for (int k = 0; k < 2; ++k) \
;         acc[ai][bj][m][n] = __builtin_amdgcn_mfma_f32_16x16x32_bf16(Bt[n][k], At[m][k], acc[ai][bj][m][n], 0, 0, 0); __builtin_amdgcn_s_setprio(0); } while (0)
; #define PG8_WAIT_V(n) asm volatile("s_waitcnt vmcnt(" #n ")" ::: "memory")
; #define PG8_WAIT_L(n) asm volatile("s_waitcnt lgkmcnt(" #n ")" ::: "memory")
; #define PG8_BAR __builtin_amdgcn_s_barrier()
; #define PG8_SCHED __builtin_amdgcn_sched_barrier(0)
; template <class Epi>
; DI void gemm_phase(int wv, LAS unsigned char* lds, LAS unsigned char* scr, const Sched& S, const Epi& E) {
;     ...
;             PG8_LDA(At, 1, 1); PG8_STAGE(PG8_SB(1, 0), b3, voffB); PG8_STAGE(PG8_SB(1, 1), b3 + hstepB, voffB); PG8_STAGE(PG8_SA(1, 0), a3, voffA);
;             PG8_WAIT_V(8); PG8_WAIT_L(0); PG8_BAR; PG8_MMA(1, 0, At, B0); PG8_MMA(1, 1, At, B1); PG8_BAR; PG8_SCHED;
;         }
;         if (wr == 0) PG8_BAR;
	s_add_i32 s30, s49, s38
	v_lshl_add_u64 v[144:145], v[144:145], 0, s[2:3]
	s_mov_b32 m0, s30
	ds_read_b128 v[202:205], v166 offset:49152
	ds_read_b128 v[206:209], v166 offset:50176
	ds_read_b128 v[210:213], v166 offset:51200
	ds_read_b128 v[214:217], v166 offset:52224
	ds_read_b128 v[218:221], v166 offset:53248
	ds_read_b128 v[222:225], v166 offset:54272
	ds_read_b128 v[226:229], v166 offset:55296
	ds_read_b128 v[230:233], v166 offset:56320
	global_load_lds_dwordx4 v[144:145], off
	s_add_i32 m0, s30, 0x2000
	s_add_u32 s28, s28, 0x40080
	v_lshl_add_u64 v[144:145], v[234:235], 0, s[2:3]
	s_addc_u32 s29, s29, 0
	s_add_i32 s30, s50, s38
	global_load_lds_dwordx4 v[144:145], off
	v_lshl_add_u64 v[144:145], s[28:29], 0, v[130:131]
	s_mov_b32 m0, s30
	s_nop 0
	global_load_lds_dwordx4 v[144:145], off
	v_lshl_add_u64 v[144:145], s[28:29], 0, v[134:135]
	s_add_i32 m0, s30, 0x2000
	s_nop 0
	global_load_lds_dwordx4 v[144:145], off
	v_lshl_add_u64 v[144:145], v[236:237], 0, s[2:3]
	s_mov_b32 m0, s45
	s_nop 0
	global_load_lds_dwordx4 v[144:145], off
	v_lshl_add_u64 v[144:145], v[238:239], 0, s[2:3]
	s_mov_b32 m0, s46
	s_nop 0
	global_load_lds_dwordx4 v[144:145], off
	s_waitcnt vmcnt(8)
	s_waitcnt lgkmcnt(0)
	s_barrier
	v_mfma_f32_16x16x32_bf16 v[60:63], v[168:171], v[202:205], v[60:63]
	v_mfma_f32_16x16x32_bf16 v[56:59], v[176:179], v[202:205], v[56:59]
	v_mfma_f32_16x16x32_bf16 v[44:47], v[168:171], v[210:213], v[44:47]
	v_mfma_f32_16x16x32_bf16 v[40:43], v[176:179], v[210:213], v[40:43]
	v_mfma_f32_16x16x32_bf16 v[28:31], v[168:171], v[218:221], v[28:31]
	v_mfma_f32_16x16x32_bf16 v[24:27], v[176:179], v[218:221], v[24:27]
	v_mfma_f32_16x16x32_bf16 v[12:15], v[168:171], v[226:229], v[12:15]
	v_mfma_f32_16x16x32_bf16 v[8:11], v[176:179], v[226:229], v[8:11]
	v_mfma_f32_16x16x32_bf16 v[60:63], v[172:175], v[206:209], v[60:63]
	v_mfma_f32_16x16x32_bf16 v[56:59], v[180:183], v[206:209], v[56:59]
	v_mfma_f32_16x16x32_bf16 v[44:47], v[172:175], v[214:217], v[44:47]
	v_mfma_f32_16x16x32_bf16 v[40:43], v[180:183], v[214:217], v[40:43]
	v_mfma_f32_16x16x32_bf16 v[28:31], v[172:175], v[222:225], v[28:31]
	v_mfma_f32_16x16x32_bf16 v[24:27], v[180:183], v[222:225], v[24:27]
	v_mfma_f32_16x16x32_bf16 v[12:15], v[172:175], v[230:233], v[12:15]
	v_mfma_f32_16x16x32_bf16 v[8:11], v[180:183], v[230:233], v[8:11]
	v_mfma_f32_16x16x32_bf16 v[52:55], v[184:187], v[202:205], v[52:55]
	v_mfma_f32_16x16x32_bf16 v[48:51], v[194:197], v[202:205], v[48:51]
	v_mfma_f32_16x16x32_bf16 v[36:39], v[184:187], v[210:213], v[36:39]
	v_mfma_f32_16x16x32_bf16 v[32:35], v[194:197], v[210:213], v[32:35]
	v_mfma_f32_16x16x32_bf16 v[20:23], v[184:187], v[218:221], v[20:23]
	v_mfma_f32_16x16x32_bf16 v[16:19], v[194:197], v[218:221], v[16:19]
	v_mfma_f32_16x16x32_bf16 v[4:7], v[184:187], v[226:229], v[4:7]
	v_mfma_f32_16x16x32_bf16 v[0:3], v[194:197], v[226:229], v[0:3]
	v_mfma_f32_16x16x32_bf16 v[52:55], v[188:191], v[206:209], v[52:55]
	v_mfma_f32_16x16x32_bf16 v[48:51], v[198:201], v[206:209], v[48:51]
	v_mfma_f32_16x16x32_bf16 v[36:39], v[188:191], v[214:217], v[36:39]
	v_mfma_f32_16x16x32_bf16 v[32:35], v[198:201], v[214:217], v[32:35]
	v_mfma_f32_16x16x32_bf16 v[20:23], v[188:191], v[222:225], v[20:23]
	v_mfma_f32_16x16x32_bf16 v[16:19], v[198:201], v[222:225], v[16:19]
	v_mfma_f32_16x16x32_bf16 v[4:7], v[188:191], v[230:233], v[4:7]
	v_mfma_f32_16x16x32_bf16 v[0:3], v[198:201], v[230:233], v[0:3]
	s_barrier
	s_add_i32 s33, s33, 2
	s_add_u32 s25, s25, 0x100
	s_addc_u32 s27, s27, 0
	s_add_u32 s12, s12, 0x100
	s_addc_u32 s13, s13, 0
	s_cmp_gt_u32 s33, 13
	s_cbranch_scc0 .LBB0_588
	s_and_b64 vcc, exec, s[14:15]
	s_cbranch_vccz .LBB0_591
	s_barrier

; #define PG8_STAGE(bufoff, gbase, voff) do { _Pragma("unroll") for (int _i = 0; _i < 2; ++_i) \
;         __builtin_amdgcn_global_load_lds((const unsigned*)((const char*)(gbase) + (voff)[_i]), (LAS unsigned*)(lds + (bufoff) + ldsw + _i * 8192), 16, 0, 0); } while (0)
; #define PG8_LDA(dst, b, h) do { _Pragma("unroll") for (int m = 0; m < 4; ++m) _Pragma("unroll") for (int k = 0; k < 2; ++k) dst[m][k] = *(const LAS bf16x8*)(lds + PG8_SA(b, h) + aoff + m * 2048 + k * 1024); } while (0)
; #define PG8_LDB(dst, b, h) do { _Pragma("unroll") for (int n = 0; n < 2; ++n) _Pragma("unroll") for (int k = 0; k < 2; ++k) dst[n][k] = *(const LAS bf16x8*)(lds + PG8_SB(b, h) + boff + n * 2048 + k * 1024); } while (0)
; #define PG8_MMA(ai, bj, At, Bt) do { __builtin_amdgcn_s_setprio(1); _Pragma("unroll") for (int m = 0; m < 4; ++m) _Pragma("unroll") for (int n = 0; n < 2; ++n) _Pragma("unroll") for (int k = 0; k < 2; ++k) \
;         acc[ai][bj][m][n] = __builtin_amdgcn_mfma_f32_16x16x32_bf16(Bt[n][k], At[m][k], acc[ai][bj][m][n], 0, 0, 0); __builtin_amdgcn_s_setprio(0); } while (0)
; #define PG8_WAIT_V(n) asm volatile("s_waitcnt vmcnt(" #n ")" ::: "memory")
; #define PG8_WAIT_L(n) asm volatile("s_waitcnt lgkmcnt(" #n ")" ::: "memory")
; #define PG8_BAR __builtin_amdgcn_s_barrier()
; #define PG8_SCHED __builtin_amdgcn_sched_barrier(0)
; template <class Epi>
; DI void gemm_phase(int wv, LAS unsigned char* lds, LAS unsigned char* scr, const Sched& S, const Epi& E) {
;     ...
;             const bool last = (t == nt - 2);
;             const char* a1 = cA + (size_t)(t + 1) * kstep;
;             const char* a2 = last ? nA : cA + (size_t)(t + 2) * kstep; const char* b2 = last ? nB : cB + (size_t)(t + 2) * kstep;
;             const char* a3 = a2 + kstep; const char* b3 = b2 + kstep;
;             PG8_LDB(B0, 0, 0); PG8_LDB(B1, 0, 1); PG8_SCHED; PG8_LDA(At, 0, 0); PG8_STAGE(PG8_SA(1, 1), a1 + hstepA, voffA);
;             PG8_WAIT_V(8); PG8_WAIT_L(0); PG8_BAR; PG8_MMA(0, 0, At, B0); PG8_MMA(0, 1, At, B1); PG8_BAR; PG8_SCHED;
;             PG8_LDA(At, 0, 1); PG8_STAGE(PG8_SB(0, 0), b2, voffB); PG8_STAGE(PG8_SB(0, 1), b2 + hstepB, voffB); PG8_STAGE(PG8_SA(0, 0), a2, voffA);
.LBB0_684:
	s_add_u32 s24, s8, 0xfffc0080
	s_addc_u32 s25, s9, -1
	s_add_i32 s46, 0, 0x10000
	s_cmp_eq_u32 s45, 12
	s_cselect_b32 s27, s11, s25
	s_cselect_b32 s26, s15, s24
	v_add_u32_e32 v143, s46, v144
	s_cselect_b32 s25, s21, s19
	s_cselect_b32 s24, s20, s17
	s_add_i32 s48, 0, 0x14000
	ds_read_b128 v[146:149], v143
	ds_read_b128 v[150:153], v143 offset:1024
	ds_read_b128 v[154:157], v143 offset:2048
	ds_read_b128 v[158:161], v143 offset:3072
	v_add_u32_e32 v143, s48, v144
	ds_read_b128 v[162:165], v143
	ds_read_b128 v[166:169], v143 offset:1024
	ds_read_b128 v[170:173], v143 offset:2048
	ds_read_b128 v[174:177], v143 offset:3072
	v_lshl_add_u64 v[190:191], s[8:9], 0, v[140:141]
	s_add_i32 m0, s34, 0xc000
	ds_read_b128 v[178:181], v145
	ds_read_b128 v[182:185], v145 offset:1024
	ds_read_b128 v[186:189], v145 offset:2048
	ds_read_b128 v[194:197], v145 offset:3072
	ds_read_b128 v[198:201], v145 offset:4096
	ds_read_b128 v[202:205], v145 offset:5120
	ds_read_b128 v[206:209], v145 offset:6144
	ds_read_b128 v[210:213], v145 offset:7168
	global_load_lds_dwordx4 v[190:191], off
	v_lshl_add_u64 v[190:191], s[8:9], 0, v[138:139]
	s_add_i32 m0, s34, 0xe000
	s_nop 0
	global_load_lds_dwordx4 v[190:191], off
	s_waitcnt vmcnt(8)
	s_waitcnt lgkmcnt(0)
	s_barrier
	v_mfma_f32_16x16x32_bf16 v[124:127], v[146:149], v[178:181], v[124:127]
	v_mfma_f32_16x16x32_bf16 v[120:123], v[154:157], v[178:181], v[120:123]
	v_mfma_f32_16x16x32_bf16 v[116:119], v[146:149], v[186:189], v[116:119]
	v_mfma_f32_16x16x32_bf16 v[112:115], v[154:157], v[186:189], v[112:115]
	v_mfma_f32_16x16x32_bf16 v[100:103], v[146:149], v[198:201], v[100:103]
	v_mfma_f32_16x16x32_bf16 v[96:99], v[154:157], v[198:201], v[96:99]
	v_mfma_f32_16x16x32_bf16 v[84:87], v[146:149], v[206:209], v[84:87]
	v_mfma_f32_16x16x32_bf16 v[80:83], v[154:157], v[206:209], v[80:83]
	v_mfma_f32_16x16x32_bf16 v[124:127], v[150:153], v[182:185], v[124:127]
	v_mfma_f32_16x16x32_bf16 v[120:123], v[158:161], v[182:185], v[120:123]
	v_mfma_f32_16x16x32_bf16 v[116:119], v[150:153], v[194:197], v[116:119]
	v_mfma_f32_16x16x32_bf16 v[112:115], v[158:161], v[194:197], v[112:115]
	v_mfma_f32_16x16x32_bf16 v[100:103], v[150:153], v[202:205], v[100:103]
	v_mfma_f32_16x16x32_bf16 v[96:99], v[158:161], v[202:205], v[96:99]
	v_mfma_f32_16x16x32_bf16 v[84:87], v[150:153], v[210:213], v[84:87]
	v_mfma_f32_16x16x32_bf16 v[80:83], v[158:161], v[210:213], v[80:83]
	v_mfma_f32_16x16x32_bf16 v[108:111], v[162:165], v[178:181], v[108:111]
	v_mfma_f32_16x16x32_bf16 v[104:107], v[170:173], v[178:181], v[104:107]
	v_mfma_f32_16x16x32_bf16 v[92:95], v[162:165], v[186:189], v[92:95]
	v_mfma_f32_16x16x32_bf16 v[88:91], v[170:173], v[186:189], v[88:91]
	v_mfma_f32_16x16x32_bf16 v[76:79], v[162:165], v[198:201], v[76:79]
	v_mfma_f32_16x16x32_bf16 v[72:75], v[170:173], v[198:201], v[72:75]
	v_mfma_f32_16x16x32_bf16 v[68:71], v[162:165], v[206:209], v[68:71]
	v_mfma_f32_16x16x32_bf16 v[64:67], v[170:173], v[206:209], v[64:67]
	v_mfma_f32_16x16x32_bf16 v[108:111], v[166:169], v[182:185], v[108:111]
	v_mfma_f32_16x16x32_bf16 v[104:107], v[174:177], v[182:185], v[104:107]
	v_mfma_f32_16x16x32_bf16 v[92:95], v[166:169], v[194:197], v[92:95]
	v_mfma_f32_16x16x32_bf16 v[88:91], v[174:177], v[194:197], v[88:91]
	v_mfma_f32_16x16x32_bf16 v[76:79], v[166:169], v[202:205], v[76:79]
	v_mfma_f32_16x16x32_bf16 v[72:75], v[174:177], v[202:205], v[72:75]
	v_mfma_f32_16x16x32_bf16 v[68:71], v[166:169], v[210:213], v[68:71]
	v_mfma_f32_16x16x32_bf16 v[64:67], v[174:177], v[210:213], v[64:67]
	s_barrier
	s_add_i32 s46, s46, s33
	v_lshl_add_u64 v[190:191], s[24:25], 0, v[132:133]
	s_mov_b32 m0, s46
	ds_read_b128 v[178:181], v145 offset:16384
	ds_read_b128 v[182:185], v145 offset:17408
	ds_read_b128 v[186:189], v145 offset:18432
	ds_read_b128 v[194:197], v145 offset:19456
	ds_read_b128 v[198:201], v145 offset:20480
	ds_read_b128 v[202:205], v145 offset:21504
	ds_read_b128 v[206:209], v145 offset:22528
	ds_read_b128 v[210:213], v145 offset:23552
	global_load_lds_dwordx4 v[190:191], off
	s_add_i32 m0, s46, 0x2000
	s_add_u32 s46, s24, 0x40000
	v_lshl_add_u64 v[214:215], s[24:25], 0, v[128:129]
	s_addc_u32 s47, s25, 0
	s_add_i32 s48, s48, s33
	global_load_lds_dwordx4 v[214:215], off
	v_lshl_add_u64 v[216:217], s[46:47], 0, v[132:133]
	s_mov_b32 m0, s48
	v_lshl_add_u64 v[218:219], s[26:27], 0, v[130:131]
	global_load_lds_dwordx4 v[216:217], off
	v_lshl_add_u64 v[216:217], s[46:47], 0, v[128:129]
	s_add_i32 m0, s48, 0x2000
	s_nop 0
	global_load_lds_dwordx4 v[216:217], off
	v_lshl_add_u64 v[216:217], s[26:27], 0, v[134:135]
	s_mov_b32 m0, s34
	s_nop 0
	global_load_lds_dwordx4 v[216:217], off
	s_mov_b32 m0, s35
	s_nop 0
	global_load_lds_dwordx4 v[218:219], off
	s_waitcnt vmcnt(8)
	s_waitcnt lgkmcnt(0)
	s_barrier
; #define PG8_STAGE(bufoff, gbase, voff) do { _Pragma("unroll") for (int _i = 0; _i < 2; ++_i) \
;         __builtin_amdgcn_global_load_lds((const unsigned*)((const char*)(gbase) + (voff)[_i]), (LAS unsigned*)(lds + (bufoff) + ldsw + _i * 8192), 16, 0, 0); } while (0)
; #define PG8_LDA(dst, b, h) do { _Pragma("unroll") for (int m = 0; m < 4; ++m) _Pragma("unroll") for (int k = 0; k < 2; ++k) dst[m][k] = *(const LAS bf16x8*)(lds + PG8_SA(b, h) + aoff + m * 2048 + k * 1024); } while (0)
; #define PG8_LDB(dst, b, h) do { _Pragma("unroll") for (int n = 0; n < 2; ++n) _Pragma("unroll") for (int k = 0; k < 2; ++k) dst[n][k] = *(const LAS bf16x8*)(lds + PG8_SB(b, h) + boff + n * 2048 + k * 1024); } while (0)
; #define PG8_MMA(ai, bj, At, Bt) do { __builtin_amdgcn_s_setprio(1); _Pragma("unroll") for (int m = 0; m < 4; ++m) _Pragma("unroll") for (int n = 0; n < 2; ++n) _Pragma("unroll") for (int k = 0; k < 2; ++k) \
;         acc[ai][bj][m][n] = __builtin_amdgcn_mfma_f32_16x16x32_bf16(Bt[n][k], At[m][k], acc[ai][bj][m][n], 0, 0, 0); __builtin_amdgcn_s_setprio(0); } while (0)
; #define PG8_WAIT_V(n) asm volatile("s_waitcnt vmcnt(" #n ")" ::: "memory")
; #define PG8_WAIT_L(n) asm volatile("s_waitcnt lgkmcnt(" #n ")" ::: "memory")
; #define PG8_BAR __builtin_amdgcn_s_barrier()
; #define PG8_SCHED __builtin_amdgcn_sched_barrier(0)
; template <class Epi>
; DI void gemm_phase(int wv, LAS unsigned char* lds, LAS unsigned char* scr, const Sched& S, const Epi& E) {
;     ...
;             PG8_WAIT_V(8); PG8_WAIT_L(0); PG8_BAR; PG8_MMA(1, 0, At, B0); PG8_MMA(1, 1, At, B1); PG8_BAR; PG8_SCHED;
;             PG8_LDB(B0, 1, 0); PG8_LDB(B1, 1, 1); PG8_SCHED; PG8_LDA(At, 1, 0); PG8_STAGE(PG8_SA(0, 1), a2 + hstepA, voffA);
;             PG8_WAIT_V(8); PG8_WAIT_L(0); PG8_BAR; PG8_MMA(0, 0, At, B0); PG8_MMA(0, 1, At, B1); PG8_BAR; PG8_SCHED;
	v_mfma_f32_16x16x32_bf16 v[60:63], v[146:149], v[178:181], v[60:63]
	v_mfma_f32_16x16x32_bf16 v[56:59], v[154:157], v[178:181], v[56:59]
	v_mfma_f32_16x16x32_bf16 v[52:55], v[146:149], v[186:189], v[52:55]
	v_mfma_f32_16x16x32_bf16 v[48:51], v[154:157], v[186:189], v[48:51]
	v_mfma_f32_16x16x32_bf16 v[36:39], v[146:149], v[198:201], v[36:39]
	v_mfma_f32_16x16x32_bf16 v[32:35], v[154:157], v[198:201], v[32:35]
	v_mfma_f32_16x16x32_bf16 v[20:23], v[146:149], v[206:209], v[20:23]
	v_mfma_f32_16x16x32_bf16 v[16:19], v[154:157], v[206:209], v[16:19]
	v_mfma_f32_16x16x32_bf16 v[60:63], v[150:153], v[182:185], v[60:63]
	v_mfma_f32_16x16x32_bf16 v[56:59], v[158:161], v[182:185], v[56:59]
	v_mfma_f32_16x16x32_bf16 v[52:55], v[150:153], v[194:197], v[52:55]
	v_mfma_f32_16x16x32_bf16 v[48:51], v[158:161], v[194:197], v[48:51]
	v_mfma_f32_16x16x32_bf16 v[36:39], v[150:153], v[202:205], v[36:39]
	v_mfma_f32_16x16x32_bf16 v[32:35], v[158:161], v[202:205], v[32:35]
	v_mfma_f32_16x16x32_bf16 v[20:23], v[150:153], v[210:213], v[20:23]
	v_mfma_f32_16x16x32_bf16 v[16:19], v[158:161], v[210:213], v[16:19]
	v_mfma_f32_16x16x32_bf16 v[44:47], v[162:165], v[178:181], v[44:47]
	v_mfma_f32_16x16x32_bf16 v[40:43], v[170:173], v[178:181], v[40:43]
	v_mfma_f32_16x16x32_bf16 v[28:31], v[162:165], v[186:189], v[28:31]
	v_mfma_f32_16x16x32_bf16 v[24:27], v[170:173], v[186:189], v[24:27]
	v_mfma_f32_16x16x32_bf16 v[12:15], v[162:165], v[198:201], v[12:15]
	v_mfma_f32_16x16x32_bf16 v[8:11], v[170:173], v[198:201], v[8:11]
	v_mfma_f32_16x16x32_bf16 v[4:7], v[162:165], v[206:209], v[4:7]
	v_mfma_f32_16x16x32_bf16 v[0:3], v[170:173], v[206:209], v[0:3]
	v_mfma_f32_16x16x32_bf16 v[44:47], v[166:169], v[182:185], v[44:47]
	v_mfma_f32_16x16x32_bf16 v[40:43], v[174:177], v[182:185], v[40:43]
	v_mfma_f32_16x16x32_bf16 v[28:31], v[166:169], v[194:197], v[28:31]
	v_mfma_f32_16x16x32_bf16 v[24:27], v[174:177], v[194:197], v[24:27]
	v_mfma_f32_16x16x32_bf16 v[12:15], v[166:169], v[202:205], v[12:15]
	v_mfma_f32_16x16x32_bf16 v[8:11], v[174:177], v[202:205], v[8:11]
	v_mfma_f32_16x16x32_bf16 v[4:7], v[166:169], v[210:213], v[4:7]
	v_mfma_f32_16x16x32_bf16 v[0:3], v[174:177], v[210:213], v[0:3]
	s_barrier
	s_add_i32 s46, 0, 0x18000
	v_add_u32_e32 v143, s46, v144
	s_add_i32 s47, 0, 0x1c000
	ds_read_b128 v[146:149], v143
	ds_read_b128 v[150:153], v143 offset:1024
	ds_read_b128 v[154:157], v143 offset:2048
	ds_read_b128 v[158:161], v143 offset:3072
	v_add_u32_e32 v143, s47, v144
	ds_read_b128 v[162:165], v143
	ds_read_b128 v[166:169], v143 offset:1024
	ds_read_b128 v[170:173], v143 offset:2048
	ds_read_b128 v[174:177], v143 offset:3072
	s_add_u32 s26, s26, 0x40000
	s_addc_u32 s27, s27, 0
	s_mov_b32 m0, s36
	v_lshl_add_u64 v[220:221], s[26:27], 0, v[134:135]
	ds_read_b128 v[178:181], v145 offset:32768
	ds_read_b128 v[182:185], v145 offset:33792
	ds_read_b128 v[186:189], v145 offset:34816
	ds_read_b128 v[194:197], v145 offset:35840
	ds_read_b128 v[198:201], v145 offset:36864
	ds_read_b128 v[202:205], v145 offset:37888
	ds_read_b128 v[206:209], v145 offset:38912
	ds_read_b128 v[210:213], v145 offset:39936
	global_load_lds_dwordx4 v[220:221], off
	v_lshl_add_u64 v[220:221], s[26:27], 0, v[130:131]
	s_mov_b32 m0, s37
	s_nop 0
	global_load_lds_dwordx4 v[220:221], off
	s_waitcnt vmcnt(8)
	s_waitcnt lgkmcnt(0)
	s_barrier
	v_mfma_f32_16x16x32_bf16 v[124:127], v[146:149], v[178:181], v[124:127]
	v_mfma_f32_16x16x32_bf16 v[120:123], v[154:157], v[178:181], v[120:123]
	v_mfma_f32_16x16x32_bf16 v[116:119], v[146:149], v[186:189], v[116:119]
	v_mfma_f32_16x16x32_bf16 v[112:115], v[154:157], v[186:189], v[112:115]
	v_mfma_f32_16x16x32_bf16 v[100:103], v[146:149], v[198:201], v[100:103]
	v_mfma_f32_16x16x32_bf16 v[96:99], v[154:157], v[198:201], v[96:99]
	v_mfma_f32_16x16x32_bf16 v[84:87], v[146:149], v[206:209], v[84:87]
	v_mfma_f32_16x16x32_bf16 v[80:83], v[154:157], v[206:209], v[80:83]
	v_mfma_f32_16x16x32_bf16 v[124:127], v[150:153], v[182:185], v[124:127]
	v_mfma_f32_16x16x32_bf16 v[120:123], v[158:161], v[182:185], v[120:123]
	v_mfma_f32_16x16x32_bf16 v[116:119], v[150:153], v[194:197], v[116:119]
	v_mfma_f32_16x16x32_bf16 v[112:115], v[158:161], v[194:197], v[112:115]
	v_mfma_f32_16x16x32_bf16 v[100:103], v[150:153], v[202:205], v[100:103]
	v_mfma_f32_16x16x32_bf16 v[96:99], v[158:161], v[202:205], v[96:99]
	v_mfma_f32_16x16x32_bf16 v[84:87], v[150:153], v[210:213], v[84:87]
	v_mfma_f32_16x16x32_bf16 v[80:83], v[158:161], v[210:213], v[80:83]
	v_mfma_f32_16x16x32_bf16 v[108:111], v[162:165], v[178:181], v[108:111]
	v_mfma_f32_16x16x32_bf16 v[104:107], v[170:173], v[178:181], v[104:107]
	v_mfma_f32_16x16x32_bf16 v[92:95], v[162:165], v[186:189], v[92:95]
	v_mfma_f32_16x16x32_bf16 v[88:91], v[170:173], v[186:189], v[88:91]
	v_mfma_f32_16x16x32_bf16 v[76:79], v[162:165], v[198:201], v[76:79]
	v_mfma_f32_16x16x32_bf16 v[72:75], v[170:173], v[198:201], v[72:75]
	v_mfma_f32_16x16x32_bf16 v[68:71], v[162:165], v[206:209], v[68:71]
	v_mfma_f32_16x16x32_bf16 v[64:67], v[170:173], v[206:209], v[64:67]
	v_mfma_f32_16x16x32_bf16 v[108:111], v[166:169], v[182:185], v[108:111]
	v_mfma_f32_16x16x32_bf16 v[104:107], v[174:177], v[182:185], v[104:107]
	v_mfma_f32_16x16x32_bf16 v[92:95], v[166:169], v[194:197], v[92:95]
	v_mfma_f32_16x16x32_bf16 v[88:91], v[174:177], v[194:197], v[88:91]
	v_mfma_f32_16x16x32_bf16 v[76:79], v[166:169], v[202:205], v[76:79]
	v_mfma_f32_16x16x32_bf16 v[72:75], v[174:177], v[202:205], v[72:75]
	v_mfma_f32_16x16x32_bf16 v[68:71], v[166:169], v[210:213], v[68:71]
	v_mfma_f32_16x16x32_bf16 v[64:67], v[174:177], v[210:213], v[64:67]
	s_barrier
; #define PG8_STAGE(bufoff, gbase, voff) do { _Pragma("unroll") for (int _i = 0; _i < 2; ++_i) \
;         __builtin_amdgcn_global_load_lds((const unsigned*)((const char*)(gbase) + (voff)[_i]), (LAS unsigned*)(lds + (bufoff) + ldsw + _i * 8192), 16, 0, 0); } while (0)
; #define PG8_LDA(dst, b, h) do { _Pragma("unroll") for (int m = 0; m < 4; ++m) _Pragma("unroll") for (int k = 0; k < 2; ++k) dst[m][k] = *(const LAS bf16x8*)(lds + PG8_SA(b, h) + aoff + m * 2048 + k * 1024); } while (0)
; #define PG8_MMA(ai, bj, At, Bt) do { __builtin_amdgcn_s_setprio(1); _Pragma("unroll") for (int m = 0; m < 4; ++m) _Pragma("unroll") for (int n = 0; n < 2; ++n) _Pragma("unroll") for (int k = 0; k < 2; ++k) \
;         acc[ai][bj][m][n] = __builtin_amdgcn_mfma_f32_16x16x32_bf16(Bt[n][k], At[m][k], acc[ai][bj][m][n], 0, 0, 0); __builtin_amdgcn_s_setprio(0); } while (0)
; #define PG8_WAIT_V(n) asm volatile("s_waitcnt vmcnt(" #n ")" ::: "memory")
; #define PG8_WAIT_L(n) asm volatile("s_waitcnt lgkmcnt(" #n ")" ::: "memory")
; #define PG8_BAR __builtin_amdgcn_s_barrier()
; #define PG8_SCHED __builtin_amdgcn_sched_barrier(0)
; template <class Epi>
; DI void gemm_phase(int wv, LAS unsigned char* lds, LAS unsigned char* scr, const Sched& S, const Epi& E) {
;     ...
;             PG8_LDA(At, 1, 1); PG8_STAGE(PG8_SB(1, 0), b3, voffB); PG8_STAGE(PG8_SB(1, 1), b3 + hstepB, voffB); PG8_STAGE(PG8_SA(1, 0), a3, voffA);
;             PG8_WAIT_V(8); PG8_WAIT_L(0); PG8_BAR; PG8_MMA(1, 0, At, B0); PG8_MMA(1, 1, At, B1); PG8_BAR; PG8_SCHED;
;         }
;         if (wr == 0) PG8_BAR;
	s_add_i32 s26, s46, s33
	v_lshl_add_u64 v[190:191], v[190:191], 0, s[2:3]
	s_mov_b32 m0, s26
	ds_read_b128 v[178:181], v145 offset:49152
	ds_read_b128 v[182:185], v145 offset:50176
	ds_read_b128 v[186:189], v145 offset:51200
	ds_read_b128 v[194:197], v145 offset:52224
	ds_read_b128 v[198:201], v145 offset:53248
	ds_read_b128 v[202:205], v145 offset:54272
	ds_read_b128 v[206:209], v145 offset:55296
	ds_read_b128 v[210:213], v145 offset:56320
	global_load_lds_dwordx4 v[190:191], off
	s_add_i32 m0, s26, 0x2000
	s_add_u32 s24, s24, 0x40080
	v_lshl_add_u64 v[190:191], v[214:215], 0, s[2:3]
	s_addc_u32 s25, s25, 0
	s_add_i32 s26, s47, s33
	global_load_lds_dwordx4 v[190:191], off
	v_lshl_add_u64 v[190:191], s[24:25], 0, v[132:133]
	s_mov_b32 m0, s26
	s_nop 0
	global_load_lds_dwordx4 v[190:191], off
	v_lshl_add_u64 v[190:191], s[24:25], 0, v[128:129]
	s_add_i32 m0, s26, 0x2000
	s_nop 0
	global_load_lds_dwordx4 v[190:191], off
	v_lshl_add_u64 v[190:191], v[216:217], 0, s[2:3]
	s_mov_b32 m0, s42
	s_nop 0
	global_load_lds_dwordx4 v[190:191], off
	v_lshl_add_u64 v[190:191], v[218:219], 0, s[2:3]
	s_mov_b32 m0, s43
	s_nop 0
	global_load_lds_dwordx4 v[190:191], off
	s_waitcnt vmcnt(8)
	s_waitcnt lgkmcnt(0)
	s_barrier
	v_mfma_f32_16x16x32_bf16 v[60:63], v[146:149], v[178:181], v[60:63]
	v_mfma_f32_16x16x32_bf16 v[56:59], v[154:157], v[178:181], v[56:59]
	v_mfma_f32_16x16x32_bf16 v[52:55], v[146:149], v[186:189], v[52:55]
	v_mfma_f32_16x16x32_bf16 v[48:51], v[154:157], v[186:189], v[48:51]
	v_mfma_f32_16x16x32_bf16 v[36:39], v[146:149], v[198:201], v[36:39]
	v_mfma_f32_16x16x32_bf16 v[32:35], v[154:157], v[198:201], v[32:35]
	v_mfma_f32_16x16x32_bf16 v[20:23], v[146:149], v[206:209], v[20:23]
	v_mfma_f32_16x16x32_bf16 v[16:19], v[154:157], v[206:209], v[16:19]
	v_mfma_f32_16x16x32_bf16 v[60:63], v[150:153], v[182:185], v[60:63]
	v_mfma_f32_16x16x32_bf16 v[56:59], v[158:161], v[182:185], v[56:59]
	v_mfma_f32_16x16x32_bf16 v[52:55], v[150:153], v[194:197], v[52:55]
	v_mfma_f32_16x16x32_bf16 v[48:51], v[158:161], v[194:197], v[48:51]
	v_mfma_f32_16x16x32_bf16 v[36:39], v[150:153], v[202:205], v[36:39]
	v_mfma_f32_16x16x32_bf16 v[32:35], v[158:161], v[202:205], v[32:35]
	v_mfma_f32_16x16x32_bf16 v[20:23], v[150:153], v[210:213], v[20:23]
	v_mfma_f32_16x16x32_bf16 v[16:19], v[158:161], v[210:213], v[16:19]
	v_mfma_f32_16x16x32_bf16 v[44:47], v[162:165], v[178:181], v[44:47]
	v_mfma_f32_16x16x32_bf16 v[40:43], v[170:173], v[178:181], v[40:43]
	v_mfma_f32_16x16x32_bf16 v[28:31], v[162:165], v[186:189], v[28:31]
	v_mfma_f32_16x16x32_bf16 v[24:27], v[170:173], v[186:189], v[24:27]
	v_mfma_f32_16x16x32_bf16 v[12:15], v[162:165], v[198:201], v[12:15]
	v_mfma_f32_16x16x32_bf16 v[8:11], v[170:173], v[198:201], v[8:11]
	v_mfma_f32_16x16x32_bf16 v[4:7], v[162:165], v[206:209], v[4:7]
	v_mfma_f32_16x16x32_bf16 v[0:3], v[170:173], v[206:209], v[0:3]
	v_mfma_f32_16x16x32_bf16 v[44:47], v[166:169], v[182:185], v[44:47]
	v_mfma_f32_16x16x32_bf16 v[40:43], v[174:177], v[182:185], v[40:43]
	v_mfma_f32_16x16x32_bf16 v[28:31], v[166:169], v[194:197], v[28:31]
	v_mfma_f32_16x16x32_bf16 v[24:27], v[174:177], v[194:197], v[24:27]
	v_mfma_f32_16x16x32_bf16 v[12:15], v[166:169], v[202:205], v[12:15]
	v_mfma_f32_16x16x32_bf16 v[8:11], v[174:177], v[202:205], v[8:11]
	v_mfma_f32_16x16x32_bf16 v[4:7], v[166:169], v[210:213], v[4:7]
	v_mfma_f32_16x16x32_bf16 v[0:3], v[174:177], v[210:213], v[0:3]
	s_barrier
	s_add_i32 s45, s45, 2
	s_add_u32 s17, s17, 0x100
	s_addc_u32 s19, s19, 0
	s_add_u32 s8, s8, 0x100
	s_addc_u32 s9, s9, 0
	s_cmp_gt_u32 s45, 13
	s_cbranch_scc0 .LBB0_684
	s_and_b64 vcc, exec, s[12:13]
	s_cbranch_vccz .LBB0_687
	s_barrier

; #define PG8_STAGE(bufoff, gbase, voff) do { _Pragma("unroll") for (int _i = 0; _i < 2; ++_i) \
;         __builtin_amdgcn_global_load_lds((const unsigned*)((const char*)(gbase) + (voff)[_i]), (LAS unsigned*)(lds + (bufoff) + ldsw + _i * 8192), 16, 0, 0); } while (0)
; #define PG8_LDA(dst, b, h) do { _Pragma("unroll") for (int m = 0; m < 4; ++m) _Pragma("unroll") for (int k = 0; k < 2; ++k) dst[m][k] = *(const LAS bf16x8*)(lds + PG8_SA(b, h) + aoff + m * 2048 + k * 1024); } while (0)
; #define PG8_LDB(dst, b, h) do { _Pragma("unroll") for (int n = 0; n < 2; ++n) _Pragma("unroll") for (int k = 0; k < 2; ++k) dst[n][k] = *(const LAS bf16x8*)(lds + PG8_SB(b, h) + boff + n * 2048 + k * 1024); } while (0)
; #define PG8_MMA(ai, bj, At, Bt) do { __builtin_amdgcn_s_setprio(1); _Pragma("unroll") for (int m = 0; m < 4; ++m) _Pragma("unroll") for (int n = 0; n < 2; ++n) _Pragma("unroll") for (int k = 0; k < 2; ++k) \
;         acc[ai][bj][m][n] = __builtin_amdgcn_mfma_f32_16x16x32_bf16(Bt[n][k], At[m][k], acc[ai][bj][m][n], 0, 0, 0); __builtin_amdgcn_s_setprio(0); } while (0)
; #define PG8_WAIT_V(n) asm volatile("s_waitcnt vmcnt(" #n ")" ::: "memory")
; #define PG8_WAIT_L(n) asm volatile("s_waitcnt lgkmcnt(" #n ")" ::: "memory")
; #define PG8_BAR __builtin_amdgcn_s_barrier()
; #define PG8_SCHED __builtin_amdgcn_sched_barrier(0)
; template <class Epi>
; DI void gemm_phase(int wv, LAS unsigned char* lds, LAS unsigned char* scr, const Sched& S, const Epi& E) {
;     ...
;         const bool has_next = S.next(ui + 1, nxt);
;         const char* nA = has_next ? S.baseA(nxt) : cA; const char* nB = has_next ? S.baseB(nxt) : cB;
;         for (int t = 0; t < nt; t += 2) {
;             const bool last = (t == nt - 2);
;             const char* a1 = cA + (size_t)(t + 1) * kstep;
;             const char* a2 = last ? nA : cA + (size_t)(t + 2) * kstep; const char* b2 = last ? nB : cB + (size_t)(t + 2) * kstep;
;             const char* a3 = a2 + kstep; const char* b3 = b2 + kstep;
;             PG8_LDB(B0, 0, 0); PG8_LDB(B1, 0, 1); PG8_SCHED; PG8_LDA(At, 0, 0); PG8_STAGE(PG8_SA(1, 1), a1 + hstepA, voffA);
;             PG8_WAIT_V(8); PG8_WAIT_L(0); PG8_BAR; PG8_MMA(0, 0, At, B0); PG8_MMA(0, 1, At, B1); PG8_BAR; PG8_SCHED;
;             PG8_LDA(At, 0, 1); PG8_STAGE(PG8_SB(0, 0), b2, voffB); PG8_STAGE(PG8_SB(0, 1), b2 + hstepB, voffB); PG8_STAGE(PG8_SA(0, 0), a2, voffA);
.LBB0_811:
	s_add_u32 s54, s28, 0xfffc0080
	s_addc_u32 s55, s29, -1
	s_add_i32 s61, 0, 0x10000
	s_cmp_eq_u32 s60, 12
	s_cselect_b32 s57, s49, s55
	s_cselect_b32 s56, s48, s54
	s_cselect_b32 s55, s47, s59
	s_cselect_b32 s54, s53, s58
	s_add_i32 s76, 0, 0x14000
	v_add_u32_e32 v140, s61, v199
	v_add_u32_e32 v156, s76, v199
	ds_read_b128 v[128:131], v140
	ds_read_b128 v[132:135], v140 offset:1024
	ds_read_b128 v[136:139], v140 offset:2048
	ds_read_b128 v[140:143], v140 offset:3072
	ds_read_b128 v[144:147], v156
	ds_read_b128 v[148:151], v156 offset:1024
	ds_read_b128 v[152:155], v156 offset:2048
	ds_read_b128 v[156:159], v156 offset:3072
	v_lshl_add_u64 v[204:205], s[28:29], 0, v[178:179]
	s_add_i32 m0, s66, 0xc000
	ds_read_b128 v[160:163], v220
	ds_read_b128 v[164:167], v220 offset:1024
	ds_read_b128 v[180:183], v220 offset:2048
	ds_read_b128 v[184:187], v220 offset:3072
	ds_read_b128 v[188:191], v220 offset:4096
	ds_read_b128 v[194:197], v220 offset:5120
	ds_read_b128 v[200:203], v220 offset:6144
	ds_read_b128 v[222:225], v220 offset:7168
	global_load_lds_dwordx4 v[204:205], off
	v_lshl_add_u64 v[204:205], s[28:29], 0, v[176:177]
	s_add_i32 m0, s66, 0xe000
	s_nop 0
	global_load_lds_dwordx4 v[204:205], off
	s_waitcnt vmcnt(8)
	s_waitcnt lgkmcnt(0)
	s_barrier
	v_mfma_f32_16x16x32_bf16 v[124:127], v[128:131], v[160:163], v[124:127]
	v_mfma_f32_16x16x32_bf16 v[92:95], v[136:139], v[160:163], v[92:95]
	v_mfma_f32_16x16x32_bf16 v[116:119], v[128:131], v[180:183], v[116:119]
	v_mfma_f32_16x16x32_bf16 v[84:87], v[136:139], v[180:183], v[84:87]
	v_mfma_f32_16x16x32_bf16 v[108:111], v[128:131], v[188:191], v[108:111]
	v_mfma_f32_16x16x32_bf16 v[76:79], v[136:139], v[188:191], v[76:79]
	v_mfma_f32_16x16x32_bf16 v[100:103], v[128:131], v[200:203], v[100:103]
	v_mfma_f32_16x16x32_bf16 v[68:71], v[136:139], v[200:203], v[68:71]
	v_mfma_f32_16x16x32_bf16 v[124:127], v[132:135], v[164:167], v[124:127]
	v_mfma_f32_16x16x32_bf16 v[92:95], v[140:143], v[164:167], v[92:95]
	v_mfma_f32_16x16x32_bf16 v[116:119], v[132:135], v[184:187], v[116:119]
	v_mfma_f32_16x16x32_bf16 v[84:87], v[140:143], v[184:187], v[84:87]
	v_mfma_f32_16x16x32_bf16 v[108:111], v[132:135], v[194:197], v[108:111]
	v_mfma_f32_16x16x32_bf16 v[76:79], v[140:143], v[194:197], v[76:79]
	v_mfma_f32_16x16x32_bf16 v[100:103], v[132:135], v[222:225], v[100:103]
	v_mfma_f32_16x16x32_bf16 v[68:71], v[140:143], v[222:225], v[68:71]
	v_mfma_f32_16x16x32_bf16 v[120:123], v[144:147], v[160:163], v[120:123]
	v_mfma_f32_16x16x32_bf16 v[88:91], v[152:155], v[160:163], v[88:91]
	v_mfma_f32_16x16x32_bf16 v[112:115], v[144:147], v[180:183], v[112:115]
	v_mfma_f32_16x16x32_bf16 v[80:83], v[152:155], v[180:183], v[80:83]
	v_mfma_f32_16x16x32_bf16 v[104:107], v[144:147], v[188:191], v[104:107]
	v_mfma_f32_16x16x32_bf16 v[72:75], v[152:155], v[188:191], v[72:75]
	v_mfma_f32_16x16x32_bf16 v[96:99], v[144:147], v[200:203], v[96:99]
	v_mfma_f32_16x16x32_bf16 v[64:67], v[152:155], v[200:203], v[64:67]
	v_mfma_f32_16x16x32_bf16 v[120:123], v[148:151], v[164:167], v[120:123]
	v_mfma_f32_16x16x32_bf16 v[88:91], v[156:159], v[164:167], v[88:91]
	v_mfma_f32_16x16x32_bf16 v[112:115], v[148:151], v[184:187], v[112:115]
	v_mfma_f32_16x16x32_bf16 v[80:83], v[156:159], v[184:187], v[80:83]
	v_mfma_f32_16x16x32_bf16 v[104:107], v[148:151], v[194:197], v[104:107]
	v_mfma_f32_16x16x32_bf16 v[72:75], v[156:159], v[194:197], v[72:75]
	v_mfma_f32_16x16x32_bf16 v[96:99], v[148:151], v[222:225], v[96:99]
	v_mfma_f32_16x16x32_bf16 v[64:67], v[156:159], v[222:225], v[64:67]
	s_barrier
	s_add_i32 s61, s61, s65
	v_lshl_add_u64 v[204:205], s[54:55], 0, v[170:171]
	s_mov_b32 m0, s61
	ds_read_b128 v[160:163], v220 offset:16384
	ds_read_b128 v[164:167], v220 offset:17408
	ds_read_b128 v[180:183], v220 offset:18432
	ds_read_b128 v[184:187], v220 offset:19456
	ds_read_b128 v[188:191], v220 offset:20480
	ds_read_b128 v[194:197], v220 offset:21504
	ds_read_b128 v[200:203], v220 offset:22528
	ds_read_b128 v[222:225], v220 offset:23552
	global_load_lds_dwordx4 v[204:205], off
	s_add_i32 m0, s61, 0x2000
	s_add_u32 s74, s54, 0x40000
	v_lshl_add_u64 v[226:227], s[54:55], 0, v[174:175]
	s_addc_u32 s75, s55, 0
	s_add_i32 s61, s76, s65
	global_load_lds_dwordx4 v[226:227], off
	v_lshl_add_u64 v[228:229], s[74:75], 0, v[170:171]
	s_mov_b32 m0, s61
	v_lshl_add_u64 v[230:231], s[56:57], 0, v[172:173]
	global_load_lds_dwordx4 v[228:229], off
	v_lshl_add_u64 v[228:229], s[74:75], 0, v[174:175]
	s_add_i32 m0, s61, 0x2000
	s_nop 0
	global_load_lds_dwordx4 v[228:229], off
	v_lshl_add_u64 v[228:229], s[56:57], 0, v[168:169]
	s_mov_b32 m0, s66
	s_nop 0
	global_load_lds_dwordx4 v[228:229], off
	s_mov_b32 m0, s67
	s_nop 0
	global_load_lds_dwordx4 v[230:231], off
	s_waitcnt vmcnt(8)
	s_waitcnt lgkmcnt(0)
	s_barrier
; #define PG8_STAGE(bufoff, gbase, voff) do { _Pragma("unroll") for (int _i = 0; _i < 2; ++_i) \
;         __builtin_amdgcn_global_load_lds((const unsigned*)((const char*)(gbase) + (voff)[_i]), (LAS unsigned*)(lds + (bufoff) + ldsw + _i * 8192), 16, 0, 0); } while (0)
; #define PG8_LDA(dst, b, h) do { _Pragma("unroll") for (int m = 0; m < 4; ++m) _Pragma("unroll") for (int k = 0; k < 2; ++k) dst[m][k] = *(const LAS bf16x8*)(lds + PG8_SA(b, h) + aoff + m * 2048 + k * 1024); } while (0)
; #define PG8_LDB(dst, b, h) do { _Pragma("unroll") for (int n = 0; n < 2; ++n) _Pragma("unroll") for (int k = 0; k < 2; ++k) dst[n][k] = *(const LAS bf16x8*)(lds + PG8_SB(b, h) + boff + n * 2048 + k * 1024); } while (0)
; #define PG8_MMA(ai, bj, At, Bt) do { __builtin_amdgcn_s_setprio(1); _Pragma("unroll") for (int m = 0; m < 4; ++m) _Pragma("unroll") for (int n = 0; n < 2; ++n) _Pragma("unroll") for (int k = 0; k < 2; ++k) \
;         acc[ai][bj][m][n] = __builtin_amdgcn_mfma_f32_16x16x32_bf16(Bt[n][k], At[m][k], acc[ai][bj][m][n], 0, 0, 0); __builtin_amdgcn_s_setprio(0); } while (0)
; #define PG8_WAIT_V(n) asm volatile("s_waitcnt vmcnt(" #n ")" ::: "memory")
; #define PG8_WAIT_L(n) asm volatile("s_waitcnt lgkmcnt(" #n ")" ::: "memory")
; #define PG8_BAR __builtin_amdgcn_s_barrier()
; #define PG8_SCHED __builtin_amdgcn_sched_barrier(0)
; template <class Epi>
; DI void gemm_phase(int wv, LAS unsigned char* lds, LAS unsigned char* scr, const Sched& S, const Epi& E) {
;     ...
;             PG8_WAIT_V(8); PG8_WAIT_L(0); PG8_BAR; PG8_MMA(1, 0, At, B0); PG8_MMA(1, 1, At, B1); PG8_BAR; PG8_SCHED;
;             PG8_LDB(B0, 1, 0); PG8_LDB(B1, 1, 1); PG8_SCHED; PG8_LDA(At, 1, 0); PG8_STAGE(PG8_SA(0, 1), a2 + hstepA, voffA);
;             PG8_WAIT_V(8); PG8_WAIT_L(0); PG8_BAR; PG8_MMA(0, 0, At, B0); PG8_MMA(0, 1, At, B1); PG8_BAR; PG8_SCHED;
	v_mfma_f32_16x16x32_bf16 v[60:63], v[128:131], v[160:163], v[60:63]
	v_mfma_f32_16x16x32_bf16 v[28:31], v[136:139], v[160:163], v[28:31]
	v_mfma_f32_16x16x32_bf16 v[52:55], v[128:131], v[180:183], v[52:55]
	v_mfma_f32_16x16x32_bf16 v[20:23], v[136:139], v[180:183], v[20:23]
	v_mfma_f32_16x16x32_bf16 v[44:47], v[128:131], v[188:191], v[44:47]
	v_mfma_f32_16x16x32_bf16 v[12:15], v[136:139], v[188:191], v[12:15]
	v_mfma_f32_16x16x32_bf16 v[36:39], v[128:131], v[200:203], v[36:39]
	v_mfma_f32_16x16x32_bf16 v[4:7], v[136:139], v[200:203], v[4:7]
	v_mfma_f32_16x16x32_bf16 v[60:63], v[132:135], v[164:167], v[60:63]
	v_mfma_f32_16x16x32_bf16 v[28:31], v[140:143], v[164:167], v[28:31]
	v_mfma_f32_16x16x32_bf16 v[52:55], v[132:135], v[184:187], v[52:55]
	v_mfma_f32_16x16x32_bf16 v[20:23], v[140:143], v[184:187], v[20:23]
	v_mfma_f32_16x16x32_bf16 v[44:47], v[132:135], v[194:197], v[44:47]
	v_mfma_f32_16x16x32_bf16 v[12:15], v[140:143], v[194:197], v[12:15]
	v_mfma_f32_16x16x32_bf16 v[36:39], v[132:135], v[222:225], v[36:39]
	v_mfma_f32_16x16x32_bf16 v[4:7], v[140:143], v[222:225], v[4:7]
	v_mfma_f32_16x16x32_bf16 v[56:59], v[144:147], v[160:163], v[56:59]
	v_mfma_f32_16x16x32_bf16 v[24:27], v[152:155], v[160:163], v[24:27]
	v_mfma_f32_16x16x32_bf16 v[48:51], v[144:147], v[180:183], v[48:51]
	v_mfma_f32_16x16x32_bf16 v[16:19], v[152:155], v[180:183], v[16:19]
	v_mfma_f32_16x16x32_bf16 v[40:43], v[144:147], v[188:191], v[40:43]
	v_mfma_f32_16x16x32_bf16 v[8:11], v[152:155], v[188:191], v[8:11]
	v_mfma_f32_16x16x32_bf16 v[32:35], v[144:147], v[200:203], v[32:35]
	v_mfma_f32_16x16x32_bf16 v[0:3], v[152:155], v[200:203], v[0:3]
	v_mfma_f32_16x16x32_bf16 v[56:59], v[148:151], v[164:167], v[56:59]
	v_mfma_f32_16x16x32_bf16 v[24:27], v[156:159], v[164:167], v[24:27]
	v_mfma_f32_16x16x32_bf16 v[48:51], v[148:151], v[184:187], v[48:51]
	v_mfma_f32_16x16x32_bf16 v[16:19], v[156:159], v[184:187], v[16:19]
	v_mfma_f32_16x16x32_bf16 v[40:43], v[148:151], v[194:197], v[40:43]
	v_mfma_f32_16x16x32_bf16 v[8:11], v[156:159], v[194:197], v[8:11]
	v_mfma_f32_16x16x32_bf16 v[32:35], v[148:151], v[222:225], v[32:35]
	v_mfma_f32_16x16x32_bf16 v[0:3], v[156:159], v[222:225], v[0:3]
	s_barrier
	s_add_i32 s61, 0, 0x18000
	s_add_i32 s74, 0, 0x1c000
	v_add_u32_e32 v140, s61, v199
	v_add_u32_e32 v156, s74, v199
	ds_read_b128 v[128:131], v140
	ds_read_b128 v[132:135], v140 offset:1024
	ds_read_b128 v[136:139], v140 offset:2048
	ds_read_b128 v[140:143], v140 offset:3072
	ds_read_b128 v[144:147], v156
	ds_read_b128 v[148:151], v156 offset:1024
	ds_read_b128 v[152:155], v156 offset:2048
	ds_read_b128 v[156:159], v156 offset:3072
	s_add_u32 s56, s56, 0x40000
	s_addc_u32 s57, s57, 0
	s_mov_b32 m0, s68
	v_lshl_add_u64 v[232:233], s[56:57], 0, v[168:169]
	ds_read_b128 v[160:163], v220 offset:32768
	ds_read_b128 v[164:167], v220 offset:33792
	ds_read_b128 v[180:183], v220 offset:34816
	ds_read_b128 v[184:187], v220 offset:35840
	ds_read_b128 v[188:191], v220 offset:36864
	ds_read_b128 v[194:197], v220 offset:37888
	ds_read_b128 v[200:203], v220 offset:38912
	ds_read_b128 v[222:225], v220 offset:39936
	global_load_lds_dwordx4 v[232:233], off
	v_lshl_add_u64 v[232:233], s[56:57], 0, v[172:173]
	s_mov_b32 m0, s69
	s_nop 0
	global_load_lds_dwordx4 v[232:233], off
	s_waitcnt vmcnt(8)
	s_waitcnt lgkmcnt(0)
	s_barrier
	v_mfma_f32_16x16x32_bf16 v[124:127], v[128:131], v[160:163], v[124:127]
	v_mfma_f32_16x16x32_bf16 v[92:95], v[136:139], v[160:163], v[92:95]
	v_mfma_f32_16x16x32_bf16 v[116:119], v[128:131], v[180:183], v[116:119]
	v_mfma_f32_16x16x32_bf16 v[84:87], v[136:139], v[180:183], v[84:87]
	v_mfma_f32_16x16x32_bf16 v[108:111], v[128:131], v[188:191], v[108:111]
	v_mfma_f32_16x16x32_bf16 v[76:79], v[136:139], v[188:191], v[76:79]
	v_mfma_f32_16x16x32_bf16 v[100:103], v[128:131], v[200:203], v[100:103]
	v_mfma_f32_16x16x32_bf16 v[68:71], v[136:139], v[200:203], v[68:71]
	v_mfma_f32_16x16x32_bf16 v[124:127], v[132:135], v[164:167], v[124:127]
	v_mfma_f32_16x16x32_bf16 v[92:95], v[140:143], v[164:167], v[92:95]
	v_mfma_f32_16x16x32_bf16 v[116:119], v[132:135], v[184:187], v[116:119]
	v_mfma_f32_16x16x32_bf16 v[84:87], v[140:143], v[184:187], v[84:87]
	v_mfma_f32_16x16x32_bf16 v[108:111], v[132:135], v[194:197], v[108:111]
	v_mfma_f32_16x16x32_bf16 v[76:79], v[140:143], v[194:197], v[76:79]
	v_mfma_f32_16x16x32_bf16 v[100:103], v[132:135], v[222:225], v[100:103]
	v_mfma_f32_16x16x32_bf16 v[68:71], v[140:143], v[222:225], v[68:71]
	v_mfma_f32_16x16x32_bf16 v[120:123], v[144:147], v[160:163], v[120:123]
	v_mfma_f32_16x16x32_bf16 v[88:91], v[152:155], v[160:163], v[88:91]
	v_mfma_f32_16x16x32_bf16 v[112:115], v[144:147], v[180:183], v[112:115]
	v_mfma_f32_16x16x32_bf16 v[80:83], v[152:155], v[180:183], v[80:83]
	v_mfma_f32_16x16x32_bf16 v[104:107], v[144:147], v[188:191], v[104:107]
	v_mfma_f32_16x16x32_bf16 v[72:75], v[152:155], v[188:191], v[72:75]
	v_mfma_f32_16x16x32_bf16 v[96:99], v[144:147], v[200:203], v[96:99]
	v_mfma_f32_16x16x32_bf16 v[64:67], v[152:155], v[200:203], v[64:67]
	v_mfma_f32_16x16x32_bf16 v[120:123], v[148:151], v[164:167], v[120:123]
	v_mfma_f32_16x16x32_bf16 v[88:91], v[156:159], v[164:167], v[88:91]
	v_mfma_f32_16x16x32_bf16 v[112:115], v[148:151], v[184:187], v[112:115]
	v_mfma_f32_16x16x32_bf16 v[80:83], v[156:159], v[184:187], v[80:83]
	v_mfma_f32_16x16x32_bf16 v[104:107], v[148:151], v[194:197], v[104:107]
	v_mfma_f32_16x16x32_bf16 v[72:75], v[156:159], v[194:197], v[72:75]
	v_mfma_f32_16x16x32_bf16 v[96:99], v[148:151], v[222:225], v[96:99]
	v_mfma_f32_16x16x32_bf16 v[64:67], v[156:159], v[222:225], v[64:67]
	s_barrier
; #define PG8_STAGE(bufoff, gbase, voff) do { _Pragma("unroll") for (int _i = 0; _i < 2; ++_i) \
;         __builtin_amdgcn_global_load_lds((const unsigned*)((const char*)(gbase) + (voff)[_i]), (LAS unsigned*)(lds + (bufoff) + ldsw + _i * 8192), 16, 0, 0); } while (0)
; #define PG8_LDA(dst, b, h) do { _Pragma("unroll") for (int m = 0; m < 4; ++m) _Pragma("unroll") for (int k = 0; k < 2; ++k) dst[m][k] = *(const LAS bf16x8*)(lds + PG8_SA(b, h) + aoff + m * 2048 + k * 1024); } while (0)
; #define PG8_MMA(ai, bj, At, Bt) do { __builtin_amdgcn_s_setprio(1); _Pragma("unroll") for (int m = 0; m < 4; ++m) _Pragma("unroll") for (int n = 0; n < 2; ++n) _Pragma("unroll") for (int k = 0; k < 2; ++k) \
;         acc[ai][bj][m][n] = __builtin_amdgcn_mfma_f32_16x16x32_bf16(Bt[n][k], At[m][k], acc[ai][bj][m][n], 0, 0, 0); __builtin_amdgcn_s_setprio(0); } while (0)
; #define PG8_WAIT_V(n) asm volatile("s_waitcnt vmcnt(" #n ")" ::: "memory")
; #define PG8_WAIT_L(n) asm volatile("s_waitcnt lgkmcnt(" #n ")" ::: "memory")
; #define PG8_BAR __builtin_amdgcn_s_barrier()
; #define PG8_SCHED __builtin_amdgcn_sched_barrier(0)
; template <class Epi>
; DI void gemm_phase(int wv, LAS unsigned char* lds, LAS unsigned char* scr, const Sched& S, const Epi& E) {
;     ...
;             PG8_LDA(At, 1, 1); PG8_STAGE(PG8_SB(1, 0), b3, voffB); PG8_STAGE(PG8_SB(1, 1), b3 + hstepB, voffB); PG8_STAGE(PG8_SA(1, 0), a3, voffA);
;             PG8_WAIT_V(8); PG8_WAIT_L(0); PG8_BAR; PG8_MMA(1, 0, At, B0); PG8_MMA(1, 1, At, B1); PG8_BAR; PG8_SCHED;
;         }
;         if (wr == 0) PG8_BAR;
	s_add_i32 s56, s61, s65
	v_lshl_add_u64 v[204:205], v[204:205], 0, s[2:3]
	s_mov_b32 m0, s56
	ds_read_b128 v[160:163], v220 offset:49152
	ds_read_b128 v[164:167], v220 offset:50176
	ds_read_b128 v[180:183], v220 offset:51200
	ds_read_b128 v[184:187], v220 offset:52224
	ds_read_b128 v[188:191], v220 offset:53248
	ds_read_b128 v[194:197], v220 offset:54272
	ds_read_b128 v[200:203], v220 offset:55296
	ds_read_b128 v[222:225], v220 offset:56320
	global_load_lds_dwordx4 v[204:205], off
	s_add_i32 m0, s56, 0x2000
	s_add_u32 s54, s54, 0x40080
	v_lshl_add_u64 v[204:205], v[226:227], 0, s[2:3]
	s_addc_u32 s55, s55, 0
	s_add_i32 s56, s74, s65
	global_load_lds_dwordx4 v[204:205], off
	v_lshl_add_u64 v[204:205], s[54:55], 0, v[170:171]
	s_mov_b32 m0, s56
	s_nop 0
	global_load_lds_dwordx4 v[204:205], off
	v_lshl_add_u64 v[204:205], s[54:55], 0, v[174:175]
	s_add_i32 m0, s56, 0x2000
	s_nop 0
	global_load_lds_dwordx4 v[204:205], off
	v_lshl_add_u64 v[204:205], v[228:229], 0, s[2:3]
	s_mov_b32 m0, s70
	s_nop 0
	global_load_lds_dwordx4 v[204:205], off
	v_lshl_add_u64 v[204:205], v[230:231], 0, s[2:3]
	s_mov_b32 m0, s71
	s_nop 0
	global_load_lds_dwordx4 v[204:205], off
	s_waitcnt vmcnt(8)
	s_waitcnt lgkmcnt(0)
	s_barrier
	v_mfma_f32_16x16x32_bf16 v[60:63], v[128:131], v[160:163], v[60:63]
	v_mfma_f32_16x16x32_bf16 v[28:31], v[136:139], v[160:163], v[28:31]
	v_mfma_f32_16x16x32_bf16 v[52:55], v[128:131], v[180:183], v[52:55]
	v_mfma_f32_16x16x32_bf16 v[20:23], v[136:139], v[180:183], v[20:23]
	v_mfma_f32_16x16x32_bf16 v[44:47], v[128:131], v[188:191], v[44:47]
	v_mfma_f32_16x16x32_bf16 v[12:15], v[136:139], v[188:191], v[12:15]
	v_mfma_f32_16x16x32_bf16 v[36:39], v[128:131], v[200:203], v[36:39]
	v_mfma_f32_16x16x32_bf16 v[4:7], v[136:139], v[200:203], v[4:7]
	v_mfma_f32_16x16x32_bf16 v[60:63], v[132:135], v[164:167], v[60:63]
	v_mfma_f32_16x16x32_bf16 v[28:31], v[140:143], v[164:167], v[28:31]
	v_mfma_f32_16x16x32_bf16 v[52:55], v[132:135], v[184:187], v[52:55]
	v_mfma_f32_16x16x32_bf16 v[20:23], v[140:143], v[184:187], v[20:23]
	v_mfma_f32_16x16x32_bf16 v[44:47], v[132:135], v[194:197], v[44:47]
	v_mfma_f32_16x16x32_bf16 v[12:15], v[140:143], v[194:197], v[12:15]
	v_mfma_f32_16x16x32_bf16 v[36:39], v[132:135], v[222:225], v[36:39]
	v_mfma_f32_16x16x32_bf16 v[4:7], v[140:143], v[222:225], v[4:7]
	v_mfma_f32_16x16x32_bf16 v[56:59], v[144:147], v[160:163], v[56:59]
	v_mfma_f32_16x16x32_bf16 v[24:27], v[152:155], v[160:163], v[24:27]
	v_mfma_f32_16x16x32_bf16 v[48:51], v[144:147], v[180:183], v[48:51]
	v_mfma_f32_16x16x32_bf16 v[16:19], v[152:155], v[180:183], v[16:19]
	v_mfma_f32_16x16x32_bf16 v[40:43], v[144:147], v[188:191], v[40:43]
	v_mfma_f32_16x16x32_bf16 v[8:11], v[152:155], v[188:191], v[8:11]
	v_mfma_f32_16x16x32_bf16 v[32:35], v[144:147], v[200:203], v[32:35]
	v_mfma_f32_16x16x32_bf16 v[0:3], v[152:155], v[200:203], v[0:3]
	v_mfma_f32_16x16x32_bf16 v[56:59], v[148:151], v[164:167], v[56:59]
	v_mfma_f32_16x16x32_bf16 v[24:27], v[156:159], v[164:167], v[24:27]
	v_mfma_f32_16x16x32_bf16 v[48:51], v[148:151], v[184:187], v[48:51]
	v_mfma_f32_16x16x32_bf16 v[16:19], v[156:159], v[184:187], v[16:19]
	v_mfma_f32_16x16x32_bf16 v[40:43], v[148:151], v[194:197], v[40:43]
	v_mfma_f32_16x16x32_bf16 v[8:11], v[156:159], v[194:197], v[8:11]
	v_mfma_f32_16x16x32_bf16 v[32:35], v[148:151], v[222:225], v[32:35]
	v_mfma_f32_16x16x32_bf16 v[0:3], v[156:159], v[222:225], v[0:3]
	s_barrier
	s_add_i32 s60, s60, 2
	s_add_u32 s58, s58, 0x100
	s_addc_u32 s59, s59, 0
	s_add_u32 s28, s28, 0x100
	s_addc_u32 s29, s29, 0
	s_cmp_gt_u32 s60, 13
	s_cbranch_scc0 .LBB0_811
	s_and_b64 vcc, exec, s[42:43]
	s_cbranch_vccz .LBB0_814
	s_barrier

; #define PG8_STAGE(bufoff, gbase, voff) do { _Pragma("unroll") for (int _i = 0; _i < 2; ++_i) \
;         __builtin_amdgcn_global_load_lds((const unsigned*)((const char*)(gbase) + (voff)[_i]), (LAS unsigned*)(lds + (bufoff) + ldsw + _i * 8192), 16, 0, 0); } while (0)
; #define PG8_LDA(dst, b, h) do { _Pragma("unroll") for (int m = 0; m < 4; ++m) _Pragma("unroll") for (int k = 0; k < 2; ++k) dst[m][k] = *(const LAS bf16x8*)(lds + PG8_SA(b, h) + aoff + m * 2048 + k * 1024); } while (0)
; #define PG8_LDB(dst, b, h) do { _Pragma("unroll") for (int n = 0; n < 2; ++n) _Pragma("unroll") for (int k = 0; k < 2; ++k) dst[n][k] = *(const LAS bf16x8*)(lds + PG8_SB(b, h) + boff + n * 2048 + k * 1024); } while (0)
; #define PG8_MMA(ai, bj, At, Bt) do { __builtin_amdgcn_s_setprio(1); _Pragma("unroll") for (int m = 0; m < 4; ++m) _Pragma("unroll") for (int n = 0; n < 2; ++n) _Pragma("unroll") for (int k = 0; k < 2; ++k) \
;         acc[ai][bj][m][n] = __builtin_amdgcn_mfma_f32_16x16x32_bf16(Bt[n][k], At[m][k], acc[ai][bj][m][n], 0, 0, 0); __builtin_amdgcn_s_setprio(0); } while (0)
; #define PG8_WAIT_V(n) asm volatile("s_waitcnt vmcnt(" #n ")" ::: "memory")
; #define PG8_WAIT_L(n) asm volatile("s_waitcnt lgkmcnt(" #n ")" ::: "memory")
; #define PG8_BAR __builtin_amdgcn_s_barrier()
; #define PG8_SCHED __builtin_amdgcn_sched_barrier(0)
; template <class Epi>
; DI void gemm_phase(int wv, LAS unsigned char* lds, LAS unsigned char* scr, const Sched& S, const Epi& E) {
;     ...
;         const bool has_next = S.next(ui + 1, nxt);
;         const char* nA = has_next ? S.baseA(nxt) : cA; const char* nB = has_next ? S.baseB(nxt) : cB;
;         for (int t = 0; t < nt; t += 2) {
;             const bool last = (t == nt - 2);
;             const char* a1 = cA + (size_t)(t + 1) * kstep;
;             const char* a2 = last ? nA : cA + (size_t)(t + 2) * kstep; const char* b2 = last ? nB : cB + (size_t)(t + 2) * kstep;
;             const char* a3 = a2 + kstep; const char* b3 = b2 + kstep;
;             PG8_LDB(B0, 0, 0); PG8_LDB(B1, 0, 1); PG8_SCHED; PG8_LDA(At, 0, 0); PG8_STAGE(PG8_SA(1, 1), a1 + hstepA, voffA);
;             PG8_WAIT_V(8); PG8_WAIT_L(0); PG8_BAR; PG8_MMA(0, 0, At, B0); PG8_MMA(0, 1, At, B1); PG8_BAR; PG8_SCHED;
;             PG8_LDA(At, 0, 1); PG8_STAGE(PG8_SB(0, 0), b2, voffB); PG8_STAGE(PG8_SB(0, 1), b2 + hstepB, voffB); PG8_STAGE(PG8_SA(0, 0), a2, voffA);
.LBB0_936:
	s_add_u32 s30, s28, 0x100
	s_addc_u32 s31, s29, 0
	s_add_i32 s69, 0, 0x10000
	s_cmp_eq_u32 s68, 40
	s_cselect_b32 s37, s9, s31
	s_cselect_b32 s36, s8, s30
	s_cselect_b32 s35, s23, s27
	s_cselect_b32 s34, s22, s25
	s_add_i32 s70, 0, 0x14000
	v_add_u32_e32 v156, s69, v142
	v_add_u32_e32 v172, s70, v142
	ds_read_b128 v[144:147], v156
	ds_read_b128 v[148:151], v156 offset:1024
	ds_read_b128 v[152:155], v156 offset:2048
	ds_read_b128 v[156:159], v156 offset:3072
	ds_read_b128 v[160:163], v172
	ds_read_b128 v[164:167], v172 offset:1024
	ds_read_b128 v[168:171], v172 offset:2048
	ds_read_b128 v[172:175], v172 offset:3072
	v_lshl_add_u64 v[210:211], s[28:29], 0, v[140:141]
	s_add_i32 m0, s57, 0xc000
	ds_read_b128 v[176:179], v143
	ds_read_b128 v[180:183], v143 offset:1024
	ds_read_b128 v[184:187], v143 offset:2048
	ds_read_b128 v[188:191], v143 offset:3072
	ds_read_b128 v[194:197], v143 offset:4096
	ds_read_b128 v[198:201], v143 offset:5120
	ds_read_b128 v[202:205], v143 offset:6144
	ds_read_b128 v[206:209], v143 offset:7168
	global_load_lds_dwordx4 v[210:211], off
	v_lshl_add_u64 v[210:211], s[28:29], 0, v[138:139]
	s_add_i32 m0, s57, 0xe000
	s_nop 0
	global_load_lds_dwordx4 v[210:211], off
	s_waitcnt vmcnt(8)
	s_waitcnt lgkmcnt(0)
	s_barrier
	v_mfma_f32_16x16x32_bf16 v[124:127], v[144:147], v[176:179], v[124:127]
	v_mfma_f32_16x16x32_bf16 v[120:123], v[152:155], v[176:179], v[120:123]
	v_mfma_f32_16x16x32_bf16 v[116:119], v[144:147], v[184:187], v[116:119]
	v_mfma_f32_16x16x32_bf16 v[112:115], v[152:155], v[184:187], v[112:115]
	v_mfma_f32_16x16x32_bf16 v[100:103], v[144:147], v[194:197], v[100:103]
	v_mfma_f32_16x16x32_bf16 v[96:99], v[152:155], v[194:197], v[96:99]
	v_mfma_f32_16x16x32_bf16 v[84:87], v[144:147], v[202:205], v[84:87]
	v_mfma_f32_16x16x32_bf16 v[80:83], v[152:155], v[202:205], v[80:83]
	v_mfma_f32_16x16x32_bf16 v[124:127], v[148:151], v[180:183], v[124:127]
	v_mfma_f32_16x16x32_bf16 v[120:123], v[156:159], v[180:183], v[120:123]
	v_mfma_f32_16x16x32_bf16 v[116:119], v[148:151], v[188:191], v[116:119]
	v_mfma_f32_16x16x32_bf16 v[112:115], v[156:159], v[188:191], v[112:115]
	v_mfma_f32_16x16x32_bf16 v[100:103], v[148:151], v[198:201], v[100:103]
	v_mfma_f32_16x16x32_bf16 v[96:99], v[156:159], v[198:201], v[96:99]
	v_mfma_f32_16x16x32_bf16 v[84:87], v[148:151], v[206:209], v[84:87]
	v_mfma_f32_16x16x32_bf16 v[80:83], v[156:159], v[206:209], v[80:83]
	v_mfma_f32_16x16x32_bf16 v[108:111], v[160:163], v[176:179], v[108:111]
	v_mfma_f32_16x16x32_bf16 v[104:107], v[168:171], v[176:179], v[104:107]
	v_mfma_f32_16x16x32_bf16 v[92:95], v[160:163], v[184:187], v[92:95]
	v_mfma_f32_16x16x32_bf16 v[88:91], v[168:171], v[184:187], v[88:91]
	v_mfma_f32_16x16x32_bf16 v[76:79], v[160:163], v[194:197], v[76:79]
	v_mfma_f32_16x16x32_bf16 v[72:75], v[168:171], v[194:197], v[72:75]
	v_mfma_f32_16x16x32_bf16 v[68:71], v[160:163], v[202:205], v[68:71]
	v_mfma_f32_16x16x32_bf16 v[64:67], v[168:171], v[202:205], v[64:67]
	v_mfma_f32_16x16x32_bf16 v[108:111], v[164:167], v[180:183], v[108:111]
	v_mfma_f32_16x16x32_bf16 v[104:107], v[172:175], v[180:183], v[104:107]
	v_mfma_f32_16x16x32_bf16 v[92:95], v[164:167], v[188:191], v[92:95]
	v_mfma_f32_16x16x32_bf16 v[88:91], v[172:175], v[188:191], v[88:91]
	v_mfma_f32_16x16x32_bf16 v[76:79], v[164:167], v[198:201], v[76:79]
	v_mfma_f32_16x16x32_bf16 v[72:75], v[172:175], v[198:201], v[72:75]
	v_mfma_f32_16x16x32_bf16 v[68:71], v[164:167], v[206:209], v[68:71]
	v_mfma_f32_16x16x32_bf16 v[64:67], v[172:175], v[206:209], v[64:67]
	s_barrier
	s_add_i32 s28, s69, s56
	v_lshl_add_u64 v[210:211], s[34:35], 0, v[132:133]
	s_mov_b32 m0, s28
	ds_read_b128 v[176:179], v143 offset:16384
	ds_read_b128 v[180:183], v143 offset:17408
	ds_read_b128 v[184:187], v143 offset:18432
	ds_read_b128 v[188:191], v143 offset:19456
	ds_read_b128 v[194:197], v143 offset:20480
	ds_read_b128 v[198:201], v143 offset:21504
	ds_read_b128 v[202:205], v143 offset:22528
	ds_read_b128 v[206:209], v143 offset:23552
	global_load_lds_dwordx4 v[210:211], off
	s_add_i32 m0, s28, 0x2000
	s_add_u32 s28, s34, 0xb0000
	v_lshl_add_u64 v[212:213], s[34:35], 0, v[128:129]
	s_addc_u32 s29, s35, 0
	s_add_i32 s69, s70, s56
	global_load_lds_dwordx4 v[212:213], off
	v_lshl_add_u64 v[214:215], s[28:29], 0, v[132:133]
	s_mov_b32 m0, s69
	v_lshl_add_u64 v[216:217], s[36:37], 0, v[130:131]
	global_load_lds_dwordx4 v[214:215], off
	v_lshl_add_u64 v[214:215], s[28:29], 0, v[128:129]
	s_add_i32 m0, s69, 0x2000
	s_nop 0
	global_load_lds_dwordx4 v[214:215], off
	v_lshl_add_u64 v[214:215], s[36:37], 0, v[134:135]
	s_mov_b32 m0, s57
	s_nop 0
	global_load_lds_dwordx4 v[214:215], off
	s_mov_b32 m0, s58
	s_nop 0
	global_load_lds_dwordx4 v[216:217], off
	s_waitcnt vmcnt(8)
	s_waitcnt lgkmcnt(0)
	s_barrier
; #define PG8_STAGE(bufoff, gbase, voff) do { _Pragma("unroll") for (int _i = 0; _i < 2; ++_i) \
;         __builtin_amdgcn_global_load_lds((const unsigned*)((const char*)(gbase) + (voff)[_i]), (LAS unsigned*)(lds + (bufoff) + ldsw + _i * 8192), 16, 0, 0); } while (0)
; #define PG8_LDA(dst, b, h) do { _Pragma("unroll") for (int m = 0; m < 4; ++m) _Pragma("unroll") for (int k = 0; k < 2; ++k) dst[m][k] = *(const LAS bf16x8*)(lds + PG8_SA(b, h) + aoff + m * 2048 + k * 1024); } while (0)
; #define PG8_LDB(dst, b, h) do { _Pragma("unroll") for (int n = 0; n < 2; ++n) _Pragma("unroll") for (int k = 0; k < 2; ++k) dst[n][k] = *(const LAS bf16x8*)(lds + PG8_SB(b, h) + boff + n * 2048 + k * 1024); } while (0)
; #define PG8_MMA(ai, bj, At, Bt) do { __builtin_amdgcn_s_setprio(1); _Pragma("unroll") for (int m = 0; m < 4; ++m) _Pragma("unroll") for (int n = 0; n < 2; ++n) _Pragma("unroll") for (int k = 0; k < 2; ++k) \
;         acc[ai][bj][m][n] = __builtin_amdgcn_mfma_f32_16x16x32_bf16(Bt[n][k], At[m][k], acc[ai][bj][m][n], 0, 0, 0); __builtin_amdgcn_s_setprio(0); } while (0)
; #define PG8_WAIT_V(n) asm volatile("s_waitcnt vmcnt(" #n ")" ::: "memory")
; #define PG8_WAIT_L(n) asm volatile("s_waitcnt lgkmcnt(" #n ")" ::: "memory")
; #define PG8_BAR __builtin_amdgcn_s_barrier()
; #define PG8_SCHED __builtin_amdgcn_sched_barrier(0)
; template <class Epi>
; DI void gemm_phase(int wv, LAS unsigned char* lds, LAS unsigned char* scr, const Sched& S, const Epi& E) {
;     ...
;             PG8_WAIT_V(8); PG8_WAIT_L(0); PG8_BAR; PG8_MMA(1, 0, At, B0); PG8_MMA(1, 1, At, B1); PG8_BAR; PG8_SCHED;
;             PG8_LDB(B0, 1, 0); PG8_LDB(B1, 1, 1); PG8_SCHED; PG8_LDA(At, 1, 0); PG8_STAGE(PG8_SA(0, 1), a2 + hstepA, voffA);
;             PG8_WAIT_V(8); PG8_WAIT_L(0); PG8_BAR; PG8_MMA(0, 0, At, B0); PG8_MMA(0, 1, At, B1); PG8_BAR; PG8_SCHED;
	v_mfma_f32_16x16x32_bf16 v[60:63], v[144:147], v[176:179], v[60:63]
	v_mfma_f32_16x16x32_bf16 v[56:59], v[152:155], v[176:179], v[56:59]
	v_mfma_f32_16x16x32_bf16 v[52:55], v[144:147], v[184:187], v[52:55]
	v_mfma_f32_16x16x32_bf16 v[48:51], v[152:155], v[184:187], v[48:51]
	v_mfma_f32_16x16x32_bf16 v[36:39], v[144:147], v[194:197], v[36:39]
	v_mfma_f32_16x16x32_bf16 v[32:35], v[152:155], v[194:197], v[32:35]
	v_mfma_f32_16x16x32_bf16 v[20:23], v[144:147], v[202:205], v[20:23]
	v_mfma_f32_16x16x32_bf16 v[16:19], v[152:155], v[202:205], v[16:19]
	v_mfma_f32_16x16x32_bf16 v[60:63], v[148:151], v[180:183], v[60:63]
	v_mfma_f32_16x16x32_bf16 v[56:59], v[156:159], v[180:183], v[56:59]
	v_mfma_f32_16x16x32_bf16 v[52:55], v[148:151], v[188:191], v[52:55]
	v_mfma_f32_16x16x32_bf16 v[48:51], v[156:159], v[188:191], v[48:51]
	v_mfma_f32_16x16x32_bf16 v[36:39], v[148:151], v[198:201], v[36:39]
	v_mfma_f32_16x16x32_bf16 v[32:35], v[156:159], v[198:201], v[32:35]
	v_mfma_f32_16x16x32_bf16 v[20:23], v[148:151], v[206:209], v[20:23]
	v_mfma_f32_16x16x32_bf16 v[16:19], v[156:159], v[206:209], v[16:19]
	v_mfma_f32_16x16x32_bf16 v[44:47], v[160:163], v[176:179], v[44:47]
	v_mfma_f32_16x16x32_bf16 v[40:43], v[168:171], v[176:179], v[40:43]
	v_mfma_f32_16x16x32_bf16 v[28:31], v[160:163], v[184:187], v[28:31]
	v_mfma_f32_16x16x32_bf16 v[24:27], v[168:171], v[184:187], v[24:27]
	v_mfma_f32_16x16x32_bf16 v[12:15], v[160:163], v[194:197], v[12:15]
	v_mfma_f32_16x16x32_bf16 v[8:11], v[168:171], v[194:197], v[8:11]
	v_mfma_f32_16x16x32_bf16 v[4:7], v[160:163], v[202:205], v[4:7]
	v_mfma_f32_16x16x32_bf16 v[0:3], v[168:171], v[202:205], v[0:3]
	v_mfma_f32_16x16x32_bf16 v[44:47], v[164:167], v[180:183], v[44:47]
	v_mfma_f32_16x16x32_bf16 v[40:43], v[172:175], v[180:183], v[40:43]
	v_mfma_f32_16x16x32_bf16 v[28:31], v[164:167], v[188:191], v[28:31]
	v_mfma_f32_16x16x32_bf16 v[24:27], v[172:175], v[188:191], v[24:27]
	v_mfma_f32_16x16x32_bf16 v[12:15], v[164:167], v[198:201], v[12:15]
	v_mfma_f32_16x16x32_bf16 v[8:11], v[172:175], v[198:201], v[8:11]
	v_mfma_f32_16x16x32_bf16 v[4:7], v[164:167], v[206:209], v[4:7]
	v_mfma_f32_16x16x32_bf16 v[0:3], v[172:175], v[206:209], v[0:3]
	s_barrier
	s_add_i32 s69, 0, 0x18000
	s_add_i32 s70, 0, 0x1c000
	v_add_u32_e32 v156, s69, v142
	v_add_u32_e32 v172, s70, v142
	ds_read_b128 v[144:147], v156
	ds_read_b128 v[148:151], v156 offset:1024
	ds_read_b128 v[152:155], v156 offset:2048
	ds_read_b128 v[156:159], v156 offset:3072
	ds_read_b128 v[160:163], v172
	ds_read_b128 v[164:167], v172 offset:1024
	ds_read_b128 v[168:171], v172 offset:2048
	ds_read_b128 v[172:175], v172 offset:3072
	s_add_u32 s28, s36, 0xb0000
	s_addc_u32 s29, s37, 0
	s_mov_b32 m0, s59
	v_lshl_add_u64 v[218:219], s[28:29], 0, v[134:135]
	ds_read_b128 v[176:179], v143 offset:32768
	ds_read_b128 v[180:183], v143 offset:33792
	ds_read_b128 v[184:187], v143 offset:34816
	ds_read_b128 v[188:191], v143 offset:35840
	ds_read_b128 v[194:197], v143 offset:36864
	ds_read_b128 v[198:201], v143 offset:37888
	ds_read_b128 v[202:205], v143 offset:38912
	ds_read_b128 v[206:209], v143 offset:39936
	global_load_lds_dwordx4 v[218:219], off
	v_lshl_add_u64 v[218:219], s[28:29], 0, v[130:131]
	s_mov_b32 m0, s60
	s_nop 0
	global_load_lds_dwordx4 v[218:219], off
	s_waitcnt vmcnt(8)
	s_waitcnt lgkmcnt(0)
	s_barrier
	v_mfma_f32_16x16x32_bf16 v[124:127], v[144:147], v[176:179], v[124:127]
	v_mfma_f32_16x16x32_bf16 v[120:123], v[152:155], v[176:179], v[120:123]
	v_mfma_f32_16x16x32_bf16 v[116:119], v[144:147], v[184:187], v[116:119]
	v_mfma_f32_16x16x32_bf16 v[112:115], v[152:155], v[184:187], v[112:115]
	v_mfma_f32_16x16x32_bf16 v[100:103], v[144:147], v[194:197], v[100:103]
	v_mfma_f32_16x16x32_bf16 v[96:99], v[152:155], v[194:197], v[96:99]
	v_mfma_f32_16x16x32_bf16 v[84:87], v[144:147], v[202:205], v[84:87]
	v_mfma_f32_16x16x32_bf16 v[80:83], v[152:155], v[202:205], v[80:83]
	v_mfma_f32_16x16x32_bf16 v[124:127], v[148:151], v[180:183], v[124:127]
	v_mfma_f32_16x16x32_bf16 v[120:123], v[156:159], v[180:183], v[120:123]
	v_mfma_f32_16x16x32_bf16 v[116:119], v[148:151], v[188:191], v[116:119]
	v_mfma_f32_16x16x32_bf16 v[112:115], v[156:159], v[188:191], v[112:115]
	v_mfma_f32_16x16x32_bf16 v[100:103], v[148:151], v[198:201], v[100:103]
	v_mfma_f32_16x16x32_bf16 v[96:99], v[156:159], v[198:201], v[96:99]
	v_mfma_f32_16x16x32_bf16 v[84:87], v[148:151], v[206:209], v[84:87]
	v_mfma_f32_16x16x32_bf16 v[80:83], v[156:159], v[206:209], v[80:83]
	v_mfma_f32_16x16x32_bf16 v[108:111], v[160:163], v[176:179], v[108:111]
	v_mfma_f32_16x16x32_bf16 v[104:107], v[168:171], v[176:179], v[104:107]
	v_mfma_f32_16x16x32_bf16 v[92:95], v[160:163], v[184:187], v[92:95]
	v_mfma_f32_16x16x32_bf16 v[88:91], v[168:171], v[184:187], v[88:91]
	v_mfma_f32_16x16x32_bf16 v[76:79], v[160:163], v[194:197], v[76:79]
	v_mfma_f32_16x16x32_bf16 v[72:75], v[168:171], v[194:197], v[72:75]
	v_mfma_f32_16x16x32_bf16 v[68:71], v[160:163], v[202:205], v[68:71]
	v_mfma_f32_16x16x32_bf16 v[64:67], v[168:171], v[202:205], v[64:67]
	v_mfma_f32_16x16x32_bf16 v[108:111], v[164:167], v[180:183], v[108:111]
	v_mfma_f32_16x16x32_bf16 v[104:107], v[172:175], v[180:183], v[104:107]
	v_mfma_f32_16x16x32_bf16 v[92:95], v[164:167], v[188:191], v[92:95]
	v_mfma_f32_16x16x32_bf16 v[88:91], v[172:175], v[188:191], v[88:91]
	v_mfma_f32_16x16x32_bf16 v[76:79], v[164:167], v[198:201], v[76:79]
	v_mfma_f32_16x16x32_bf16 v[72:75], v[172:175], v[198:201], v[72:75]
	v_mfma_f32_16x16x32_bf16 v[68:71], v[164:167], v[206:209], v[68:71]
	v_mfma_f32_16x16x32_bf16 v[64:67], v[172:175], v[206:209], v[64:67]
	s_barrier
; #define PG8_STAGE(bufoff, gbase, voff) do { _Pragma("unroll") for (int _i = 0; _i < 2; ++_i) \
;         __builtin_amdgcn_global_load_lds((const unsigned*)((const char*)(gbase) + (voff)[_i]), (LAS unsigned*)(lds + (bufoff) + ldsw + _i * 8192), 16, 0, 0); } while (0)
; #define PG8_LDA(dst, b, h) do { _Pragma("unroll") for (int m = 0; m < 4; ++m) _Pragma("unroll") for (int k = 0; k < 2; ++k) dst[m][k] = *(const LAS bf16x8*)(lds + PG8_SA(b, h) + aoff + m * 2048 + k * 1024); } while (0)
; #define PG8_MMA(ai, bj, At, Bt) do { __builtin_amdgcn_s_setprio(1); _Pragma("unroll") for (int m = 0; m < 4; ++m) _Pragma("unroll") for (int n = 0; n < 2; ++n) _Pragma("unroll") for (int k = 0; k < 2; ++k) \
;         acc[ai][bj][m][n] = __builtin_amdgcn_mfma_f32_16x16x32_bf16(Bt[n][k], At[m][k], acc[ai][bj][m][n], 0, 0, 0); __builtin_amdgcn_s_setprio(0); } while (0)
; #define PG8_WAIT_V(n) asm volatile("s_waitcnt vmcnt(" #n ")" ::: "memory")
; #define PG8_WAIT_L(n) asm volatile("s_waitcnt lgkmcnt(" #n ")" ::: "memory")
; #define PG8_BAR __builtin_amdgcn_s_barrier()
; #define PG8_SCHED __builtin_amdgcn_sched_barrier(0)
; template <class Epi>
; DI void gemm_phase(int wv, LAS unsigned char* lds, LAS unsigned char* scr, const Sched& S, const Epi& E) {
;     ...
;             PG8_LDA(At, 1, 1); PG8_STAGE(PG8_SB(1, 0), b3, voffB); PG8_STAGE(PG8_SB(1, 1), b3 + hstepB, voffB); PG8_STAGE(PG8_SA(1, 0), a3, voffA);
;             PG8_WAIT_V(8); PG8_WAIT_L(0); PG8_BAR; PG8_MMA(1, 0, At, B0); PG8_MMA(1, 1, At, B1); PG8_BAR; PG8_SCHED;
;         }
;         if (wr == 0) PG8_BAR;
	s_add_i32 s28, s69, s56
	v_lshl_add_u64 v[210:211], v[210:211], 0, s[2:3]
	s_mov_b32 m0, s28
	ds_read_b128 v[176:179], v143 offset:49152
	ds_read_b128 v[180:183], v143 offset:50176
	ds_read_b128 v[184:187], v143 offset:51200
	ds_read_b128 v[188:191], v143 offset:52224
	ds_read_b128 v[194:197], v143 offset:53248
	ds_read_b128 v[198:201], v143 offset:54272
	ds_read_b128 v[202:205], v143 offset:55296
	ds_read_b128 v[206:209], v143 offset:56320
	global_load_lds_dwordx4 v[210:211], off
	s_add_i32 m0, s28, 0x2000
	s_add_u32 s28, s34, 0xb0080
	v_lshl_add_u64 v[210:211], v[212:213], 0, s[2:3]
	s_addc_u32 s29, s35, 0
	s_add_i32 s34, s70, s56
	global_load_lds_dwordx4 v[210:211], off
	v_lshl_add_u64 v[210:211], s[28:29], 0, v[132:133]
	s_mov_b32 m0, s34
	s_nop 0
	global_load_lds_dwordx4 v[210:211], off
	v_lshl_add_u64 v[210:211], s[28:29], 0, v[128:129]
	s_add_i32 m0, s34, 0x2000
	s_nop 0
	global_load_lds_dwordx4 v[210:211], off
	v_lshl_add_u64 v[210:211], v[214:215], 0, s[2:3]
	s_mov_b32 m0, s63
	s_nop 0
	global_load_lds_dwordx4 v[210:211], off
	v_lshl_add_u64 v[210:211], v[216:217], 0, s[2:3]
	s_mov_b32 m0, s64
	s_nop 0
	global_load_lds_dwordx4 v[210:211], off
	s_waitcnt vmcnt(8)
	s_waitcnt lgkmcnt(0)
	s_barrier
	v_mfma_f32_16x16x32_bf16 v[60:63], v[144:147], v[176:179], v[60:63]
	v_mfma_f32_16x16x32_bf16 v[56:59], v[152:155], v[176:179], v[56:59]
	v_mfma_f32_16x16x32_bf16 v[52:55], v[144:147], v[184:187], v[52:55]
	v_mfma_f32_16x16x32_bf16 v[48:51], v[152:155], v[184:187], v[48:51]
	v_mfma_f32_16x16x32_bf16 v[36:39], v[144:147], v[194:197], v[36:39]
	v_mfma_f32_16x16x32_bf16 v[32:35], v[152:155], v[194:197], v[32:35]
	v_mfma_f32_16x16x32_bf16 v[20:23], v[144:147], v[202:205], v[20:23]
	v_mfma_f32_16x16x32_bf16 v[16:19], v[152:155], v[202:205], v[16:19]
	v_mfma_f32_16x16x32_bf16 v[60:63], v[148:151], v[180:183], v[60:63]
	v_mfma_f32_16x16x32_bf16 v[56:59], v[156:159], v[180:183], v[56:59]
	v_mfma_f32_16x16x32_bf16 v[52:55], v[148:151], v[188:191], v[52:55]
	v_mfma_f32_16x16x32_bf16 v[48:51], v[156:159], v[188:191], v[48:51]
	v_mfma_f32_16x16x32_bf16 v[36:39], v[148:151], v[198:201], v[36:39]
	v_mfma_f32_16x16x32_bf16 v[32:35], v[156:159], v[198:201], v[32:35]
	v_mfma_f32_16x16x32_bf16 v[20:23], v[148:151], v[206:209], v[20:23]
	v_mfma_f32_16x16x32_bf16 v[16:19], v[156:159], v[206:209], v[16:19]
	v_mfma_f32_16x16x32_bf16 v[44:47], v[160:163], v[176:179], v[44:47]
	v_mfma_f32_16x16x32_bf16 v[40:43], v[168:171], v[176:179], v[40:43]
	v_mfma_f32_16x16x32_bf16 v[28:31], v[160:163], v[184:187], v[28:31]
	v_mfma_f32_16x16x32_bf16 v[24:27], v[168:171], v[184:187], v[24:27]
	v_mfma_f32_16x16x32_bf16 v[12:15], v[160:163], v[194:197], v[12:15]
	v_mfma_f32_16x16x32_bf16 v[8:11], v[168:171], v[194:197], v[8:11]
	v_mfma_f32_16x16x32_bf16 v[4:7], v[160:163], v[202:205], v[4:7]
	v_mfma_f32_16x16x32_bf16 v[0:3], v[168:171], v[202:205], v[0:3]
	v_mfma_f32_16x16x32_bf16 v[44:47], v[164:167], v[180:183], v[44:47]
	v_mfma_f32_16x16x32_bf16 v[40:43], v[172:175], v[180:183], v[40:43]
	v_mfma_f32_16x16x32_bf16 v[28:31], v[164:167], v[188:191], v[28:31]
	v_mfma_f32_16x16x32_bf16 v[24:27], v[172:175], v[188:191], v[24:27]
	v_mfma_f32_16x16x32_bf16 v[12:15], v[164:167], v[198:201], v[12:15]
	v_mfma_f32_16x16x32_bf16 v[8:11], v[172:175], v[198:201], v[8:11]
	v_mfma_f32_16x16x32_bf16 v[4:7], v[164:167], v[206:209], v[4:7]
	v_mfma_f32_16x16x32_bf16 v[0:3], v[172:175], v[206:209], v[0:3]
	s_barrier
	s_add_i32 s68, s68, 2
	s_add_u32 s25, s25, 0x100
	s_addc_u32 s27, s27, 0
	s_cmp_gt_u32 s68, 41
	s_mov_b64 s[28:29], s[30:31]
	s_cbranch_scc0 .LBB0_936
	s_and_b64 vcc, exec, s[20:21]
	s_cbranch_vccz .LBB0_939
	s_barrier
